# pair-GEMM loops: s_setprio 1 held across each 32-MFMA block (prio 0 for LDS-DMA issue, waits and barriers)
# speedup vs baseline: 1.1721x; 1.0023x over previous
.Lfin3_loop:
	v_add_u32_e32 v234, s22, v232
	v_add_u32_e32 v236, s28, v232
	v_add_u32_e32 v235, s22, v233
	v_add_u32_e32 v237, s28, v233
	ds_read_b128 v[136:139], v234
	ds_read_b128 v[140:143], v234 offset:2048
	ds_read_b128 v[144:147], v234 offset:4096
	ds_read_b128 v[148:151], v234 offset:6144
	ds_read_b128 v[188:191], v236
	ds_read_b128 v[196:199], v236 offset:2048
	ds_read_b128 v[200:203], v236 offset:4096
	ds_read_b128 v[204:207], v236 offset:6144
	ds_read_b128 v[172:175], v235
	ds_read_b128 v[176:179], v235 offset:2048
	ds_read_b128 v[180:183], v235 offset:4096
	ds_read_b128 v[184:187], v235 offset:6144
	ds_read_b128 v[212:215], v237
	ds_read_b128 v[216:219], v237 offset:2048
	ds_read_b128 v[220:223], v237 offset:4096
	ds_read_b128 v[224:227], v237 offset:6144
	s_add_i32 m0, s51, 0xc000
	s_nop 0
	global_load_lds_dwordx4 v228, s[44:45]
	s_add_i32 m0, s51, 0xc400
	s_nop 0
	global_load_lds_dwordx4 v230, s[44:45]
	s_add_i32 m0, s51, 0xe000
	s_nop 0
	global_load_lds_dwordx4 v229, s[44:45]
	s_add_i32 m0, s51, 0xe400
	s_nop 0
	global_load_lds_dwordx4 v231, s[44:45]
	s_add_i32 m0, s51, 0x10000
	s_nop 0
	global_load_lds_dwordx4 v228, s[46:47]
	s_add_i32 m0, s51, 0x10400
	s_nop 0
	global_load_lds_dwordx4 v230, s[46:47]
	s_waitcnt lgkmcnt(8)
	s_setprio 1
	v_mfma_f32_16x16x32_bf16 v[2:5], v[136:139], v[188:191], v[2:5]
	v_mfma_f32_16x16x32_bf16 v[6:9], v[136:139], v[196:199], v[6:9]
	v_mfma_f32_16x16x32_bf16 v[10:13], v[136:139], v[200:203], v[10:13]
	v_mfma_f32_16x16x32_bf16 v[14:17], v[136:139], v[204:207], v[14:17]
	v_mfma_f32_16x16x32_bf16 v[18:21], v[140:143], v[188:191], v[18:21]
	v_mfma_f32_16x16x32_bf16 v[22:25], v[140:143], v[196:199], v[22:25]
	v_mfma_f32_16x16x32_bf16 v[26:29], v[140:143], v[200:203], v[26:29]
	v_mfma_f32_16x16x32_bf16 v[30:33], v[140:143], v[204:207], v[30:33]
	v_mfma_f32_16x16x32_bf16 v[34:37], v[144:147], v[188:191], v[34:37]
	v_mfma_f32_16x16x32_bf16 v[38:41], v[144:147], v[196:199], v[38:41]
	v_mfma_f32_16x16x32_bf16 v[42:45], v[144:147], v[200:203], v[42:45]
	v_mfma_f32_16x16x32_bf16 v[46:49], v[144:147], v[204:207], v[46:49]
	v_mfma_f32_16x16x32_bf16 v[50:53], v[148:151], v[188:191], v[50:53]
	v_mfma_f32_16x16x32_bf16 v[54:57], v[148:151], v[196:199], v[54:57]
	v_mfma_f32_16x16x32_bf16 v[58:61], v[148:151], v[200:203], v[58:61]
	v_mfma_f32_16x16x32_bf16 v[62:65], v[148:151], v[204:207], v[62:65]
	s_waitcnt lgkmcnt(0)
	v_mfma_f32_16x16x32_bf16 v[2:5], v[172:175], v[212:215], v[2:5]
	v_mfma_f32_16x16x32_bf16 v[6:9], v[172:175], v[216:219], v[6:9]
	v_mfma_f32_16x16x32_bf16 v[10:13], v[172:175], v[220:223], v[10:13]
	v_mfma_f32_16x16x32_bf16 v[14:17], v[172:175], v[224:227], v[14:17]
	v_mfma_f32_16x16x32_bf16 v[18:21], v[176:179], v[212:215], v[18:21]
	v_mfma_f32_16x16x32_bf16 v[22:25], v[176:179], v[216:219], v[22:25]
	v_mfma_f32_16x16x32_bf16 v[26:29], v[176:179], v[220:223], v[26:29]
	v_mfma_f32_16x16x32_bf16 v[30:33], v[176:179], v[224:227], v[30:33]
	v_mfma_f32_16x16x32_bf16 v[34:37], v[180:183], v[212:215], v[34:37]
	v_mfma_f32_16x16x32_bf16 v[38:41], v[180:183], v[216:219], v[38:41]
	v_mfma_f32_16x16x32_bf16 v[42:45], v[180:183], v[220:223], v[42:45]
	v_mfma_f32_16x16x32_bf16 v[46:49], v[180:183], v[224:227], v[46:49]
	v_mfma_f32_16x16x32_bf16 v[50:53], v[184:187], v[212:215], v[50:53]
	v_mfma_f32_16x16x32_bf16 v[54:57], v[184:187], v[216:219], v[54:57]
	v_mfma_f32_16x16x32_bf16 v[58:61], v[184:187], v[220:223], v[58:61]
	v_mfma_f32_16x16x32_bf16 v[62:65], v[184:187], v[224:227], v[62:65]
	s_setprio 0
	s_waitcnt vmcnt(6)
	s_barrier
	v_add_u32_e32 v236, s40, v232
	v_add_u32_e32 v237, s40, v233
	ds_read_b128 v[188:191], v236
	ds_read_b128 v[196:199], v236 offset:2048
	ds_read_b128 v[200:203], v236 offset:4096
	ds_read_b128 v[204:207], v236 offset:6144
	ds_read_b128 v[212:215], v237
	ds_read_b128 v[216:219], v237 offset:2048
	ds_read_b128 v[220:223], v237 offset:4096
	ds_read_b128 v[224:227], v237 offset:6144
	s_mov_b32 m0, s51
	s_nop 0
	global_load_lds_dwordx4 v229, s[46:47]
	s_add_i32 m0, s51, 0x400
	s_nop 0
	global_load_lds_dwordx4 v231, s[46:47]
	s_add_i32 m0, s51, 0x2000
	s_nop 0
	global_load_lds_dwordx4 v228, s[48:49]
	s_add_i32 m0, s51, 0x2400
	s_nop 0
	global_load_lds_dwordx4 v230, s[48:49]
	s_add_i32 m0, s51, 0x4000
	s_nop 0
	global_load_lds_dwordx4 v229, s[48:49]
	s_add_i32 m0, s51, 0x4400
	s_nop 0
	global_load_lds_dwordx4 v231, s[48:49]
	s_waitcnt lgkmcnt(4)
	s_setprio 1
	v_mfma_f32_16x16x32_bf16 v[66:69], v[136:139], v[188:191], v[66:69]
	v_mfma_f32_16x16x32_bf16 v[70:73], v[136:139], v[196:199], v[70:73]
	v_mfma_f32_16x16x32_bf16 v[74:77], v[136:139], v[200:203], v[74:77]
	v_mfma_f32_16x16x32_bf16 v[78:81], v[136:139], v[204:207], v[78:81]
	v_mfma_f32_16x16x32_bf16 v[82:85], v[140:143], v[188:191], v[82:85]
	v_mfma_f32_16x16x32_bf16 v[86:89], v[140:143], v[196:199], v[86:89]
	v_mfma_f32_16x16x32_bf16 v[90:93], v[140:143], v[200:203], v[90:93]
	v_mfma_f32_16x16x32_bf16 v[94:97], v[140:143], v[204:207], v[94:97]
	v_mfma_f32_16x16x32_bf16 v[98:101], v[144:147], v[188:191], v[98:101]
	v_mfma_f32_16x16x32_bf16 v[102:105], v[144:147], v[196:199], v[102:105]
	v_mfma_f32_16x16x32_bf16 v[106:109], v[144:147], v[200:203], v[106:109]
	v_mfma_f32_16x16x32_bf16 v[110:113], v[144:147], v[204:207], v[110:113]
	v_mfma_f32_16x16x32_bf16 v[114:117], v[148:151], v[188:191], v[114:117]
	v_mfma_f32_16x16x32_bf16 v[118:121], v[148:151], v[196:199], v[118:121]
	v_mfma_f32_16x16x32_bf16 v[122:125], v[148:151], v[200:203], v[122:125]
	v_mfma_f32_16x16x32_bf16 v[126:129], v[148:151], v[204:207], v[126:129]
	s_waitcnt lgkmcnt(0)
	v_mfma_f32_16x16x32_bf16 v[66:69], v[172:175], v[212:215], v[66:69]
	v_mfma_f32_16x16x32_bf16 v[70:73], v[172:175], v[216:219], v[70:73]
	v_mfma_f32_16x16x32_bf16 v[74:77], v[172:175], v[220:223], v[74:77]
	v_mfma_f32_16x16x32_bf16 v[78:81], v[172:175], v[224:227], v[78:81]
	v_mfma_f32_16x16x32_bf16 v[82:85], v[176:179], v[212:215], v[82:85]
	v_mfma_f32_16x16x32_bf16 v[86:89], v[176:179], v[216:219], v[86:89]
	v_mfma_f32_16x16x32_bf16 v[90:93], v[176:179], v[220:223], v[90:93]
	v_mfma_f32_16x16x32_bf16 v[94:97], v[176:179], v[224:227], v[94:97]
	v_mfma_f32_16x16x32_bf16 v[98:101], v[180:183], v[212:215], v[98:101]
	v_mfma_f32_16x16x32_bf16 v[102:105], v[180:183], v[216:219], v[102:105]
	v_mfma_f32_16x16x32_bf16 v[106:109], v[180:183], v[220:223], v[106:109]
	v_mfma_f32_16x16x32_bf16 v[110:113], v[180:183], v[224:227], v[110:113]
	v_mfma_f32_16x16x32_bf16 v[114:117], v[184:187], v[212:215], v[114:117]
	v_mfma_f32_16x16x32_bf16 v[118:121], v[184:187], v[216:219], v[118:121]
	v_mfma_f32_16x16x32_bf16 v[122:125], v[184:187], v[220:223], v[122:125]
	v_mfma_f32_16x16x32_bf16 v[126:129], v[184:187], v[224:227], v[126:129]
	s_setprio 0
	v_add_u32_e32 v228, 0x80, v228
	v_add_u32_e32 v229, 0x80, v229
	v_add_u32_e32 v230, 0x80, v230
	v_add_u32_e32 v231, 0x80, v231
	s_waitcnt vmcnt(4)
	s_barrier
	v_add_u32_e32 v234, s23, v232
	v_add_u32_e32 v236, s29, v232
	v_add_u32_e32 v235, s23, v233
	v_add_u32_e32 v237, s29, v233
	ds_read_b128 v[136:139], v234
	ds_read_b128 v[140:143], v234 offset:2048
	ds_read_b128 v[144:147], v234 offset:4096
	ds_read_b128 v[148:151], v234 offset:6144
	ds_read_b128 v[188:191], v236
	ds_read_b128 v[196:199], v236 offset:2048
	ds_read_b128 v[200:203], v236 offset:4096
	ds_read_b128 v[204:207], v236 offset:6144
	ds_read_b128 v[172:175], v235
	ds_read_b128 v[176:179], v235 offset:2048
	ds_read_b128 v[180:183], v235 offset:4096
	ds_read_b128 v[184:187], v235 offset:6144
	ds_read_b128 v[212:215], v237
	ds_read_b128 v[216:219], v237 offset:2048
	ds_read_b128 v[220:223], v237 offset:4096
	ds_read_b128 v[224:227], v237 offset:6144
	s_add_i32 m0, s51, 0x6000
	s_nop 0
	global_load_lds_dwordx4 v228, s[44:45]
	s_add_i32 m0, s51, 0x6400
	s_nop 0
	global_load_lds_dwordx4 v230, s[44:45]
	s_add_i32 m0, s51, 0x8000
	s_nop 0
	global_load_lds_dwordx4 v229, s[44:45]
	s_add_i32 m0, s51, 0x8400
	s_nop 0
	global_load_lds_dwordx4 v231, s[44:45]
	s_add_i32 m0, s51, 0xa000
	s_nop 0
	global_load_lds_dwordx4 v228, s[46:47]
	s_add_i32 m0, s51, 0xa400
	s_nop 0
	global_load_lds_dwordx4 v230, s[46:47]
	s_waitcnt lgkmcnt(8)
	s_setprio 1
	v_mfma_f32_16x16x32_bf16 v[2:5], v[136:139], v[188:191], v[2:5]
	v_mfma_f32_16x16x32_bf16 v[6:9], v[136:139], v[196:199], v[6:9]
	v_mfma_f32_16x16x32_bf16 v[10:13], v[136:139], v[200:203], v[10:13]
	v_mfma_f32_16x16x32_bf16 v[14:17], v[136:139], v[204:207], v[14:17]
	v_mfma_f32_16x16x32_bf16 v[18:21], v[140:143], v[188:191], v[18:21]
	v_mfma_f32_16x16x32_bf16 v[22:25], v[140:143], v[196:199], v[22:25]
	v_mfma_f32_16x16x32_bf16 v[26:29], v[140:143], v[200:203], v[26:29]
	v_mfma_f32_16x16x32_bf16 v[30:33], v[140:143], v[204:207], v[30:33]
	v_mfma_f32_16x16x32_bf16 v[34:37], v[144:147], v[188:191], v[34:37]
	v_mfma_f32_16x16x32_bf16 v[38:41], v[144:147], v[196:199], v[38:41]
	v_mfma_f32_16x16x32_bf16 v[42:45], v[144:147], v[200:203], v[42:45]
	v_mfma_f32_16x16x32_bf16 v[46:49], v[144:147], v[204:207], v[46:49]
	v_mfma_f32_16x16x32_bf16 v[50:53], v[148:151], v[188:191], v[50:53]
	v_mfma_f32_16x16x32_bf16 v[54:57], v[148:151], v[196:199], v[54:57]
	v_mfma_f32_16x16x32_bf16 v[58:61], v[148:151], v[200:203], v[58:61]
	v_mfma_f32_16x16x32_bf16 v[62:65], v[148:151], v[204:207], v[62:65]
	s_waitcnt lgkmcnt(0)
	v_mfma_f32_16x16x32_bf16 v[2:5], v[172:175], v[212:215], v[2:5]
	v_mfma_f32_16x16x32_bf16 v[6:9], v[172:175], v[216:219], v[6:9]
	v_mfma_f32_16x16x32_bf16 v[10:13], v[172:175], v[220:223], v[10:13]
	v_mfma_f32_16x16x32_bf16 v[14:17], v[172:175], v[224:227], v[14:17]
	v_mfma_f32_16x16x32_bf16 v[18:21], v[176:179], v[212:215], v[18:21]
	v_mfma_f32_16x16x32_bf16 v[22:25], v[176:179], v[216:219], v[22:25]
	v_mfma_f32_16x16x32_bf16 v[26:29], v[176:179], v[220:223], v[26:29]
	v_mfma_f32_16x16x32_bf16 v[30:33], v[176:179], v[224:227], v[30:33]
	v_mfma_f32_16x16x32_bf16 v[34:37], v[180:183], v[212:215], v[34:37]
	v_mfma_f32_16x16x32_bf16 v[38:41], v[180:183], v[216:219], v[38:41]
	v_mfma_f32_16x16x32_bf16 v[42:45], v[180:183], v[220:223], v[42:45]
	v_mfma_f32_16x16x32_bf16 v[46:49], v[180:183], v[224:227], v[46:49]
	v_mfma_f32_16x16x32_bf16 v[50:53], v[184:187], v[212:215], v[50:53]
	v_mfma_f32_16x16x32_bf16 v[54:57], v[184:187], v[216:219], v[54:57]
	v_mfma_f32_16x16x32_bf16 v[58:61], v[184:187], v[220:223], v[58:61]
	v_mfma_f32_16x16x32_bf16 v[62:65], v[184:187], v[224:227], v[62:65]
	s_setprio 0
	s_waitcnt vmcnt(6)
	s_barrier
	v_add_u32_e32 v236, s41, v232
	v_add_u32_e32 v237, s41, v233
	ds_read_b128 v[188:191], v236
	ds_read_b128 v[196:199], v236 offset:2048
	ds_read_b128 v[200:203], v236 offset:4096
	ds_read_b128 v[204:207], v236 offset:6144
	ds_read_b128 v[212:215], v237
	ds_read_b128 v[216:219], v237 offset:2048
	ds_read_b128 v[220:223], v237 offset:4096
	ds_read_b128 v[224:227], v237 offset:6144
	s_add_i32 m0, s51, 0xc000
	s_nop 0
	global_load_lds_dwordx4 v229, s[46:47]
	s_add_i32 m0, s51, 0xc400
	s_nop 0
	global_load_lds_dwordx4 v231, s[46:47]
	s_add_i32 m0, s51, 0xe000
	s_nop 0
	global_load_lds_dwordx4 v228, s[48:49]
	s_add_i32 m0, s51, 0xe400
	s_nop 0
	global_load_lds_dwordx4 v230, s[48:49]
	s_add_i32 m0, s51, 0x10000
	s_nop 0
	global_load_lds_dwordx4 v229, s[48:49]
	s_add_i32 m0, s51, 0x10400
	s_nop 0
	global_load_lds_dwordx4 v231, s[48:49]
	s_waitcnt lgkmcnt(4)
	s_setprio 1
	v_mfma_f32_16x16x32_bf16 v[66:69], v[136:139], v[188:191], v[66:69]
	v_mfma_f32_16x16x32_bf16 v[70:73], v[136:139], v[196:199], v[70:73]
	v_mfma_f32_16x16x32_bf16 v[74:77], v[136:139], v[200:203], v[74:77]
	v_mfma_f32_16x16x32_bf16 v[78:81], v[136:139], v[204:207], v[78:81]
	v_mfma_f32_16x16x32_bf16 v[82:85], v[140:143], v[188:191], v[82:85]
	v_mfma_f32_16x16x32_bf16 v[86:89], v[140:143], v[196:199], v[86:89]
	v_mfma_f32_16x16x32_bf16 v[90:93], v[140:143], v[200:203], v[90:93]
	v_mfma_f32_16x16x32_bf16 v[94:97], v[140:143], v[204:207], v[94:97]
	v_mfma_f32_16x16x32_bf16 v[98:101], v[144:147], v[188:191], v[98:101]
	v_mfma_f32_16x16x32_bf16 v[102:105], v[144:147], v[196:199], v[102:105]
	v_mfma_f32_16x16x32_bf16 v[106:109], v[144:147], v[200:203], v[106:109]
	v_mfma_f32_16x16x32_bf16 v[110:113], v[144:147], v[204:207], v[110:113]
	v_mfma_f32_16x16x32_bf16 v[114:117], v[148:151], v[188:191], v[114:117]
	v_mfma_f32_16x16x32_bf16 v[118:121], v[148:151], v[196:199], v[118:121]
	v_mfma_f32_16x16x32_bf16 v[122:125], v[148:151], v[200:203], v[122:125]
	v_mfma_f32_16x16x32_bf16 v[126:129], v[148:151], v[204:207], v[126:129]
	s_waitcnt lgkmcnt(0)
	v_mfma_f32_16x16x32_bf16 v[66:69], v[172:175], v[212:215], v[66:69]
	v_mfma_f32_16x16x32_bf16 v[70:73], v[172:175], v[216:219], v[70:73]
	v_mfma_f32_16x16x32_bf16 v[74:77], v[172:175], v[220:223], v[74:77]
	v_mfma_f32_16x16x32_bf16 v[78:81], v[172:175], v[224:227], v[78:81]
	v_mfma_f32_16x16x32_bf16 v[82:85], v[176:179], v[212:215], v[82:85]
	v_mfma_f32_16x16x32_bf16 v[86:89], v[176:179], v[216:219], v[86:89]
	v_mfma_f32_16x16x32_bf16 v[90:93], v[176:179], v[220:223], v[90:93]
	v_mfma_f32_16x16x32_bf16 v[94:97], v[176:179], v[224:227], v[94:97]
	v_mfma_f32_16x16x32_bf16 v[98:101], v[180:183], v[212:215], v[98:101]
	v_mfma_f32_16x16x32_bf16 v[102:105], v[180:183], v[216:219], v[102:105]
	v_mfma_f32_16x16x32_bf16 v[106:109], v[180:183], v[220:223], v[106:109]
	v_mfma_f32_16x16x32_bf16 v[110:113], v[180:183], v[224:227], v[110:113]
	v_mfma_f32_16x16x32_bf16 v[114:117], v[184:187], v[212:215], v[114:117]
	v_mfma_f32_16x16x32_bf16 v[118:121], v[184:187], v[216:219], v[118:121]
	v_mfma_f32_16x16x32_bf16 v[122:125], v[184:187], v[220:223], v[122:125]
	v_mfma_f32_16x16x32_bf16 v[126:129], v[184:187], v[224:227], v[126:129]
	s_setprio 0
	v_add_u32_e32 v228, 0x80, v228
	v_add_u32_e32 v229, 0x80, v229
	v_add_u32_e32 v230, 0x80, v230
	v_add_u32_e32 v231, 0x80, v231
	s_waitcnt vmcnt(4)
	s_barrier
	v_add_u32_e32 v234, s24, v232
	v_add_u32_e32 v236, s30, v232
	v_add_u32_e32 v235, s24, v233
	v_add_u32_e32 v237, s30, v233
	ds_read_b128 v[136:139], v234
	ds_read_b128 v[140:143], v234 offset:2048
	ds_read_b128 v[144:147], v234 offset:4096
	ds_read_b128 v[148:151], v234 offset:6144
	ds_read_b128 v[188:191], v236
	ds_read_b128 v[196:199], v236 offset:2048
	ds_read_b128 v[200:203], v236 offset:4096
	ds_read_b128 v[204:207], v236 offset:6144
	ds_read_b128 v[172:175], v235
	ds_read_b128 v[176:179], v235 offset:2048
	ds_read_b128 v[180:183], v235 offset:4096
	ds_read_b128 v[184:187], v235 offset:6144
	ds_read_b128 v[212:215], v237
	ds_read_b128 v[216:219], v237 offset:2048
	ds_read_b128 v[220:223], v237 offset:4096
	ds_read_b128 v[224:227], v237 offset:6144
	s_mov_b32 m0, s51
	s_nop 0
	global_load_lds_dwordx4 v228, s[44:45]
	s_add_i32 m0, s51, 0x400
	s_nop 0
	global_load_lds_dwordx4 v230, s[44:45]
	s_add_i32 m0, s51, 0x2000
	s_nop 0
	global_load_lds_dwordx4 v229, s[44:45]
	s_add_i32 m0, s51, 0x2400
	s_nop 0
	global_load_lds_dwordx4 v231, s[44:45]
	s_add_i32 m0, s51, 0x4000
	s_nop 0
	global_load_lds_dwordx4 v228, s[46:47]
	s_add_i32 m0, s51, 0x4400
	s_nop 0
	global_load_lds_dwordx4 v230, s[46:47]
	s_waitcnt lgkmcnt(8)
	s_setprio 1
	v_mfma_f32_16x16x32_bf16 v[2:5], v[136:139], v[188:191], v[2:5]
	v_mfma_f32_16x16x32_bf16 v[6:9], v[136:139], v[196:199], v[6:9]
	v_mfma_f32_16x16x32_bf16 v[10:13], v[136:139], v[200:203], v[10:13]
	v_mfma_f32_16x16x32_bf16 v[14:17], v[136:139], v[204:207], v[14:17]
	v_mfma_f32_16x16x32_bf16 v[18:21], v[140:143], v[188:191], v[18:21]
	v_mfma_f32_16x16x32_bf16 v[22:25], v[140:143], v[196:199], v[22:25]
	v_mfma_f32_16x16x32_bf16 v[26:29], v[140:143], v[200:203], v[26:29]
	v_mfma_f32_16x16x32_bf16 v[30:33], v[140:143], v[204:207], v[30:33]
	v_mfma_f32_16x16x32_bf16 v[34:37], v[144:147], v[188:191], v[34:37]
	v_mfma_f32_16x16x32_bf16 v[38:41], v[144:147], v[196:199], v[38:41]
	v_mfma_f32_16x16x32_bf16 v[42:45], v[144:147], v[200:203], v[42:45]
	v_mfma_f32_16x16x32_bf16 v[46:49], v[144:147], v[204:207], v[46:49]
	v_mfma_f32_16x16x32_bf16 v[50:53], v[148:151], v[188:191], v[50:53]
	v_mfma_f32_16x16x32_bf16 v[54:57], v[148:151], v[196:199], v[54:57]
	v_mfma_f32_16x16x32_bf16 v[58:61], v[148:151], v[200:203], v[58:61]
	v_mfma_f32_16x16x32_bf16 v[62:65], v[148:151], v[204:207], v[62:65]
	s_waitcnt lgkmcnt(0)
	v_mfma_f32_16x16x32_bf16 v[2:5], v[172:175], v[212:215], v[2:5]
	v_mfma_f32_16x16x32_bf16 v[6:9], v[172:175], v[216:219], v[6:9]
	v_mfma_f32_16x16x32_bf16 v[10:13], v[172:175], v[220:223], v[10:13]
	v_mfma_f32_16x16x32_bf16 v[14:17], v[172:175], v[224:227], v[14:17]
	v_mfma_f32_16x16x32_bf16 v[18:21], v[176:179], v[212:215], v[18:21]
	v_mfma_f32_16x16x32_bf16 v[22:25], v[176:179], v[216:219], v[22:25]
	v_mfma_f32_16x16x32_bf16 v[26:29], v[176:179], v[220:223], v[26:29]
	v_mfma_f32_16x16x32_bf16 v[30:33], v[176:179], v[224:227], v[30:33]
	v_mfma_f32_16x16x32_bf16 v[34:37], v[180:183], v[212:215], v[34:37]
	v_mfma_f32_16x16x32_bf16 v[38:41], v[180:183], v[216:219], v[38:41]
	v_mfma_f32_16x16x32_bf16 v[42:45], v[180:183], v[220:223], v[42:45]
	v_mfma_f32_16x16x32_bf16 v[46:49], v[180:183], v[224:227], v[46:49]
	v_mfma_f32_16x16x32_bf16 v[50:53], v[184:187], v[212:215], v[50:53]
	v_mfma_f32_16x16x32_bf16 v[54:57], v[184:187], v[216:219], v[54:57]
	v_mfma_f32_16x16x32_bf16 v[58:61], v[184:187], v[220:223], v[58:61]
	v_mfma_f32_16x16x32_bf16 v[62:65], v[184:187], v[224:227], v[62:65]
	s_setprio 0
	s_waitcnt vmcnt(6)
	s_barrier
	v_add_u32_e32 v236, s42, v232
	v_add_u32_e32 v237, s42, v233
	ds_read_b128 v[188:191], v236
	ds_read_b128 v[196:199], v236 offset:2048
	ds_read_b128 v[200:203], v236 offset:4096
	ds_read_b128 v[204:207], v236 offset:6144
	ds_read_b128 v[212:215], v237
	ds_read_b128 v[216:219], v237 offset:2048
	ds_read_b128 v[220:223], v237 offset:4096
	ds_read_b128 v[224:227], v237 offset:6144
	s_add_i32 m0, s51, 0x6000
	s_nop 0
	global_load_lds_dwordx4 v229, s[46:47]
	s_add_i32 m0, s51, 0x6400
	s_nop 0
	global_load_lds_dwordx4 v231, s[46:47]
	s_add_i32 m0, s51, 0x8000
	s_nop 0
	global_load_lds_dwordx4 v228, s[48:49]
	s_add_i32 m0, s51, 0x8400
	s_nop 0
	global_load_lds_dwordx4 v230, s[48:49]
	s_add_i32 m0, s51, 0xa000
	s_nop 0
	global_load_lds_dwordx4 v229, s[48:49]
	s_add_i32 m0, s51, 0xa400
	s_nop 0
	global_load_lds_dwordx4 v231, s[48:49]
	s_waitcnt lgkmcnt(4)
	s_setprio 1
	v_mfma_f32_16x16x32_bf16 v[66:69], v[136:139], v[188:191], v[66:69]
	v_mfma_f32_16x16x32_bf16 v[70:73], v[136:139], v[196:199], v[70:73]
	v_mfma_f32_16x16x32_bf16 v[74:77], v[136:139], v[200:203], v[74:77]
	v_mfma_f32_16x16x32_bf16 v[78:81], v[136:139], v[204:207], v[78:81]
	v_mfma_f32_16x16x32_bf16 v[82:85], v[140:143], v[188:191], v[82:85]
	v_mfma_f32_16x16x32_bf16 v[86:89], v[140:143], v[196:199], v[86:89]
	v_mfma_f32_16x16x32_bf16 v[90:93], v[140:143], v[200:203], v[90:93]
	v_mfma_f32_16x16x32_bf16 v[94:97], v[140:143], v[204:207], v[94:97]
	v_mfma_f32_16x16x32_bf16 v[98:101], v[144:147], v[188:191], v[98:101]
	v_mfma_f32_16x16x32_bf16 v[102:105], v[144:147], v[196:199], v[102:105]
	v_mfma_f32_16x16x32_bf16 v[106:109], v[144:147], v[200:203], v[106:109]
	v_mfma_f32_16x16x32_bf16 v[110:113], v[144:147], v[204:207], v[110:113]
	v_mfma_f32_16x16x32_bf16 v[114:117], v[148:151], v[188:191], v[114:117]
	v_mfma_f32_16x16x32_bf16 v[118:121], v[148:151], v[196:199], v[118:121]
	v_mfma_f32_16x16x32_bf16 v[122:125], v[148:151], v[200:203], v[122:125]
	v_mfma_f32_16x16x32_bf16 v[126:129], v[148:151], v[204:207], v[126:129]
	s_waitcnt lgkmcnt(0)
	v_mfma_f32_16x16x32_bf16 v[66:69], v[172:175], v[212:215], v[66:69]
	v_mfma_f32_16x16x32_bf16 v[70:73], v[172:175], v[216:219], v[70:73]
	v_mfma_f32_16x16x32_bf16 v[74:77], v[172:175], v[220:223], v[74:77]
	v_mfma_f32_16x16x32_bf16 v[78:81], v[172:175], v[224:227], v[78:81]
	v_mfma_f32_16x16x32_bf16 v[82:85], v[176:179], v[212:215], v[82:85]
	v_mfma_f32_16x16x32_bf16 v[86:89], v[176:179], v[216:219], v[86:89]
	v_mfma_f32_16x16x32_bf16 v[90:93], v[176:179], v[220:223], v[90:93]
	v_mfma_f32_16x16x32_bf16 v[94:97], v[176:179], v[224:227], v[94:97]
	v_mfma_f32_16x16x32_bf16 v[98:101], v[180:183], v[212:215], v[98:101]
	v_mfma_f32_16x16x32_bf16 v[102:105], v[180:183], v[216:219], v[102:105]
	v_mfma_f32_16x16x32_bf16 v[106:109], v[180:183], v[220:223], v[106:109]
	v_mfma_f32_16x16x32_bf16 v[110:113], v[180:183], v[224:227], v[110:113]
	v_mfma_f32_16x16x32_bf16 v[114:117], v[184:187], v[212:215], v[114:117]
	v_mfma_f32_16x16x32_bf16 v[118:121], v[184:187], v[216:219], v[118:121]
	v_mfma_f32_16x16x32_bf16 v[122:125], v[184:187], v[220:223], v[122:125]
	v_mfma_f32_16x16x32_bf16 v[126:129], v[184:187], v[224:227], v[126:129]
	s_setprio 0
	v_add_u32_e32 v228, 0x80, v228
	v_add_u32_e32 v229, 0x80, v229
	v_add_u32_e32 v230, 0x80, v230
	v_add_u32_e32 v231, 0x80, v231
	s_waitcnt vmcnt(4)
	s_barrier
	s_add_i32 s52, s52, 1
	s_cmp_lt_u32 s52, 29
	s_cbranch_scc1 .Lfin3_loop
	v_add_u32_e32 v234, s22, v232
	v_add_u32_e32 v236, s28, v232
	v_add_u32_e32 v235, s22, v233
	v_add_u32_e32 v237, s28, v233
	ds_read_b128 v[136:139], v234
	ds_read_b128 v[140:143], v234 offset:2048
	ds_read_b128 v[144:147], v234 offset:4096
	ds_read_b128 v[148:151], v234 offset:6144
	ds_read_b128 v[188:191], v236
	ds_read_b128 v[196:199], v236 offset:2048
	ds_read_b128 v[200:203], v236 offset:4096
	ds_read_b128 v[204:207], v236 offset:6144
	ds_read_b128 v[172:175], v235
	ds_read_b128 v[176:179], v235 offset:2048
	ds_read_b128 v[180:183], v235 offset:4096
	ds_read_b128 v[184:187], v235 offset:6144
	ds_read_b128 v[212:215], v237
	ds_read_b128 v[216:219], v237 offset:2048
	ds_read_b128 v[220:223], v237 offset:4096
	ds_read_b128 v[224:227], v237 offset:6144
	s_waitcnt lgkmcnt(8)
	s_setprio 1
	v_mfma_f32_16x16x32_bf16 v[2:5], v[136:139], v[188:191], v[2:5]
	v_mfma_f32_16x16x32_bf16 v[6:9], v[136:139], v[196:199], v[6:9]
	v_mfma_f32_16x16x32_bf16 v[10:13], v[136:139], v[200:203], v[10:13]
	v_mfma_f32_16x16x32_bf16 v[14:17], v[136:139], v[204:207], v[14:17]
	v_mfma_f32_16x16x32_bf16 v[18:21], v[140:143], v[188:191], v[18:21]
	v_mfma_f32_16x16x32_bf16 v[22:25], v[140:143], v[196:199], v[22:25]
	v_mfma_f32_16x16x32_bf16 v[26:29], v[140:143], v[200:203], v[26:29]
	v_mfma_f32_16x16x32_bf16 v[30:33], v[140:143], v[204:207], v[30:33]
	v_mfma_f32_16x16x32_bf16 v[34:37], v[144:147], v[188:191], v[34:37]
	v_mfma_f32_16x16x32_bf16 v[38:41], v[144:147], v[196:199], v[38:41]
	v_mfma_f32_16x16x32_bf16 v[42:45], v[144:147], v[200:203], v[42:45]
	v_mfma_f32_16x16x32_bf16 v[46:49], v[144:147], v[204:207], v[46:49]
	v_mfma_f32_16x16x32_bf16 v[50:53], v[148:151], v[188:191], v[50:53]
	v_mfma_f32_16x16x32_bf16 v[54:57], v[148:151], v[196:199], v[54:57]
	v_mfma_f32_16x16x32_bf16 v[58:61], v[148:151], v[200:203], v[58:61]
	v_mfma_f32_16x16x32_bf16 v[62:65], v[148:151], v[204:207], v[62:65]
	s_waitcnt lgkmcnt(0)
	v_mfma_f32_16x16x32_bf16 v[2:5], v[172:175], v[212:215], v[2:5]
	v_mfma_f32_16x16x32_bf16 v[6:9], v[172:175], v[216:219], v[6:9]
	v_mfma_f32_16x16x32_bf16 v[10:13], v[172:175], v[220:223], v[10:13]
	v_mfma_f32_16x16x32_bf16 v[14:17], v[172:175], v[224:227], v[14:17]
	v_mfma_f32_16x16x32_bf16 v[18:21], v[176:179], v[212:215], v[18:21]
	v_mfma_f32_16x16x32_bf16 v[22:25], v[176:179], v[216:219], v[22:25]
	v_mfma_f32_16x16x32_bf16 v[26:29], v[176:179], v[220:223], v[26:29]
	v_mfma_f32_16x16x32_bf16 v[30:33], v[176:179], v[224:227], v[30:33]
	v_mfma_f32_16x16x32_bf16 v[34:37], v[180:183], v[212:215], v[34:37]
	v_mfma_f32_16x16x32_bf16 v[38:41], v[180:183], v[216:219], v[38:41]
	v_mfma_f32_16x16x32_bf16 v[42:45], v[180:183], v[220:223], v[42:45]
	v_mfma_f32_16x16x32_bf16 v[46:49], v[180:183], v[224:227], v[46:49]
	v_mfma_f32_16x16x32_bf16 v[50:53], v[184:187], v[212:215], v[50:53]
	v_mfma_f32_16x16x32_bf16 v[54:57], v[184:187], v[216:219], v[54:57]
	v_mfma_f32_16x16x32_bf16 v[58:61], v[184:187], v[220:223], v[58:61]
	v_mfma_f32_16x16x32_bf16 v[62:65], v[184:187], v[224:227], v[62:65]
	s_setprio 0
	s_waitcnt vmcnt(0)
	s_barrier
	v_add_u32_e32 v236, s40, v232
	v_add_u32_e32 v237, s40, v233
	ds_read_b128 v[188:191], v236
	ds_read_b128 v[196:199], v236 offset:2048
	ds_read_b128 v[200:203], v236 offset:4096
	ds_read_b128 v[204:207], v236 offset:6144
	ds_read_b128 v[212:215], v237
	ds_read_b128 v[216:219], v237 offset:2048
	ds_read_b128 v[220:223], v237 offset:4096
	ds_read_b128 v[224:227], v237 offset:6144
	s_waitcnt lgkmcnt(4)
	s_setprio 1
	v_mfma_f32_16x16x32_bf16 v[66:69], v[136:139], v[188:191], v[66:69]
	v_mfma_f32_16x16x32_bf16 v[70:73], v[136:139], v[196:199], v[70:73]
	v_mfma_f32_16x16x32_bf16 v[74:77], v[136:139], v[200:203], v[74:77]
	v_mfma_f32_16x16x32_bf16 v[78:81], v[136:139], v[204:207], v[78:81]
	v_mfma_f32_16x16x32_bf16 v[82:85], v[140:143], v[188:191], v[82:85]
	v_mfma_f32_16x16x32_bf16 v[86:89], v[140:143], v[196:199], v[86:89]
	v_mfma_f32_16x16x32_bf16 v[90:93], v[140:143], v[200:203], v[90:93]
	v_mfma_f32_16x16x32_bf16 v[94:97], v[140:143], v[204:207], v[94:97]
	v_mfma_f32_16x16x32_bf16 v[98:101], v[144:147], v[188:191], v[98:101]
	v_mfma_f32_16x16x32_bf16 v[102:105], v[144:147], v[196:199], v[102:105]
	v_mfma_f32_16x16x32_bf16 v[106:109], v[144:147], v[200:203], v[106:109]
	v_mfma_f32_16x16x32_bf16 v[110:113], v[144:147], v[204:207], v[110:113]
	v_mfma_f32_16x16x32_bf16 v[114:117], v[148:151], v[188:191], v[114:117]
	v_mfma_f32_16x16x32_bf16 v[118:121], v[148:151], v[196:199], v[118:121]
	v_mfma_f32_16x16x32_bf16 v[122:125], v[148:151], v[200:203], v[122:125]
	v_mfma_f32_16x16x32_bf16 v[126:129], v[148:151], v[204:207], v[126:129]
	s_waitcnt lgkmcnt(0)
	v_mfma_f32_16x16x32_bf16 v[66:69], v[172:175], v[212:215], v[66:69]
	v_mfma_f32_16x16x32_bf16 v[70:73], v[172:175], v[216:219], v[70:73]
	v_mfma_f32_16x16x32_bf16 v[74:77], v[172:175], v[220:223], v[74:77]
	v_mfma_f32_16x16x32_bf16 v[78:81], v[172:175], v[224:227], v[78:81]
	v_mfma_f32_16x16x32_bf16 v[82:85], v[176:179], v[212:215], v[82:85]
	v_mfma_f32_16x16x32_bf16 v[86:89], v[176:179], v[216:219], v[86:89]
	v_mfma_f32_16x16x32_bf16 v[90:93], v[176:179], v[220:223], v[90:93]
	v_mfma_f32_16x16x32_bf16 v[94:97], v[176:179], v[224:227], v[94:97]
	v_mfma_f32_16x16x32_bf16 v[98:101], v[180:183], v[212:215], v[98:101]
	v_mfma_f32_16x16x32_bf16 v[102:105], v[180:183], v[216:219], v[102:105]
	v_mfma_f32_16x16x32_bf16 v[106:109], v[180:183], v[220:223], v[106:109]
	v_mfma_f32_16x16x32_bf16 v[110:113], v[180:183], v[224:227], v[110:113]
	v_mfma_f32_16x16x32_bf16 v[114:117], v[184:187], v[212:215], v[114:117]
	v_mfma_f32_16x16x32_bf16 v[118:121], v[184:187], v[216:219], v[118:121]
	v_mfma_f32_16x16x32_bf16 v[122:125], v[184:187], v[220:223], v[122:125]
	v_mfma_f32_16x16x32_bf16 v[126:129], v[184:187], v[224:227], v[126:129]
	s_setprio 0
	s_nop 7
	s_barrier
	s_load_dwordx2 s[58:59], s[12:13], 0x100
	v_lshrrev_b32_e32 v241, 5, v131
	v_and_b32_e32 v242, 31, v131
	v_lshlrev_b32_e32 v243, 4, v242
	s_movk_i32 s56, 0x210
	v_mad_u32_u24 v239, v241, s56, v243
	v_add_u32_e32 v239, 16, v239
	v_lshlrev_b32_e32 v240, 13, v241
	v_or_b32_e32 v240, v240, v243
	s_lshl_b32 s56, s53, 13
	s_lshl_b32 s57, s54, 2
	s_add_i32 s56, s56, s57
	s_waitcnt lgkmcnt(0)
	s_add_u32 s58, s58, s56
	s_addc_u32 s59, s59, 0
	ds_write_b32 v238, v2
	ds_write_b32 v238, v3 offset:528
	ds_write_b32 v238, v4 offset:1056
	ds_write_b32 v238, v5 offset:1584
	ds_write_b32 v238, v6 offset:64
	ds_write_b32 v238, v7 offset:592
	ds_write_b32 v238, v8 offset:1120
	ds_write_b32 v238, v9 offset:1648
	ds_write_b32 v238, v10 offset:128
	ds_write_b32 v238, v11 offset:656
	ds_write_b32 v238, v12 offset:1184
	ds_write_b32 v238, v13 offset:1712
	ds_write_b32 v238, v14 offset:192
	ds_write_b32 v238, v15 offset:720
	ds_write_b32 v238, v16 offset:1248
	ds_write_b32 v238, v17 offset:1776
	ds_write_b32 v238, v18 offset:8448
	ds_write_b32 v238, v19 offset:8976
	ds_write_b32 v238, v20 offset:9504
	ds_write_b32 v238, v21 offset:10032
	ds_write_b32 v238, v22 offset:8512
	ds_write_b32 v238, v23 offset:9040
	ds_write_b32 v238, v24 offset:9568
	ds_write_b32 v238, v25 offset:10096
	ds_write_b32 v238, v26 offset:8576
	ds_write_b32 v238, v27 offset:9104
	ds_write_b32 v238, v28 offset:9632
	ds_write_b32 v238, v29 offset:10160
	ds_write_b32 v238, v30 offset:8640
	ds_write_b32 v238, v31 offset:9168
	ds_write_b32 v238, v32 offset:9696
	ds_write_b32 v238, v33 offset:10224
	ds_write_b32 v238, v34 offset:16896
	ds_write_b32 v238, v35 offset:17424
	ds_write_b32 v238, v36 offset:17952
	ds_write_b32 v238, v37 offset:18480
	ds_write_b32 v238, v38 offset:16960
	ds_write_b32 v238, v39 offset:17488
	ds_write_b32 v238, v40 offset:18016
	ds_write_b32 v238, v41 offset:18544
	ds_write_b32 v238, v42 offset:17024
	ds_write_b32 v238, v43 offset:17552
	ds_write_b32 v238, v44 offset:18080
	ds_write_b32 v238, v45 offset:18608
	ds_write_b32 v238, v46 offset:17088
	ds_write_b32 v238, v47 offset:17616
	ds_write_b32 v238, v48 offset:18144
	ds_write_b32 v238, v49 offset:18672
	ds_write_b32 v238, v50 offset:25344
	ds_write_b32 v238, v51 offset:25872
	ds_write_b32 v238, v52 offset:26400
	ds_write_b32 v238, v53 offset:26928
	ds_write_b32 v238, v54 offset:25408
	ds_write_b32 v238, v55 offset:25936
	ds_write_b32 v238, v56 offset:26464
	ds_write_b32 v238, v57 offset:26992
	ds_write_b32 v238, v58 offset:25472
	ds_write_b32 v238, v59 offset:26000
	ds_write_b32 v238, v60 offset:26528
	ds_write_b32 v238, v61 offset:27056
	ds_write_b32 v238, v62 offset:25536
	ds_write_b32 v238, v63 offset:26064
	ds_write_b32 v238, v64 offset:26592
	ds_write_b32 v238, v65 offset:27120
	s_mov_b32 s0, s58
	s_mov_b32 s1, s59
	global_load_dwordx4 v[136:139], v240, s[0:1]
	s_add_u32 s0, s0, 0x10000
	s_addc_u32 s1, s1, 0
	global_load_dwordx4 v[140:143], v240, s[0:1]
	s_add_u32 s0, s0, 0x10000
	s_addc_u32 s1, s1, 0
	global_load_dwordx4 v[144:147], v240, s[0:1]
	s_add_u32 s0, s0, 0x10000
	s_addc_u32 s1, s1, 0
	global_load_dwordx4 v[148:151], v240, s[0:1]
	s_add_u32 s0, s0, 0x10000
	s_addc_u32 s1, s1, 0
	global_load_dwordx4 v[172:175], v240, s[0:1]
	s_add_u32 s0, s0, 0x10000
	s_addc_u32 s1, s1, 0
	global_load_dwordx4 v[176:179], v240, s[0:1]
	s_add_u32 s0, s0, 0x10000
	s_addc_u32 s1, s1, 0
	global_load_dwordx4 v[180:183], v240, s[0:1]
	s_add_u32 s0, s0, 0x10000
	s_addc_u32 s1, s1, 0
	global_load_dwordx4 v[184:187], v240, s[0:1]
	s_add_u32 s0, s0, 0x10000
	s_addc_u32 s1, s1, 0
	global_load_dwordx4 v[188:191], v240, s[0:1]
	s_add_u32 s0, s0, 0x10000
	s_addc_u32 s1, s1, 0
	global_load_dwordx4 v[196:199], v240, s[0:1]
	s_add_u32 s0, s0, 0x10000
	s_addc_u32 s1, s1, 0
	global_load_dwordx4 v[200:203], v240, s[0:1]
	s_add_u32 s0, s0, 0x10000
	s_addc_u32 s1, s1, 0
	global_load_dwordx4 v[204:207], v240, s[0:1]
	s_add_u32 s0, s0, 0x10000
	s_addc_u32 s1, s1, 0
	global_load_dwordx4 v[212:215], v240, s[0:1]
	s_add_u32 s0, s0, 0x10000
	s_addc_u32 s1, s1, 0
	global_load_dwordx4 v[216:219], v240, s[0:1]
	s_add_u32 s0, s0, 0x10000
	s_addc_u32 s1, s1, 0
	global_load_dwordx4 v[220:223], v240, s[0:1]
	s_add_u32 s0, s0, 0x10000
	s_addc_u32 s1, s1, 0
	global_load_dwordx4 v[224:227], v240, s[0:1]
	s_waitcnt lgkmcnt(0)
	s_barrier
	ds_read_b128 v[2:5], v239
	ds_read_b128 v[6:9], v239 offset:4224
	ds_read_b128 v[10:13], v239 offset:8448
	ds_read_b128 v[14:17], v239 offset:12672
	ds_read_b128 v[18:21], v239 offset:16896
	ds_read_b128 v[22:25], v239 offset:21120
	ds_read_b128 v[26:29], v239 offset:25344
	ds_read_b128 v[30:33], v239 offset:29568
	ds_read_b128 v[34:37], v239 offset:33792
	ds_read_b128 v[38:41], v239 offset:38016
	ds_read_b128 v[42:45], v239 offset:42240
	ds_read_b128 v[46:49], v239 offset:46464
	ds_read_b128 v[50:53], v239 offset:50688
	ds_read_b128 v[54:57], v239 offset:54912
	ds_read_b128 v[58:61], v239 offset:59136
	ds_read_b128 v[62:65], v239 offset:63360
	s_mov_b32 s0, s58
	s_mov_b32 s1, s59
	s_waitcnt vmcnt(15) lgkmcnt(15)
	v_pk_add_f32 v[2:3], v[2:3], v[136:137]
	v_pk_add_f32 v[4:5], v[4:5], v[138:139]
	s_waitcnt vmcnt(14) lgkmcnt(14)
	v_pk_add_f32 v[6:7], v[6:7], v[140:141]
	v_pk_add_f32 v[8:9], v[8:9], v[142:143]
	s_waitcnt vmcnt(13) lgkmcnt(13)
	v_pk_add_f32 v[10:11], v[10:11], v[144:145]
	v_pk_add_f32 v[12:13], v[12:13], v[146:147]
	s_waitcnt vmcnt(12) lgkmcnt(12)
	v_pk_add_f32 v[14:15], v[14:15], v[148:149]
	v_pk_add_f32 v[16:17], v[16:17], v[150:151]
	s_waitcnt vmcnt(11) lgkmcnt(11)
	v_pk_add_f32 v[18:19], v[18:19], v[172:173]
	v_pk_add_f32 v[20:21], v[20:21], v[174:175]
	s_waitcnt vmcnt(10) lgkmcnt(10)
	v_pk_add_f32 v[22:23], v[22:23], v[176:177]
	v_pk_add_f32 v[24:25], v[24:25], v[178:179]
	s_waitcnt vmcnt(9) lgkmcnt(9)
	v_pk_add_f32 v[26:27], v[26:27], v[180:181]
	v_pk_add_f32 v[28:29], v[28:29], v[182:183]
	s_waitcnt vmcnt(8) lgkmcnt(8)
	v_pk_add_f32 v[30:31], v[30:31], v[184:185]
	v_pk_add_f32 v[32:33], v[32:33], v[186:187]
	s_waitcnt vmcnt(7) lgkmcnt(7)
	v_pk_add_f32 v[34:35], v[34:35], v[188:189]
	v_pk_add_f32 v[36:37], v[36:37], v[190:191]
	s_waitcnt vmcnt(6) lgkmcnt(6)
	v_pk_add_f32 v[38:39], v[38:39], v[196:197]
	v_pk_add_f32 v[40:41], v[40:41], v[198:199]
	s_waitcnt vmcnt(5) lgkmcnt(5)
	v_pk_add_f32 v[42:43], v[42:43], v[200:201]
	v_pk_add_f32 v[44:45], v[44:45], v[202:203]
	s_waitcnt vmcnt(4) lgkmcnt(4)
	v_pk_add_f32 v[46:47], v[46:47], v[204:205]
	v_pk_add_f32 v[48:49], v[48:49], v[206:207]
	s_waitcnt vmcnt(3) lgkmcnt(3)
	v_pk_add_f32 v[50:51], v[50:51], v[212:213]
	v_pk_add_f32 v[52:53], v[52:53], v[214:215]
	s_waitcnt vmcnt(2) lgkmcnt(2)
	v_pk_add_f32 v[54:55], v[54:55], v[216:217]
	v_pk_add_f32 v[56:57], v[56:57], v[218:219]
	s_waitcnt vmcnt(1) lgkmcnt(1)
	v_pk_add_f32 v[58:59], v[58:59], v[220:221]
	v_pk_add_f32 v[60:61], v[60:61], v[222:223]
	s_waitcnt vmcnt(0) lgkmcnt(0)
	v_pk_add_f32 v[62:63], v[62:63], v[224:225]
	v_pk_add_f32 v[64:65], v[64:65], v[226:227]
	global_store_dwordx4 v240, v[2:5], s[0:1]
	s_add_u32 s0, s0, 0x10000
	s_addc_u32 s1, s1, 0
	global_store_dwordx4 v240, v[6:9], s[0:1]
	s_add_u32 s0, s0, 0x10000
	s_addc_u32 s1, s1, 0
	global_store_dwordx4 v240, v[10:13], s[0:1]
	s_add_u32 s0, s0, 0x10000
	s_addc_u32 s1, s1, 0
	global_store_dwordx4 v240, v[14:17], s[0:1]
	s_add_u32 s0, s0, 0x10000
	s_addc_u32 s1, s1, 0
	global_store_dwordx4 v240, v[18:21], s[0:1]
	s_add_u32 s0, s0, 0x10000
	s_addc_u32 s1, s1, 0
	global_store_dwordx4 v240, v[22:25], s[0:1]
	s_add_u32 s0, s0, 0x10000
	s_addc_u32 s1, s1, 0
	global_store_dwordx4 v240, v[26:29], s[0:1]
	s_add_u32 s0, s0, 0x10000
	s_addc_u32 s1, s1, 0
	global_store_dwordx4 v240, v[30:33], s[0:1]
	s_add_u32 s0, s0, 0x10000
	s_addc_u32 s1, s1, 0
	global_store_dwordx4 v240, v[34:37], s[0:1]
	s_add_u32 s0, s0, 0x10000
	s_addc_u32 s1, s1, 0
	global_store_dwordx4 v240, v[38:41], s[0:1]
	s_add_u32 s0, s0, 0x10000
	s_addc_u32 s1, s1, 0
	global_store_dwordx4 v240, v[42:45], s[0:1]
	s_add_u32 s0, s0, 0x10000
	s_addc_u32 s1, s1, 0
	global_store_dwordx4 v240, v[46:49], s[0:1]
	s_add_u32 s0, s0, 0x10000
	s_addc_u32 s1, s1, 0
	global_store_dwordx4 v240, v[50:53], s[0:1]
	s_add_u32 s0, s0, 0x10000
	s_addc_u32 s1, s1, 0
	global_store_dwordx4 v240, v[54:57], s[0:1]
	s_add_u32 s0, s0, 0x10000
	s_addc_u32 s1, s1, 0
	global_store_dwordx4 v240, v[58:61], s[0:1]
	s_add_u32 s0, s0, 0x10000
	s_addc_u32 s1, s1, 0
	global_store_dwordx4 v240, v[62:65], s[0:1]
	s_add_u32 s58, s58, 0x1000
	s_addc_u32 s59, s59, 0
	s_waitcnt lgkmcnt(0)
	s_barrier
	ds_write_b32 v238, v66
	ds_write_b32 v238, v67 offset:528
	ds_write_b32 v238, v68 offset:1056
	ds_write_b32 v238, v69 offset:1584
	ds_write_b32 v238, v70 offset:64
	ds_write_b32 v238, v71 offset:592
	ds_write_b32 v238, v72 offset:1120
	ds_write_b32 v238, v73 offset:1648
	ds_write_b32 v238, v74 offset:128
	ds_write_b32 v238, v75 offset:656
	ds_write_b32 v238, v76 offset:1184
	ds_write_b32 v238, v77 offset:1712
	ds_write_b32 v238, v78 offset:192
	ds_write_b32 v238, v79 offset:720
	ds_write_b32 v238, v80 offset:1248
	ds_write_b32 v238, v81 offset:1776
	ds_write_b32 v238, v82 offset:8448
	ds_write_b32 v238, v83 offset:8976
	ds_write_b32 v238, v84 offset:9504
	ds_write_b32 v238, v85 offset:10032
	ds_write_b32 v238, v86 offset:8512
	ds_write_b32 v238, v87 offset:9040
	ds_write_b32 v238, v88 offset:9568
	ds_write_b32 v238, v89 offset:10096
	ds_write_b32 v238, v90 offset:8576
	ds_write_b32 v238, v91 offset:9104
	ds_write_b32 v238, v92 offset:9632
	ds_write_b32 v238, v93 offset:10160
	ds_write_b32 v238, v94 offset:8640
	ds_write_b32 v238, v95 offset:9168
	ds_write_b32 v238, v96 offset:9696
	ds_write_b32 v238, v97 offset:10224
	ds_write_b32 v238, v98 offset:16896
	ds_write_b32 v238, v99 offset:17424
	ds_write_b32 v238, v100 offset:17952
	ds_write_b32 v238, v101 offset:18480
	ds_write_b32 v238, v102 offset:16960
	ds_write_b32 v238, v103 offset:17488
	ds_write_b32 v238, v104 offset:18016
	ds_write_b32 v238, v105 offset:18544
	ds_write_b32 v238, v106 offset:17024
	ds_write_b32 v238, v107 offset:17552
	ds_write_b32 v238, v108 offset:18080
	ds_write_b32 v238, v109 offset:18608
	ds_write_b32 v238, v110 offset:17088
	ds_write_b32 v238, v111 offset:17616
	ds_write_b32 v238, v112 offset:18144
	ds_write_b32 v238, v113 offset:18672
	ds_write_b32 v238, v114 offset:25344
	ds_write_b32 v238, v115 offset:25872
	ds_write_b32 v238, v116 offset:26400
	ds_write_b32 v238, v117 offset:26928
	ds_write_b32 v238, v118 offset:25408
	ds_write_b32 v238, v119 offset:25936
	ds_write_b32 v238, v120 offset:26464
	ds_write_b32 v238, v121 offset:26992
	ds_write_b32 v238, v122 offset:25472
	ds_write_b32 v238, v123 offset:26000
	ds_write_b32 v238, v124 offset:26528
	ds_write_b32 v238, v125 offset:27056
	ds_write_b32 v238, v126 offset:25536
	ds_write_b32 v238, v127 offset:26064
	ds_write_b32 v238, v128 offset:26592
	ds_write_b32 v238, v129 offset:27120
	s_mov_b32 s0, s58
	s_mov_b32 s1, s59
	global_load_dwordx4 v[136:139], v240, s[0:1]
	s_add_u32 s0, s0, 0x10000
	s_addc_u32 s1, s1, 0
	global_load_dwordx4 v[140:143], v240, s[0:1]
	s_add_u32 s0, s0, 0x10000
	s_addc_u32 s1, s1, 0
	global_load_dwordx4 v[144:147], v240, s[0:1]
	s_add_u32 s0, s0, 0x10000
	s_addc_u32 s1, s1, 0
	global_load_dwordx4 v[148:151], v240, s[0:1]
	s_add_u32 s0, s0, 0x10000
	s_addc_u32 s1, s1, 0
	global_load_dwordx4 v[172:175], v240, s[0:1]
	s_add_u32 s0, s0, 0x10000
	s_addc_u32 s1, s1, 0
	global_load_dwordx4 v[176:179], v240, s[0:1]
	s_add_u32 s0, s0, 0x10000
	s_addc_u32 s1, s1, 0
	global_load_dwordx4 v[180:183], v240, s[0:1]
	s_add_u32 s0, s0, 0x10000
	s_addc_u32 s1, s1, 0
	global_load_dwordx4 v[184:187], v240, s[0:1]
	s_add_u32 s0, s0, 0x10000
	s_addc_u32 s1, s1, 0
	global_load_dwordx4 v[188:191], v240, s[0:1]
	s_add_u32 s0, s0, 0x10000
	s_addc_u32 s1, s1, 0
	global_load_dwordx4 v[196:199], v240, s[0:1]
	s_add_u32 s0, s0, 0x10000
	s_addc_u32 s1, s1, 0
	global_load_dwordx4 v[200:203], v240, s[0:1]
	s_add_u32 s0, s0, 0x10000
	s_addc_u32 s1, s1, 0
	global_load_dwordx4 v[204:207], v240, s[0:1]
	s_add_u32 s0, s0, 0x10000
	s_addc_u32 s1, s1, 0
	global_load_dwordx4 v[212:215], v240, s[0:1]
	s_add_u32 s0, s0, 0x10000
	s_addc_u32 s1, s1, 0
	global_load_dwordx4 v[216:219], v240, s[0:1]
	s_add_u32 s0, s0, 0x10000
	s_addc_u32 s1, s1, 0
	global_load_dwordx4 v[220:223], v240, s[0:1]
	s_add_u32 s0, s0, 0x10000
	s_addc_u32 s1, s1, 0
	global_load_dwordx4 v[224:227], v240, s[0:1]
	s_waitcnt lgkmcnt(0)
	s_barrier
	ds_read_b128 v[66:69], v239
	ds_read_b128 v[70:73], v239 offset:4224
	ds_read_b128 v[74:77], v239 offset:8448
	ds_read_b128 v[78:81], v239 offset:12672
	ds_read_b128 v[82:85], v239 offset:16896
	ds_read_b128 v[86:89], v239 offset:21120
	ds_read_b128 v[90:93], v239 offset:25344
	ds_read_b128 v[94:97], v239 offset:29568
	ds_read_b128 v[98:101], v239 offset:33792
	ds_read_b128 v[102:105], v239 offset:38016
	ds_read_b128 v[106:109], v239 offset:42240
	ds_read_b128 v[110:113], v239 offset:46464
	ds_read_b128 v[114:117], v239 offset:50688
	ds_read_b128 v[118:121], v239 offset:54912
	ds_read_b128 v[122:125], v239 offset:59136
	ds_read_b128 v[126:129], v239 offset:63360
	s_mov_b32 s0, s58
	s_mov_b32 s1, s59
	s_waitcnt vmcnt(15) lgkmcnt(15)
	v_pk_add_f32 v[66:67], v[66:67], v[136:137]
	v_pk_add_f32 v[68:69], v[68:69], v[138:139]
	s_waitcnt vmcnt(14) lgkmcnt(14)
	v_pk_add_f32 v[70:71], v[70:71], v[140:141]
	v_pk_add_f32 v[72:73], v[72:73], v[142:143]
	s_waitcnt vmcnt(13) lgkmcnt(13)
	v_pk_add_f32 v[74:75], v[74:75], v[144:145]
	v_pk_add_f32 v[76:77], v[76:77], v[146:147]
	s_waitcnt vmcnt(12) lgkmcnt(12)
	v_pk_add_f32 v[78:79], v[78:79], v[148:149]
	v_pk_add_f32 v[80:81], v[80:81], v[150:151]
	s_waitcnt vmcnt(11) lgkmcnt(11)
	v_pk_add_f32 v[82:83], v[82:83], v[172:173]
	v_pk_add_f32 v[84:85], v[84:85], v[174:175]
	s_waitcnt vmcnt(10) lgkmcnt(10)
	v_pk_add_f32 v[86:87], v[86:87], v[176:177]
	v_pk_add_f32 v[88:89], v[88:89], v[178:179]
	s_waitcnt vmcnt(9) lgkmcnt(9)
	v_pk_add_f32 v[90:91], v[90:91], v[180:181]
	v_pk_add_f32 v[92:93], v[92:93], v[182:183]
	s_waitcnt vmcnt(8) lgkmcnt(8)
	v_pk_add_f32 v[94:95], v[94:95], v[184:185]
	v_pk_add_f32 v[96:97], v[96:97], v[186:187]
	s_waitcnt vmcnt(7) lgkmcnt(7)
	v_pk_add_f32 v[98:99], v[98:99], v[188:189]
	v_pk_add_f32 v[100:101], v[100:101], v[190:191]
	s_waitcnt vmcnt(6) lgkmcnt(6)
	v_pk_add_f32 v[102:103], v[102:103], v[196:197]
	v_pk_add_f32 v[104:105], v[104:105], v[198:199]
	s_waitcnt vmcnt(5) lgkmcnt(5)
	v_pk_add_f32 v[106:107], v[106:107], v[200:201]
	v_pk_add_f32 v[108:109], v[108:109], v[202:203]
	s_waitcnt vmcnt(4) lgkmcnt(4)
	v_pk_add_f32 v[110:111], v[110:111], v[204:205]
	v_pk_add_f32 v[112:113], v[112:113], v[206:207]
	s_waitcnt vmcnt(3) lgkmcnt(3)
	v_pk_add_f32 v[114:115], v[114:115], v[212:213]
	v_pk_add_f32 v[116:117], v[116:117], v[214:215]
	s_waitcnt vmcnt(2) lgkmcnt(2)
	v_pk_add_f32 v[118:119], v[118:119], v[216:217]
	v_pk_add_f32 v[120:121], v[120:121], v[218:219]
	s_waitcnt vmcnt(1) lgkmcnt(1)
	v_pk_add_f32 v[122:123], v[122:123], v[220:221]
	v_pk_add_f32 v[124:125], v[124:125], v[222:223]
	s_waitcnt vmcnt(0) lgkmcnt(0)
	v_pk_add_f32 v[126:127], v[126:127], v[224:225]
	v_pk_add_f32 v[128:129], v[128:129], v[226:227]
	global_store_dwordx4 v240, v[66:69], s[0:1]
	s_add_u32 s0, s0, 0x10000
	s_addc_u32 s1, s1, 0
	global_store_dwordx4 v240, v[70:73], s[0:1]
	s_add_u32 s0, s0, 0x10000
	s_addc_u32 s1, s1, 0
	global_store_dwordx4 v240, v[74:77], s[0:1]
	s_add_u32 s0, s0, 0x10000
	s_addc_u32 s1, s1, 0
	global_store_dwordx4 v240, v[78:81], s[0:1]
	s_add_u32 s0, s0, 0x10000
	s_addc_u32 s1, s1, 0
	global_store_dwordx4 v240, v[82:85], s[0:1]
	s_add_u32 s0, s0, 0x10000
	s_addc_u32 s1, s1, 0
	global_store_dwordx4 v240, v[86:89], s[0:1]
	s_add_u32 s0, s0, 0x10000
	s_addc_u32 s1, s1, 0
	global_store_dwordx4 v240, v[90:93], s[0:1]
	s_add_u32 s0, s0, 0x10000
	s_addc_u32 s1, s1, 0
	global_store_dwordx4 v240, v[94:97], s[0:1]
	s_add_u32 s0, s0, 0x10000
	s_addc_u32 s1, s1, 0
	global_store_dwordx4 v240, v[98:101], s[0:1]
	s_add_u32 s0, s0, 0x10000
	s_addc_u32 s1, s1, 0
	global_store_dwordx4 v240, v[102:105], s[0:1]
	s_add_u32 s0, s0, 0x10000
	s_addc_u32 s1, s1, 0
	global_store_dwordx4 v240, v[106:109], s[0:1]
	s_add_u32 s0, s0, 0x10000
	s_addc_u32 s1, s1, 0
	global_store_dwordx4 v240, v[110:113], s[0:1]
	s_add_u32 s0, s0, 0x10000
	s_addc_u32 s1, s1, 0
	global_store_dwordx4 v240, v[114:117], s[0:1]
	s_add_u32 s0, s0, 0x10000
	s_addc_u32 s1, s1, 0
	global_store_dwordx4 v240, v[118:121], s[0:1]
	s_add_u32 s0, s0, 0x10000
	s_addc_u32 s1, s1, 0
	global_store_dwordx4 v240, v[122:125], s[0:1]
	s_add_u32 s0, s0, 0x10000
	s_addc_u32 s1, s1, 0
	global_store_dwordx4 v240, v[126:129], s[0:1]
	s_add_i32 s21, s21, s72
	s_cmpk_lt_i32 s21, 0x200
	s_waitcnt lgkmcnt(0)
	s_barrier
	s_cbranch_scc1 .Lfin3_tile

.Lgu2_loop:
	v_add_u32_e32 v234, s22, v232
	v_add_u32_e32 v236, s28, v232
	v_add_u32_e32 v235, s22, v233
	v_add_u32_e32 v237, s28, v233
	ds_read_b128 v[136:139], v234
	ds_read_b128 v[140:143], v234 offset:2048
	ds_read_b128 v[144:147], v234 offset:4096
	ds_read_b128 v[148:151], v234 offset:6144
	ds_read_b128 v[188:191], v236
	ds_read_b128 v[196:199], v236 offset:2048
	ds_read_b128 v[200:203], v236 offset:4096
	ds_read_b128 v[204:207], v236 offset:6144
	ds_read_b128 v[172:175], v235
	ds_read_b128 v[176:179], v235 offset:2048
	ds_read_b128 v[180:183], v235 offset:4096
	ds_read_b128 v[184:187], v235 offset:6144
	ds_read_b128 v[212:215], v237
	ds_read_b128 v[216:219], v237 offset:2048
	ds_read_b128 v[220:223], v237 offset:4096
	ds_read_b128 v[224:227], v237 offset:6144
	s_add_i32 m0, s51, 0xc000
	s_nop 0
	global_load_lds_dwordx4 v228, s[44:45]
	s_add_i32 m0, s51, 0xc400
	s_nop 0
	global_load_lds_dwordx4 v230, s[44:45]
	s_add_i32 m0, s51, 0xe000
	s_nop 0
	global_load_lds_dwordx4 v229, s[44:45]
	s_add_i32 m0, s51, 0xe400
	s_nop 0
	global_load_lds_dwordx4 v231, s[44:45]
	s_add_i32 m0, s51, 0x10000
	s_nop 0
	global_load_lds_dwordx4 v228, s[46:47]
	s_add_i32 m0, s51, 0x10400
	s_nop 0
	global_load_lds_dwordx4 v230, s[46:47]
	s_waitcnt lgkmcnt(8)
	s_setprio 1
	v_mfma_f32_16x16x32_bf16 v[2:5], v[136:139], v[188:191], v[2:5]
	v_mfma_f32_16x16x32_bf16 v[6:9], v[136:139], v[196:199], v[6:9]
	v_mfma_f32_16x16x32_bf16 v[10:13], v[136:139], v[200:203], v[10:13]
	v_mfma_f32_16x16x32_bf16 v[14:17], v[136:139], v[204:207], v[14:17]
	v_mfma_f32_16x16x32_bf16 v[18:21], v[140:143], v[188:191], v[18:21]
	v_mfma_f32_16x16x32_bf16 v[22:25], v[140:143], v[196:199], v[22:25]
	v_mfma_f32_16x16x32_bf16 v[26:29], v[140:143], v[200:203], v[26:29]
	v_mfma_f32_16x16x32_bf16 v[30:33], v[140:143], v[204:207], v[30:33]
	v_mfma_f32_16x16x32_bf16 v[34:37], v[144:147], v[188:191], v[34:37]
	v_mfma_f32_16x16x32_bf16 v[38:41], v[144:147], v[196:199], v[38:41]
	v_mfma_f32_16x16x32_bf16 v[42:45], v[144:147], v[200:203], v[42:45]
	v_mfma_f32_16x16x32_bf16 v[46:49], v[144:147], v[204:207], v[46:49]
	v_mfma_f32_16x16x32_bf16 v[50:53], v[148:151], v[188:191], v[50:53]
	v_mfma_f32_16x16x32_bf16 v[54:57], v[148:151], v[196:199], v[54:57]
	v_mfma_f32_16x16x32_bf16 v[58:61], v[148:151], v[200:203], v[58:61]
	v_mfma_f32_16x16x32_bf16 v[62:65], v[148:151], v[204:207], v[62:65]
	s_waitcnt lgkmcnt(0)
	v_mfma_f32_16x16x32_bf16 v[2:5], v[172:175], v[212:215], v[2:5]
	v_mfma_f32_16x16x32_bf16 v[6:9], v[172:175], v[216:219], v[6:9]
	v_mfma_f32_16x16x32_bf16 v[10:13], v[172:175], v[220:223], v[10:13]
	v_mfma_f32_16x16x32_bf16 v[14:17], v[172:175], v[224:227], v[14:17]
	v_mfma_f32_16x16x32_bf16 v[18:21], v[176:179], v[212:215], v[18:21]
	v_mfma_f32_16x16x32_bf16 v[22:25], v[176:179], v[216:219], v[22:25]
	v_mfma_f32_16x16x32_bf16 v[26:29], v[176:179], v[220:223], v[26:29]
	v_mfma_f32_16x16x32_bf16 v[30:33], v[176:179], v[224:227], v[30:33]
	v_mfma_f32_16x16x32_bf16 v[34:37], v[180:183], v[212:215], v[34:37]
	v_mfma_f32_16x16x32_bf16 v[38:41], v[180:183], v[216:219], v[38:41]
	v_mfma_f32_16x16x32_bf16 v[42:45], v[180:183], v[220:223], v[42:45]
	v_mfma_f32_16x16x32_bf16 v[46:49], v[180:183], v[224:227], v[46:49]
	v_mfma_f32_16x16x32_bf16 v[50:53], v[184:187], v[212:215], v[50:53]
	v_mfma_f32_16x16x32_bf16 v[54:57], v[184:187], v[216:219], v[54:57]
	v_mfma_f32_16x16x32_bf16 v[58:61], v[184:187], v[220:223], v[58:61]
	v_mfma_f32_16x16x32_bf16 v[62:65], v[184:187], v[224:227], v[62:65]
	s_setprio 0
	s_waitcnt vmcnt(6)
	s_barrier
	v_add_u32_e32 v236, s40, v232
	v_add_u32_e32 v237, s40, v233
	ds_read_b128 v[188:191], v236
	ds_read_b128 v[196:199], v236 offset:2048
	ds_read_b128 v[200:203], v236 offset:4096
	ds_read_b128 v[204:207], v236 offset:6144
	ds_read_b128 v[212:215], v237
	ds_read_b128 v[216:219], v237 offset:2048
	ds_read_b128 v[220:223], v237 offset:4096
	ds_read_b128 v[224:227], v237 offset:6144
	s_mov_b32 m0, s51
	s_nop 0
	global_load_lds_dwordx4 v229, s[46:47]
	s_add_i32 m0, s51, 0x400
	s_nop 0
	global_load_lds_dwordx4 v231, s[46:47]
	s_add_i32 m0, s51, 0x2000
	s_nop 0
	global_load_lds_dwordx4 v228, s[48:49]
	s_add_i32 m0, s51, 0x2400
	s_nop 0
	global_load_lds_dwordx4 v230, s[48:49]
	s_add_i32 m0, s51, 0x4000
	s_nop 0
	global_load_lds_dwordx4 v229, s[48:49]
	s_add_i32 m0, s51, 0x4400
	s_nop 0
	global_load_lds_dwordx4 v231, s[48:49]
	s_waitcnt lgkmcnt(4)
	s_setprio 1
	v_mfma_f32_16x16x32_bf16 v[66:69], v[136:139], v[188:191], v[66:69]
	v_mfma_f32_16x16x32_bf16 v[70:73], v[136:139], v[196:199], v[70:73]
	v_mfma_f32_16x16x32_bf16 v[74:77], v[136:139], v[200:203], v[74:77]
	v_mfma_f32_16x16x32_bf16 v[78:81], v[136:139], v[204:207], v[78:81]
	v_mfma_f32_16x16x32_bf16 v[82:85], v[140:143], v[188:191], v[82:85]
	v_mfma_f32_16x16x32_bf16 v[86:89], v[140:143], v[196:199], v[86:89]
	v_mfma_f32_16x16x32_bf16 v[90:93], v[140:143], v[200:203], v[90:93]
	v_mfma_f32_16x16x32_bf16 v[94:97], v[140:143], v[204:207], v[94:97]
	v_mfma_f32_16x16x32_bf16 v[98:101], v[144:147], v[188:191], v[98:101]
	v_mfma_f32_16x16x32_bf16 v[102:105], v[144:147], v[196:199], v[102:105]
	v_mfma_f32_16x16x32_bf16 v[106:109], v[144:147], v[200:203], v[106:109]
	v_mfma_f32_16x16x32_bf16 v[110:113], v[144:147], v[204:207], v[110:113]
	v_mfma_f32_16x16x32_bf16 v[114:117], v[148:151], v[188:191], v[114:117]
	v_mfma_f32_16x16x32_bf16 v[118:121], v[148:151], v[196:199], v[118:121]
	v_mfma_f32_16x16x32_bf16 v[122:125], v[148:151], v[200:203], v[122:125]
	v_mfma_f32_16x16x32_bf16 v[126:129], v[148:151], v[204:207], v[126:129]
	s_waitcnt lgkmcnt(0)
	v_mfma_f32_16x16x32_bf16 v[66:69], v[172:175], v[212:215], v[66:69]
	v_mfma_f32_16x16x32_bf16 v[70:73], v[172:175], v[216:219], v[70:73]
	v_mfma_f32_16x16x32_bf16 v[74:77], v[172:175], v[220:223], v[74:77]
	v_mfma_f32_16x16x32_bf16 v[78:81], v[172:175], v[224:227], v[78:81]
	v_mfma_f32_16x16x32_bf16 v[82:85], v[176:179], v[212:215], v[82:85]
	v_mfma_f32_16x16x32_bf16 v[86:89], v[176:179], v[216:219], v[86:89]
	v_mfma_f32_16x16x32_bf16 v[90:93], v[176:179], v[220:223], v[90:93]
	v_mfma_f32_16x16x32_bf16 v[94:97], v[176:179], v[224:227], v[94:97]
	v_mfma_f32_16x16x32_bf16 v[98:101], v[180:183], v[212:215], v[98:101]
	v_mfma_f32_16x16x32_bf16 v[102:105], v[180:183], v[216:219], v[102:105]
	v_mfma_f32_16x16x32_bf16 v[106:109], v[180:183], v[220:223], v[106:109]
	v_mfma_f32_16x16x32_bf16 v[110:113], v[180:183], v[224:227], v[110:113]
	v_mfma_f32_16x16x32_bf16 v[114:117], v[184:187], v[212:215], v[114:117]
	v_mfma_f32_16x16x32_bf16 v[118:121], v[184:187], v[216:219], v[118:121]
	v_mfma_f32_16x16x32_bf16 v[122:125], v[184:187], v[220:223], v[122:125]
	v_mfma_f32_16x16x32_bf16 v[126:129], v[184:187], v[224:227], v[126:129]
	s_setprio 0
	v_add_u32_e32 v228, 0x80, v228
	v_add_u32_e32 v229, 0x80, v229
	v_add_u32_e32 v230, 0x80, v230
	v_add_u32_e32 v231, 0x80, v231
	s_waitcnt vmcnt(4)
	s_barrier
	v_add_u32_e32 v234, s23, v232
	v_add_u32_e32 v236, s29, v232
	v_add_u32_e32 v235, s23, v233
	v_add_u32_e32 v237, s29, v233
	ds_read_b128 v[136:139], v234
	ds_read_b128 v[140:143], v234 offset:2048
	ds_read_b128 v[144:147], v234 offset:4096
	ds_read_b128 v[148:151], v234 offset:6144
	ds_read_b128 v[188:191], v236
	ds_read_b128 v[196:199], v236 offset:2048
	ds_read_b128 v[200:203], v236 offset:4096
	ds_read_b128 v[204:207], v236 offset:6144
	ds_read_b128 v[172:175], v235
	ds_read_b128 v[176:179], v235 offset:2048
	ds_read_b128 v[180:183], v235 offset:4096
	ds_read_b128 v[184:187], v235 offset:6144
	ds_read_b128 v[212:215], v237
	ds_read_b128 v[216:219], v237 offset:2048
	ds_read_b128 v[220:223], v237 offset:4096
	ds_read_b128 v[224:227], v237 offset:6144
	s_add_i32 m0, s51, 0x6000
	s_nop 0
	global_load_lds_dwordx4 v228, s[44:45]
	s_add_i32 m0, s51, 0x6400
	s_nop 0
	global_load_lds_dwordx4 v230, s[44:45]
	s_add_i32 m0, s51, 0x8000
	s_nop 0
	global_load_lds_dwordx4 v229, s[44:45]
	s_add_i32 m0, s51, 0x8400
	s_nop 0
	global_load_lds_dwordx4 v231, s[44:45]
	s_add_i32 m0, s51, 0xa000
	s_nop 0
	global_load_lds_dwordx4 v228, s[46:47]
	s_add_i32 m0, s51, 0xa400
	s_nop 0
	global_load_lds_dwordx4 v230, s[46:47]
	s_waitcnt lgkmcnt(8)
	s_setprio 1
	v_mfma_f32_16x16x32_bf16 v[2:5], v[136:139], v[188:191], v[2:5]
	v_mfma_f32_16x16x32_bf16 v[6:9], v[136:139], v[196:199], v[6:9]
	v_mfma_f32_16x16x32_bf16 v[10:13], v[136:139], v[200:203], v[10:13]
	v_mfma_f32_16x16x32_bf16 v[14:17], v[136:139], v[204:207], v[14:17]
	v_mfma_f32_16x16x32_bf16 v[18:21], v[140:143], v[188:191], v[18:21]
	v_mfma_f32_16x16x32_bf16 v[22:25], v[140:143], v[196:199], v[22:25]
	v_mfma_f32_16x16x32_bf16 v[26:29], v[140:143], v[200:203], v[26:29]
	v_mfma_f32_16x16x32_bf16 v[30:33], v[140:143], v[204:207], v[30:33]
	v_mfma_f32_16x16x32_bf16 v[34:37], v[144:147], v[188:191], v[34:37]
	v_mfma_f32_16x16x32_bf16 v[38:41], v[144:147], v[196:199], v[38:41]
	v_mfma_f32_16x16x32_bf16 v[42:45], v[144:147], v[200:203], v[42:45]
	v_mfma_f32_16x16x32_bf16 v[46:49], v[144:147], v[204:207], v[46:49]
	v_mfma_f32_16x16x32_bf16 v[50:53], v[148:151], v[188:191], v[50:53]
	v_mfma_f32_16x16x32_bf16 v[54:57], v[148:151], v[196:199], v[54:57]
	v_mfma_f32_16x16x32_bf16 v[58:61], v[148:151], v[200:203], v[58:61]
	v_mfma_f32_16x16x32_bf16 v[62:65], v[148:151], v[204:207], v[62:65]
	s_waitcnt lgkmcnt(0)
	v_mfma_f32_16x16x32_bf16 v[2:5], v[172:175], v[212:215], v[2:5]
	v_mfma_f32_16x16x32_bf16 v[6:9], v[172:175], v[216:219], v[6:9]
	v_mfma_f32_16x16x32_bf16 v[10:13], v[172:175], v[220:223], v[10:13]
	v_mfma_f32_16x16x32_bf16 v[14:17], v[172:175], v[224:227], v[14:17]
	v_mfma_f32_16x16x32_bf16 v[18:21], v[176:179], v[212:215], v[18:21]
	v_mfma_f32_16x16x32_bf16 v[22:25], v[176:179], v[216:219], v[22:25]
	v_mfma_f32_16x16x32_bf16 v[26:29], v[176:179], v[220:223], v[26:29]
	v_mfma_f32_16x16x32_bf16 v[30:33], v[176:179], v[224:227], v[30:33]
	v_mfma_f32_16x16x32_bf16 v[34:37], v[180:183], v[212:215], v[34:37]
	v_mfma_f32_16x16x32_bf16 v[38:41], v[180:183], v[216:219], v[38:41]
	v_mfma_f32_16x16x32_bf16 v[42:45], v[180:183], v[220:223], v[42:45]
	v_mfma_f32_16x16x32_bf16 v[46:49], v[180:183], v[224:227], v[46:49]
	v_mfma_f32_16x16x32_bf16 v[50:53], v[184:187], v[212:215], v[50:53]
	v_mfma_f32_16x16x32_bf16 v[54:57], v[184:187], v[216:219], v[54:57]
	v_mfma_f32_16x16x32_bf16 v[58:61], v[184:187], v[220:223], v[58:61]
	v_mfma_f32_16x16x32_bf16 v[62:65], v[184:187], v[224:227], v[62:65]
	s_setprio 0
	s_waitcnt vmcnt(6)
	s_barrier
	v_add_u32_e32 v236, s41, v232
	v_add_u32_e32 v237, s41, v233
	ds_read_b128 v[188:191], v236
	ds_read_b128 v[196:199], v236 offset:2048
	ds_read_b128 v[200:203], v236 offset:4096
	ds_read_b128 v[204:207], v236 offset:6144
	ds_read_b128 v[212:215], v237
	ds_read_b128 v[216:219], v237 offset:2048
	ds_read_b128 v[220:223], v237 offset:4096
	ds_read_b128 v[224:227], v237 offset:6144
	s_add_i32 m0, s51, 0xc000
	s_nop 0
	global_load_lds_dwordx4 v229, s[46:47]
	s_add_i32 m0, s51, 0xc400
	s_nop 0
	global_load_lds_dwordx4 v231, s[46:47]
	s_add_i32 m0, s51, 0xe000
	s_nop 0
	global_load_lds_dwordx4 v228, s[48:49]
	s_add_i32 m0, s51, 0xe400
	s_nop 0
	global_load_lds_dwordx4 v230, s[48:49]
	s_add_i32 m0, s51, 0x10000
	s_nop 0
	global_load_lds_dwordx4 v229, s[48:49]
	s_add_i32 m0, s51, 0x10400
	s_nop 0
	global_load_lds_dwordx4 v231, s[48:49]
	s_waitcnt lgkmcnt(4)
	s_setprio 1
	v_mfma_f32_16x16x32_bf16 v[66:69], v[136:139], v[188:191], v[66:69]
	v_mfma_f32_16x16x32_bf16 v[70:73], v[136:139], v[196:199], v[70:73]
	v_mfma_f32_16x16x32_bf16 v[74:77], v[136:139], v[200:203], v[74:77]
	v_mfma_f32_16x16x32_bf16 v[78:81], v[136:139], v[204:207], v[78:81]
	v_mfma_f32_16x16x32_bf16 v[82:85], v[140:143], v[188:191], v[82:85]
	v_mfma_f32_16x16x32_bf16 v[86:89], v[140:143], v[196:199], v[86:89]
	v_mfma_f32_16x16x32_bf16 v[90:93], v[140:143], v[200:203], v[90:93]
	v_mfma_f32_16x16x32_bf16 v[94:97], v[140:143], v[204:207], v[94:97]
	v_mfma_f32_16x16x32_bf16 v[98:101], v[144:147], v[188:191], v[98:101]
	v_mfma_f32_16x16x32_bf16 v[102:105], v[144:147], v[196:199], v[102:105]
	v_mfma_f32_16x16x32_bf16 v[106:109], v[144:147], v[200:203], v[106:109]
	v_mfma_f32_16x16x32_bf16 v[110:113], v[144:147], v[204:207], v[110:113]
	v_mfma_f32_16x16x32_bf16 v[114:117], v[148:151], v[188:191], v[114:117]
	v_mfma_f32_16x16x32_bf16 v[118:121], v[148:151], v[196:199], v[118:121]
	v_mfma_f32_16x16x32_bf16 v[122:125], v[148:151], v[200:203], v[122:125]
	v_mfma_f32_16x16x32_bf16 v[126:129], v[148:151], v[204:207], v[126:129]
	s_waitcnt lgkmcnt(0)
	v_mfma_f32_16x16x32_bf16 v[66:69], v[172:175], v[212:215], v[66:69]
	v_mfma_f32_16x16x32_bf16 v[70:73], v[172:175], v[216:219], v[70:73]
	v_mfma_f32_16x16x32_bf16 v[74:77], v[172:175], v[220:223], v[74:77]
	v_mfma_f32_16x16x32_bf16 v[78:81], v[172:175], v[224:227], v[78:81]
	v_mfma_f32_16x16x32_bf16 v[82:85], v[176:179], v[212:215], v[82:85]
	v_mfma_f32_16x16x32_bf16 v[86:89], v[176:179], v[216:219], v[86:89]
	v_mfma_f32_16x16x32_bf16 v[90:93], v[176:179], v[220:223], v[90:93]
	v_mfma_f32_16x16x32_bf16 v[94:97], v[176:179], v[224:227], v[94:97]
	v_mfma_f32_16x16x32_bf16 v[98:101], v[180:183], v[212:215], v[98:101]
	v_mfma_f32_16x16x32_bf16 v[102:105], v[180:183], v[216:219], v[102:105]
	v_mfma_f32_16x16x32_bf16 v[106:109], v[180:183], v[220:223], v[106:109]
	v_mfma_f32_16x16x32_bf16 v[110:113], v[180:183], v[224:227], v[110:113]
	v_mfma_f32_16x16x32_bf16 v[114:117], v[184:187], v[212:215], v[114:117]
	v_mfma_f32_16x16x32_bf16 v[118:121], v[184:187], v[216:219], v[118:121]
	v_mfma_f32_16x16x32_bf16 v[122:125], v[184:187], v[220:223], v[122:125]
	v_mfma_f32_16x16x32_bf16 v[126:129], v[184:187], v[224:227], v[126:129]
	s_setprio 0
	v_add_u32_e32 v228, 0x80, v228
	v_add_u32_e32 v229, 0x80, v229
	v_add_u32_e32 v230, 0x80, v230
	v_add_u32_e32 v231, 0x80, v231
	s_waitcnt vmcnt(4)
	s_barrier
	v_add_u32_e32 v234, s24, v232
	v_add_u32_e32 v236, s30, v232
	v_add_u32_e32 v235, s24, v233
	v_add_u32_e32 v237, s30, v233
	ds_read_b128 v[136:139], v234
	ds_read_b128 v[140:143], v234 offset:2048
	ds_read_b128 v[144:147], v234 offset:4096
	ds_read_b128 v[148:151], v234 offset:6144
	ds_read_b128 v[188:191], v236
	ds_read_b128 v[196:199], v236 offset:2048
	ds_read_b128 v[200:203], v236 offset:4096
	ds_read_b128 v[204:207], v236 offset:6144
	ds_read_b128 v[172:175], v235
	ds_read_b128 v[176:179], v235 offset:2048
	ds_read_b128 v[180:183], v235 offset:4096
	ds_read_b128 v[184:187], v235 offset:6144
	ds_read_b128 v[212:215], v237
	ds_read_b128 v[216:219], v237 offset:2048
	ds_read_b128 v[220:223], v237 offset:4096
	ds_read_b128 v[224:227], v237 offset:6144
	s_mov_b32 m0, s51
	s_nop 0
	global_load_lds_dwordx4 v228, s[44:45]
	s_add_i32 m0, s51, 0x400
	s_nop 0
	global_load_lds_dwordx4 v230, s[44:45]
	s_add_i32 m0, s51, 0x2000
	s_nop 0
	global_load_lds_dwordx4 v229, s[44:45]
	s_add_i32 m0, s51, 0x2400
	s_nop 0
	global_load_lds_dwordx4 v231, s[44:45]
	s_add_i32 m0, s51, 0x4000
	s_nop 0
	global_load_lds_dwordx4 v228, s[46:47]
	s_add_i32 m0, s51, 0x4400
	s_nop 0
	global_load_lds_dwordx4 v230, s[46:47]
	s_waitcnt lgkmcnt(8)
	s_setprio 1
	v_mfma_f32_16x16x32_bf16 v[2:5], v[136:139], v[188:191], v[2:5]
	v_mfma_f32_16x16x32_bf16 v[6:9], v[136:139], v[196:199], v[6:9]
	v_mfma_f32_16x16x32_bf16 v[10:13], v[136:139], v[200:203], v[10:13]
	v_mfma_f32_16x16x32_bf16 v[14:17], v[136:139], v[204:207], v[14:17]
	v_mfma_f32_16x16x32_bf16 v[18:21], v[140:143], v[188:191], v[18:21]
	v_mfma_f32_16x16x32_bf16 v[22:25], v[140:143], v[196:199], v[22:25]
	v_mfma_f32_16x16x32_bf16 v[26:29], v[140:143], v[200:203], v[26:29]
	v_mfma_f32_16x16x32_bf16 v[30:33], v[140:143], v[204:207], v[30:33]
	v_mfma_f32_16x16x32_bf16 v[34:37], v[144:147], v[188:191], v[34:37]
	v_mfma_f32_16x16x32_bf16 v[38:41], v[144:147], v[196:199], v[38:41]
	v_mfma_f32_16x16x32_bf16 v[42:45], v[144:147], v[200:203], v[42:45]
	v_mfma_f32_16x16x32_bf16 v[46:49], v[144:147], v[204:207], v[46:49]
	v_mfma_f32_16x16x32_bf16 v[50:53], v[148:151], v[188:191], v[50:53]
	v_mfma_f32_16x16x32_bf16 v[54:57], v[148:151], v[196:199], v[54:57]
	v_mfma_f32_16x16x32_bf16 v[58:61], v[148:151], v[200:203], v[58:61]
	v_mfma_f32_16x16x32_bf16 v[62:65], v[148:151], v[204:207], v[62:65]
	s_waitcnt lgkmcnt(0)
	v_mfma_f32_16x16x32_bf16 v[2:5], v[172:175], v[212:215], v[2:5]
	v_mfma_f32_16x16x32_bf16 v[6:9], v[172:175], v[216:219], v[6:9]
	v_mfma_f32_16x16x32_bf16 v[10:13], v[172:175], v[220:223], v[10:13]
	v_mfma_f32_16x16x32_bf16 v[14:17], v[172:175], v[224:227], v[14:17]
	v_mfma_f32_16x16x32_bf16 v[18:21], v[176:179], v[212:215], v[18:21]
	v_mfma_f32_16x16x32_bf16 v[22:25], v[176:179], v[216:219], v[22:25]
	v_mfma_f32_16x16x32_bf16 v[26:29], v[176:179], v[220:223], v[26:29]
	v_mfma_f32_16x16x32_bf16 v[30:33], v[176:179], v[224:227], v[30:33]
	v_mfma_f32_16x16x32_bf16 v[34:37], v[180:183], v[212:215], v[34:37]
	v_mfma_f32_16x16x32_bf16 v[38:41], v[180:183], v[216:219], v[38:41]
	v_mfma_f32_16x16x32_bf16 v[42:45], v[180:183], v[220:223], v[42:45]
	v_mfma_f32_16x16x32_bf16 v[46:49], v[180:183], v[224:227], v[46:49]
	v_mfma_f32_16x16x32_bf16 v[50:53], v[184:187], v[212:215], v[50:53]
	v_mfma_f32_16x16x32_bf16 v[54:57], v[184:187], v[216:219], v[54:57]
	v_mfma_f32_16x16x32_bf16 v[58:61], v[184:187], v[220:223], v[58:61]
	v_mfma_f32_16x16x32_bf16 v[62:65], v[184:187], v[224:227], v[62:65]
	s_setprio 0
	s_waitcnt vmcnt(6)
	s_barrier
	v_add_u32_e32 v236, s42, v232
	v_add_u32_e32 v237, s42, v233
	ds_read_b128 v[188:191], v236
	ds_read_b128 v[196:199], v236 offset:2048
	ds_read_b128 v[200:203], v236 offset:4096
	ds_read_b128 v[204:207], v236 offset:6144
	ds_read_b128 v[212:215], v237
	ds_read_b128 v[216:219], v237 offset:2048
	ds_read_b128 v[220:223], v237 offset:4096
	ds_read_b128 v[224:227], v237 offset:6144
	s_add_i32 m0, s51, 0x6000
	s_nop 0
	global_load_lds_dwordx4 v229, s[46:47]
	s_add_i32 m0, s51, 0x6400
	s_nop 0
	global_load_lds_dwordx4 v231, s[46:47]
	s_add_i32 m0, s51, 0x8000
	s_nop 0
	global_load_lds_dwordx4 v228, s[48:49]
	s_add_i32 m0, s51, 0x8400
	s_nop 0
	global_load_lds_dwordx4 v230, s[48:49]
	s_add_i32 m0, s51, 0xa000
	s_nop 0
	global_load_lds_dwordx4 v229, s[48:49]
	s_add_i32 m0, s51, 0xa400
	s_nop 0
	global_load_lds_dwordx4 v231, s[48:49]
	s_waitcnt lgkmcnt(4)
	s_setprio 1
	v_mfma_f32_16x16x32_bf16 v[66:69], v[136:139], v[188:191], v[66:69]
	v_mfma_f32_16x16x32_bf16 v[70:73], v[136:139], v[196:199], v[70:73]
	v_mfma_f32_16x16x32_bf16 v[74:77], v[136:139], v[200:203], v[74:77]
	v_mfma_f32_16x16x32_bf16 v[78:81], v[136:139], v[204:207], v[78:81]
	v_mfma_f32_16x16x32_bf16 v[82:85], v[140:143], v[188:191], v[82:85]
	v_mfma_f32_16x16x32_bf16 v[86:89], v[140:143], v[196:199], v[86:89]
	v_mfma_f32_16x16x32_bf16 v[90:93], v[140:143], v[200:203], v[90:93]
	v_mfma_f32_16x16x32_bf16 v[94:97], v[140:143], v[204:207], v[94:97]
	v_mfma_f32_16x16x32_bf16 v[98:101], v[144:147], v[188:191], v[98:101]
	v_mfma_f32_16x16x32_bf16 v[102:105], v[144:147], v[196:199], v[102:105]
	v_mfma_f32_16x16x32_bf16 v[106:109], v[144:147], v[200:203], v[106:109]
	v_mfma_f32_16x16x32_bf16 v[110:113], v[144:147], v[204:207], v[110:113]
	v_mfma_f32_16x16x32_bf16 v[114:117], v[148:151], v[188:191], v[114:117]
	v_mfma_f32_16x16x32_bf16 v[118:121], v[148:151], v[196:199], v[118:121]
	v_mfma_f32_16x16x32_bf16 v[122:125], v[148:151], v[200:203], v[122:125]
	v_mfma_f32_16x16x32_bf16 v[126:129], v[148:151], v[204:207], v[126:129]
	s_waitcnt lgkmcnt(0)
	v_mfma_f32_16x16x32_bf16 v[66:69], v[172:175], v[212:215], v[66:69]
	v_mfma_f32_16x16x32_bf16 v[70:73], v[172:175], v[216:219], v[70:73]
	v_mfma_f32_16x16x32_bf16 v[74:77], v[172:175], v[220:223], v[74:77]
	v_mfma_f32_16x16x32_bf16 v[78:81], v[172:175], v[224:227], v[78:81]
	v_mfma_f32_16x16x32_bf16 v[82:85], v[176:179], v[212:215], v[82:85]
	v_mfma_f32_16x16x32_bf16 v[86:89], v[176:179], v[216:219], v[86:89]
	v_mfma_f32_16x16x32_bf16 v[90:93], v[176:179], v[220:223], v[90:93]
	v_mfma_f32_16x16x32_bf16 v[94:97], v[176:179], v[224:227], v[94:97]
	v_mfma_f32_16x16x32_bf16 v[98:101], v[180:183], v[212:215], v[98:101]
	v_mfma_f32_16x16x32_bf16 v[102:105], v[180:183], v[216:219], v[102:105]
	v_mfma_f32_16x16x32_bf16 v[106:109], v[180:183], v[220:223], v[106:109]
	v_mfma_f32_16x16x32_bf16 v[110:113], v[180:183], v[224:227], v[110:113]
	v_mfma_f32_16x16x32_bf16 v[114:117], v[184:187], v[212:215], v[114:117]
	v_mfma_f32_16x16x32_bf16 v[118:121], v[184:187], v[216:219], v[118:121]
	v_mfma_f32_16x16x32_bf16 v[122:125], v[184:187], v[220:223], v[122:125]
	v_mfma_f32_16x16x32_bf16 v[126:129], v[184:187], v[224:227], v[126:129]
	s_setprio 0
	v_add_u32_e32 v228, 0x80, v228
	v_add_u32_e32 v229, 0x80, v229
	v_add_u32_e32 v230, 0x80, v230
	v_add_u32_e32 v231, 0x80, v231
	s_waitcnt vmcnt(4)
	s_barrier
	s_add_i32 s52, s52, 1
	s_cmp_lt_u32 s52, 10
	s_cbranch_scc1 .Lgu2_loop
	v_add_u32_e32 v234, s22, v232
	v_add_u32_e32 v236, s28, v232
	v_add_u32_e32 v235, s22, v233
	v_add_u32_e32 v237, s28, v233
	ds_read_b128 v[136:139], v234
	ds_read_b128 v[140:143], v234 offset:2048
	ds_read_b128 v[144:147], v234 offset:4096
	ds_read_b128 v[148:151], v234 offset:6144
	ds_read_b128 v[188:191], v236
	ds_read_b128 v[196:199], v236 offset:2048
	ds_read_b128 v[200:203], v236 offset:4096
	ds_read_b128 v[204:207], v236 offset:6144
	ds_read_b128 v[172:175], v235
	ds_read_b128 v[176:179], v235 offset:2048
	ds_read_b128 v[180:183], v235 offset:4096
	ds_read_b128 v[184:187], v235 offset:6144
	ds_read_b128 v[212:215], v237
	ds_read_b128 v[216:219], v237 offset:2048
	ds_read_b128 v[220:223], v237 offset:4096
	ds_read_b128 v[224:227], v237 offset:6144
	s_add_i32 m0, s51, 0xc000
	s_nop 0
	global_load_lds_dwordx4 v228, s[44:45]
	s_add_i32 m0, s51, 0xc400
	s_nop 0
	global_load_lds_dwordx4 v230, s[44:45]
	s_add_i32 m0, s51, 0xe000
	s_nop 0
	global_load_lds_dwordx4 v229, s[44:45]
	s_add_i32 m0, s51, 0xe400
	s_nop 0
	global_load_lds_dwordx4 v231, s[44:45]
	s_add_i32 m0, s51, 0x10000
	s_nop 0
	global_load_lds_dwordx4 v228, s[46:47]
	s_add_i32 m0, s51, 0x10400
	s_nop 0
	global_load_lds_dwordx4 v230, s[46:47]
	s_waitcnt lgkmcnt(8)
	s_setprio 1
	v_mfma_f32_16x16x32_bf16 v[2:5], v[136:139], v[188:191], v[2:5]
	v_mfma_f32_16x16x32_bf16 v[6:9], v[136:139], v[196:199], v[6:9]
	v_mfma_f32_16x16x32_bf16 v[10:13], v[136:139], v[200:203], v[10:13]
	v_mfma_f32_16x16x32_bf16 v[14:17], v[136:139], v[204:207], v[14:17]
	v_mfma_f32_16x16x32_bf16 v[18:21], v[140:143], v[188:191], v[18:21]
	v_mfma_f32_16x16x32_bf16 v[22:25], v[140:143], v[196:199], v[22:25]
	v_mfma_f32_16x16x32_bf16 v[26:29], v[140:143], v[200:203], v[26:29]
	v_mfma_f32_16x16x32_bf16 v[30:33], v[140:143], v[204:207], v[30:33]
	v_mfma_f32_16x16x32_bf16 v[34:37], v[144:147], v[188:191], v[34:37]
	v_mfma_f32_16x16x32_bf16 v[38:41], v[144:147], v[196:199], v[38:41]
	v_mfma_f32_16x16x32_bf16 v[42:45], v[144:147], v[200:203], v[42:45]
	v_mfma_f32_16x16x32_bf16 v[46:49], v[144:147], v[204:207], v[46:49]
	v_mfma_f32_16x16x32_bf16 v[50:53], v[148:151], v[188:191], v[50:53]
	v_mfma_f32_16x16x32_bf16 v[54:57], v[148:151], v[196:199], v[54:57]
	v_mfma_f32_16x16x32_bf16 v[58:61], v[148:151], v[200:203], v[58:61]
	v_mfma_f32_16x16x32_bf16 v[62:65], v[148:151], v[204:207], v[62:65]
	s_waitcnt lgkmcnt(0)
	v_mfma_f32_16x16x32_bf16 v[2:5], v[172:175], v[212:215], v[2:5]
	v_mfma_f32_16x16x32_bf16 v[6:9], v[172:175], v[216:219], v[6:9]
	v_mfma_f32_16x16x32_bf16 v[10:13], v[172:175], v[220:223], v[10:13]
	v_mfma_f32_16x16x32_bf16 v[14:17], v[172:175], v[224:227], v[14:17]
	v_mfma_f32_16x16x32_bf16 v[18:21], v[176:179], v[212:215], v[18:21]
	v_mfma_f32_16x16x32_bf16 v[22:25], v[176:179], v[216:219], v[22:25]
	v_mfma_f32_16x16x32_bf16 v[26:29], v[176:179], v[220:223], v[26:29]
	v_mfma_f32_16x16x32_bf16 v[30:33], v[176:179], v[224:227], v[30:33]
	v_mfma_f32_16x16x32_bf16 v[34:37], v[180:183], v[212:215], v[34:37]
	v_mfma_f32_16x16x32_bf16 v[38:41], v[180:183], v[216:219], v[38:41]
	v_mfma_f32_16x16x32_bf16 v[42:45], v[180:183], v[220:223], v[42:45]
	v_mfma_f32_16x16x32_bf16 v[46:49], v[180:183], v[224:227], v[46:49]
	v_mfma_f32_16x16x32_bf16 v[50:53], v[184:187], v[212:215], v[50:53]
	v_mfma_f32_16x16x32_bf16 v[54:57], v[184:187], v[216:219], v[54:57]
	v_mfma_f32_16x16x32_bf16 v[58:61], v[184:187], v[220:223], v[58:61]
	v_mfma_f32_16x16x32_bf16 v[62:65], v[184:187], v[224:227], v[62:65]
	s_setprio 0
	s_waitcnt vmcnt(6)
	s_barrier
	v_add_u32_e32 v236, s40, v232
	v_add_u32_e32 v237, s40, v233
	ds_read_b128 v[188:191], v236
	ds_read_b128 v[196:199], v236 offset:2048
	ds_read_b128 v[200:203], v236 offset:4096
	ds_read_b128 v[204:207], v236 offset:6144
	ds_read_b128 v[212:215], v237
	ds_read_b128 v[216:219], v237 offset:2048
	ds_read_b128 v[220:223], v237 offset:4096
	ds_read_b128 v[224:227], v237 offset:6144
	s_mov_b32 m0, s51
	s_nop 0
	global_load_lds_dwordx4 v229, s[46:47]
	s_add_i32 m0, s51, 0x400
	s_nop 0
	global_load_lds_dwordx4 v231, s[46:47]
	s_add_i32 m0, s51, 0x2000
	s_nop 0
	global_load_lds_dwordx4 v228, s[48:49]
	s_add_i32 m0, s51, 0x2400
	s_nop 0
	global_load_lds_dwordx4 v230, s[48:49]
	s_add_i32 m0, s51, 0x4000
	s_nop 0
	global_load_lds_dwordx4 v229, s[48:49]
	s_add_i32 m0, s51, 0x4400
	s_nop 0
	global_load_lds_dwordx4 v231, s[48:49]
	s_waitcnt lgkmcnt(4)
	s_setprio 1
	v_mfma_f32_16x16x32_bf16 v[66:69], v[136:139], v[188:191], v[66:69]
	v_mfma_f32_16x16x32_bf16 v[70:73], v[136:139], v[196:199], v[70:73]
	v_mfma_f32_16x16x32_bf16 v[74:77], v[136:139], v[200:203], v[74:77]
	v_mfma_f32_16x16x32_bf16 v[78:81], v[136:139], v[204:207], v[78:81]
	v_mfma_f32_16x16x32_bf16 v[82:85], v[140:143], v[188:191], v[82:85]
	v_mfma_f32_16x16x32_bf16 v[86:89], v[140:143], v[196:199], v[86:89]
	v_mfma_f32_16x16x32_bf16 v[90:93], v[140:143], v[200:203], v[90:93]
	v_mfma_f32_16x16x32_bf16 v[94:97], v[140:143], v[204:207], v[94:97]
	v_mfma_f32_16x16x32_bf16 v[98:101], v[144:147], v[188:191], v[98:101]
	v_mfma_f32_16x16x32_bf16 v[102:105], v[144:147], v[196:199], v[102:105]
	v_mfma_f32_16x16x32_bf16 v[106:109], v[144:147], v[200:203], v[106:109]
	v_mfma_f32_16x16x32_bf16 v[110:113], v[144:147], v[204:207], v[110:113]
	v_mfma_f32_16x16x32_bf16 v[114:117], v[148:151], v[188:191], v[114:117]
	v_mfma_f32_16x16x32_bf16 v[118:121], v[148:151], v[196:199], v[118:121]
	v_mfma_f32_16x16x32_bf16 v[122:125], v[148:151], v[200:203], v[122:125]
	v_mfma_f32_16x16x32_bf16 v[126:129], v[148:151], v[204:207], v[126:129]
	s_waitcnt lgkmcnt(0)
	v_mfma_f32_16x16x32_bf16 v[66:69], v[172:175], v[212:215], v[66:69]
	v_mfma_f32_16x16x32_bf16 v[70:73], v[172:175], v[216:219], v[70:73]
	v_mfma_f32_16x16x32_bf16 v[74:77], v[172:175], v[220:223], v[74:77]
	v_mfma_f32_16x16x32_bf16 v[78:81], v[172:175], v[224:227], v[78:81]
	v_mfma_f32_16x16x32_bf16 v[82:85], v[176:179], v[212:215], v[82:85]
	v_mfma_f32_16x16x32_bf16 v[86:89], v[176:179], v[216:219], v[86:89]
	v_mfma_f32_16x16x32_bf16 v[90:93], v[176:179], v[220:223], v[90:93]
	v_mfma_f32_16x16x32_bf16 v[94:97], v[176:179], v[224:227], v[94:97]
	v_mfma_f32_16x16x32_bf16 v[98:101], v[180:183], v[212:215], v[98:101]
	v_mfma_f32_16x16x32_bf16 v[102:105], v[180:183], v[216:219], v[102:105]
	v_mfma_f32_16x16x32_bf16 v[106:109], v[180:183], v[220:223], v[106:109]
	v_mfma_f32_16x16x32_bf16 v[110:113], v[180:183], v[224:227], v[110:113]
	v_mfma_f32_16x16x32_bf16 v[114:117], v[184:187], v[212:215], v[114:117]
	v_mfma_f32_16x16x32_bf16 v[118:121], v[184:187], v[216:219], v[118:121]
	v_mfma_f32_16x16x32_bf16 v[122:125], v[184:187], v[220:223], v[122:125]
	v_mfma_f32_16x16x32_bf16 v[126:129], v[184:187], v[224:227], v[126:129]
	s_setprio 0
	v_add_u32_e32 v228, 0x80, v228
	v_add_u32_e32 v229, 0x80, v229
	v_add_u32_e32 v230, 0x80, v230
	v_add_u32_e32 v231, 0x80, v231
	s_waitcnt vmcnt(4)
	s_barrier
	v_add_u32_e32 v234, s23, v232
	v_add_u32_e32 v236, s29, v232
	v_add_u32_e32 v235, s23, v233
	v_add_u32_e32 v237, s29, v233
	ds_read_b128 v[136:139], v234
	ds_read_b128 v[140:143], v234 offset:2048
	ds_read_b128 v[144:147], v234 offset:4096
	ds_read_b128 v[148:151], v234 offset:6144
	ds_read_b128 v[188:191], v236
	ds_read_b128 v[196:199], v236 offset:2048
	ds_read_b128 v[200:203], v236 offset:4096
	ds_read_b128 v[204:207], v236 offset:6144
	ds_read_b128 v[172:175], v235
	ds_read_b128 v[176:179], v235 offset:2048
	ds_read_b128 v[180:183], v235 offset:4096
	ds_read_b128 v[184:187], v235 offset:6144
	ds_read_b128 v[212:215], v237
	ds_read_b128 v[216:219], v237 offset:2048
	ds_read_b128 v[220:223], v237 offset:4096
	ds_read_b128 v[224:227], v237 offset:6144
	s_waitcnt lgkmcnt(8)
	s_setprio 1
	v_mfma_f32_16x16x32_bf16 v[2:5], v[136:139], v[188:191], v[2:5]
	v_mfma_f32_16x16x32_bf16 v[6:9], v[136:139], v[196:199], v[6:9]
	v_mfma_f32_16x16x32_bf16 v[10:13], v[136:139], v[200:203], v[10:13]
	v_mfma_f32_16x16x32_bf16 v[14:17], v[136:139], v[204:207], v[14:17]
	v_mfma_f32_16x16x32_bf16 v[18:21], v[140:143], v[188:191], v[18:21]
	v_mfma_f32_16x16x32_bf16 v[22:25], v[140:143], v[196:199], v[22:25]
	v_mfma_f32_16x16x32_bf16 v[26:29], v[140:143], v[200:203], v[26:29]
	v_mfma_f32_16x16x32_bf16 v[30:33], v[140:143], v[204:207], v[30:33]
	v_mfma_f32_16x16x32_bf16 v[34:37], v[144:147], v[188:191], v[34:37]
	v_mfma_f32_16x16x32_bf16 v[38:41], v[144:147], v[196:199], v[38:41]
	v_mfma_f32_16x16x32_bf16 v[42:45], v[144:147], v[200:203], v[42:45]
	v_mfma_f32_16x16x32_bf16 v[46:49], v[144:147], v[204:207], v[46:49]
	v_mfma_f32_16x16x32_bf16 v[50:53], v[148:151], v[188:191], v[50:53]
	v_mfma_f32_16x16x32_bf16 v[54:57], v[148:151], v[196:199], v[54:57]
	v_mfma_f32_16x16x32_bf16 v[58:61], v[148:151], v[200:203], v[58:61]
	v_mfma_f32_16x16x32_bf16 v[62:65], v[148:151], v[204:207], v[62:65]
	s_waitcnt lgkmcnt(0)
	v_mfma_f32_16x16x32_bf16 v[2:5], v[172:175], v[212:215], v[2:5]
	v_mfma_f32_16x16x32_bf16 v[6:9], v[172:175], v[216:219], v[6:9]
	v_mfma_f32_16x16x32_bf16 v[10:13], v[172:175], v[220:223], v[10:13]
	v_mfma_f32_16x16x32_bf16 v[14:17], v[172:175], v[224:227], v[14:17]
	v_mfma_f32_16x16x32_bf16 v[18:21], v[176:179], v[212:215], v[18:21]
	v_mfma_f32_16x16x32_bf16 v[22:25], v[176:179], v[216:219], v[22:25]
	v_mfma_f32_16x16x32_bf16 v[26:29], v[176:179], v[220:223], v[26:29]
	v_mfma_f32_16x16x32_bf16 v[30:33], v[176:179], v[224:227], v[30:33]
	v_mfma_f32_16x16x32_bf16 v[34:37], v[180:183], v[212:215], v[34:37]
	v_mfma_f32_16x16x32_bf16 v[38:41], v[180:183], v[216:219], v[38:41]
	v_mfma_f32_16x16x32_bf16 v[42:45], v[180:183], v[220:223], v[42:45]
	v_mfma_f32_16x16x32_bf16 v[46:49], v[180:183], v[224:227], v[46:49]
	v_mfma_f32_16x16x32_bf16 v[50:53], v[184:187], v[212:215], v[50:53]
	v_mfma_f32_16x16x32_bf16 v[54:57], v[184:187], v[216:219], v[54:57]
	v_mfma_f32_16x16x32_bf16 v[58:61], v[184:187], v[220:223], v[58:61]
	v_mfma_f32_16x16x32_bf16 v[62:65], v[184:187], v[224:227], v[62:65]
	s_setprio 0
	s_waitcnt vmcnt(0)
	s_barrier
	v_add_u32_e32 v236, s41, v232
	v_add_u32_e32 v237, s41, v233
	ds_read_b128 v[188:191], v236
	ds_read_b128 v[196:199], v236 offset:2048
	ds_read_b128 v[200:203], v236 offset:4096
	ds_read_b128 v[204:207], v236 offset:6144
	ds_read_b128 v[212:215], v237
	ds_read_b128 v[216:219], v237 offset:2048
	ds_read_b128 v[220:223], v237 offset:4096
	ds_read_b128 v[224:227], v237 offset:6144
	s_waitcnt lgkmcnt(4)
	s_setprio 1
	v_mfma_f32_16x16x32_bf16 v[66:69], v[136:139], v[188:191], v[66:69]
	v_mfma_f32_16x16x32_bf16 v[70:73], v[136:139], v[196:199], v[70:73]
	v_mfma_f32_16x16x32_bf16 v[74:77], v[136:139], v[200:203], v[74:77]
	v_mfma_f32_16x16x32_bf16 v[78:81], v[136:139], v[204:207], v[78:81]
	v_mfma_f32_16x16x32_bf16 v[82:85], v[140:143], v[188:191], v[82:85]
	v_mfma_f32_16x16x32_bf16 v[86:89], v[140:143], v[196:199], v[86:89]
	v_mfma_f32_16x16x32_bf16 v[90:93], v[140:143], v[200:203], v[90:93]
	v_mfma_f32_16x16x32_bf16 v[94:97], v[140:143], v[204:207], v[94:97]
	v_mfma_f32_16x16x32_bf16 v[98:101], v[144:147], v[188:191], v[98:101]
	v_mfma_f32_16x16x32_bf16 v[102:105], v[144:147], v[196:199], v[102:105]
	v_mfma_f32_16x16x32_bf16 v[106:109], v[144:147], v[200:203], v[106:109]
	v_mfma_f32_16x16x32_bf16 v[110:113], v[144:147], v[204:207], v[110:113]
	v_mfma_f32_16x16x32_bf16 v[114:117], v[148:151], v[188:191], v[114:117]
	v_mfma_f32_16x16x32_bf16 v[118:121], v[148:151], v[196:199], v[118:121]
	v_mfma_f32_16x16x32_bf16 v[122:125], v[148:151], v[200:203], v[122:125]
	v_mfma_f32_16x16x32_bf16 v[126:129], v[148:151], v[204:207], v[126:129]
	s_waitcnt lgkmcnt(0)
	v_mfma_f32_16x16x32_bf16 v[66:69], v[172:175], v[212:215], v[66:69]
	v_mfma_f32_16x16x32_bf16 v[70:73], v[172:175], v[216:219], v[70:73]
	v_mfma_f32_16x16x32_bf16 v[74:77], v[172:175], v[220:223], v[74:77]
	v_mfma_f32_16x16x32_bf16 v[78:81], v[172:175], v[224:227], v[78:81]
	v_mfma_f32_16x16x32_bf16 v[82:85], v[176:179], v[212:215], v[82:85]
	v_mfma_f32_16x16x32_bf16 v[86:89], v[176:179], v[216:219], v[86:89]
	v_mfma_f32_16x16x32_bf16 v[90:93], v[176:179], v[220:223], v[90:93]
	v_mfma_f32_16x16x32_bf16 v[94:97], v[176:179], v[224:227], v[94:97]
	v_mfma_f32_16x16x32_bf16 v[98:101], v[180:183], v[212:215], v[98:101]
	v_mfma_f32_16x16x32_bf16 v[102:105], v[180:183], v[216:219], v[102:105]
	v_mfma_f32_16x16x32_bf16 v[106:109], v[180:183], v[220:223], v[106:109]
	v_mfma_f32_16x16x32_bf16 v[110:113], v[180:183], v[224:227], v[110:113]
	v_mfma_f32_16x16x32_bf16 v[114:117], v[184:187], v[212:215], v[114:117]
	v_mfma_f32_16x16x32_bf16 v[118:121], v[184:187], v[216:219], v[118:121]
	v_mfma_f32_16x16x32_bf16 v[122:125], v[184:187], v[220:223], v[122:125]
	v_mfma_f32_16x16x32_bf16 v[126:129], v[184:187], v[224:227], v[126:129]
	s_setprio 0
	s_nop 7
	s_barrier
	s_load_dwordx2 s[58:59], s[12:13], 0x180
	v_mov_b32_e32 v241, 0x3a000000
	v_mov_b32_e32 v242, 0x358637bd
	v_fma_f32 v152, v152, v241, v242
	v_fma_f32 v153, v153, v241, v242
	v_fma_f32 v154, v154, v241, v242
	v_fma_f32 v155, v155, v241, v242
	v_fma_f32 v244, v244, v241, v242
	v_fma_f32 v245, v245, v241, v242
	v_fma_f32 v246, v246, v241, v242
	v_fma_f32 v247, v247, v241, v242
	v_fma_f32 v248, v248, v241, v242
	v_fma_f32 v249, v249, v241, v242
	v_fma_f32 v250, v250, v241, v242
	v_fma_f32 v251, v251, v241, v242
	v_fma_f32 v252, v252, v241, v242
	v_fma_f32 v253, v253, v241, v242
	v_fma_f32 v254, v254, v241, v242
	v_fma_f32 v255, v255, v241, v242
	v_rsq_f32_e32 v152, v152
	v_rsq_f32_e32 v153, v153
	v_rsq_f32_e32 v154, v154
	v_rsq_f32_e32 v155, v155
	v_rsq_f32_e32 v244, v244
	v_rsq_f32_e32 v245, v245
	v_rsq_f32_e32 v246, v246
	v_rsq_f32_e32 v247, v247
	v_rsq_f32_e32 v248, v248
	v_rsq_f32_e32 v249, v249
	v_rsq_f32_e32 v250, v250
	v_rsq_f32_e32 v251, v251
	v_rsq_f32_e32 v252, v252
	v_rsq_f32_e32 v253, v253
	v_rsq_f32_e32 v254, v254
	v_rsq_f32_e32 v255, v255
	v_and_b32_e32 v241, 63, v131
	v_lshrrev_b32_e32 v242, 4, v241
	v_and_b32_e32 v241, 15, v241
	s_lshr_b32 s56, s50, 1
	s_and_b32 s57, s50, 1
	s_mul_i32 s56, s56, 64*144
	s_lshl_b32 s57, s57, 6
	s_add_i32 s56, s56, s57
	s_add_i32 s56, s56, 16
	v_mul_u32_u24_e32 v242, 4*144, v242
	v_lshl_add_u32 v242, v241, 1, v242
	v_add_u32_e32 v188, s56, v242
	v_lshrrev_b32_e32 v241, 3, v131
	v_and_b32_e32 v242, 7, v131
	v_lshlrev_b32_e32 v242, 4, v242
	v_mul_u32_u24_e32 v189, 144, v241
	v_add3_u32 v189, v189, v242, 16
	s_movk_i32 s56, 0x2c80
	v_mad_u32_u24 v243, v241, s56, v242
	s_mul_i32 s56, s53, 0x2c80
	s_add_i32 s56, s56, s54
	s_waitcnt lgkmcnt(0)
	s_add_u32 s58, s58, s56
	s_addc_u32 s59, s59, 0
	v_mul_f32_e32 v2, v2, v152
	v_mul_f32_e32 v6, v6, v152
	v_mul_f32_e32 v10, v10, v152
	v_mul_f32_e32 v14, v14, v152
	v_mul_f32_e32 v136, 0xbfb8aa3b, v2
	v_mul_f32_e32 v137, 0xbfb8aa3b, v6
	v_exp_f32_e32 v136, v136
	v_exp_f32_e32 v137, v137
	v_mul_f32_e32 v10, v10, v2
	v_mul_f32_e32 v14, v14, v6
	v_add_f32_e32 v136, 1.0, v136
	v_add_f32_e32 v137, 1.0, v137
	v_rcp_f32_e32 v136, v136
	v_rcp_f32_e32 v137, v137
	s_nop 0
	v_mul_f32_e32 v10, v10, v136
	v_mul_f32_e32 v14, v14, v137
	v_cvt_pk_bf16_f32 v10, v10, v14
	ds_write_b16 v188, v10
	ds_write_b16_d16_hi v188, v10 offset:32
	v_mul_f32_e32 v3, v3, v153
	v_mul_f32_e32 v7, v7, v153
	v_mul_f32_e32 v11, v11, v153
	v_mul_f32_e32 v15, v15, v153
	v_mul_f32_e32 v136, 0xbfb8aa3b, v3
	v_mul_f32_e32 v137, 0xbfb8aa3b, v7
	v_exp_f32_e32 v136, v136
	v_exp_f32_e32 v137, v137
	v_mul_f32_e32 v11, v11, v3
	v_mul_f32_e32 v15, v15, v7
	v_add_f32_e32 v136, 1.0, v136
	v_add_f32_e32 v137, 1.0, v137
	v_rcp_f32_e32 v136, v136
	v_rcp_f32_e32 v137, v137
	s_nop 0
	v_mul_f32_e32 v11, v11, v136
	v_mul_f32_e32 v15, v15, v137
	v_cvt_pk_bf16_f32 v11, v11, v15
	ds_write_b16 v188, v11 offset:144
	ds_write_b16_d16_hi v188, v11 offset:176
	v_mul_f32_e32 v4, v4, v154
	v_mul_f32_e32 v8, v8, v154
	v_mul_f32_e32 v12, v12, v154
	v_mul_f32_e32 v16, v16, v154
	v_mul_f32_e32 v136, 0xbfb8aa3b, v4
	v_mul_f32_e32 v137, 0xbfb8aa3b, v8
	v_exp_f32_e32 v136, v136
	v_exp_f32_e32 v137, v137
	v_mul_f32_e32 v12, v12, v4
	v_mul_f32_e32 v16, v16, v8
	v_add_f32_e32 v136, 1.0, v136
	v_add_f32_e32 v137, 1.0, v137
	v_rcp_f32_e32 v136, v136
	v_rcp_f32_e32 v137, v137
	s_nop 0
	v_mul_f32_e32 v12, v12, v136
	v_mul_f32_e32 v16, v16, v137
	v_cvt_pk_bf16_f32 v12, v12, v16
	ds_write_b16 v188, v12 offset:288
	ds_write_b16_d16_hi v188, v12 offset:320
	v_mul_f32_e32 v5, v5, v155
	v_mul_f32_e32 v9, v9, v155
	v_mul_f32_e32 v13, v13, v155
	v_mul_f32_e32 v17, v17, v155
	v_mul_f32_e32 v136, 0xbfb8aa3b, v5
	v_mul_f32_e32 v137, 0xbfb8aa3b, v9
	v_exp_f32_e32 v136, v136
	v_exp_f32_e32 v137, v137
	v_mul_f32_e32 v13, v13, v5
	v_mul_f32_e32 v17, v17, v9
	v_add_f32_e32 v136, 1.0, v136
	v_add_f32_e32 v137, 1.0, v137
	v_rcp_f32_e32 v136, v136
	v_rcp_f32_e32 v137, v137
	s_nop 0
	v_mul_f32_e32 v13, v13, v136
	v_mul_f32_e32 v17, v17, v137
	v_cvt_pk_bf16_f32 v13, v13, v17
	ds_write_b16 v188, v13 offset:432
	ds_write_b16_d16_hi v188, v13 offset:464
	v_mul_f32_e32 v18, v18, v244
	v_mul_f32_e32 v22, v22, v244
	v_mul_f32_e32 v26, v26, v244
	v_mul_f32_e32 v30, v30, v244
	v_mul_f32_e32 v136, 0xbfb8aa3b, v18
	v_mul_f32_e32 v137, 0xbfb8aa3b, v22
	v_exp_f32_e32 v136, v136
	v_exp_f32_e32 v137, v137
	v_mul_f32_e32 v26, v26, v18
	v_mul_f32_e32 v30, v30, v22
	v_add_f32_e32 v136, 1.0, v136
	v_add_f32_e32 v137, 1.0, v137
	v_rcp_f32_e32 v136, v136
	v_rcp_f32_e32 v137, v137
	s_nop 0
	v_mul_f32_e32 v26, v26, v136
	v_mul_f32_e32 v30, v30, v137
	v_cvt_pk_bf16_f32 v26, v26, v30
	ds_write_b16 v188, v26 offset:2304
	ds_write_b16_d16_hi v188, v26 offset:2336
	v_mul_f32_e32 v19, v19, v245
	v_mul_f32_e32 v23, v23, v245
	v_mul_f32_e32 v27, v27, v245
	v_mul_f32_e32 v31, v31, v245
	v_mul_f32_e32 v136, 0xbfb8aa3b, v19
	v_mul_f32_e32 v137, 0xbfb8aa3b, v23
	v_exp_f32_e32 v136, v136
	v_exp_f32_e32 v137, v137
	v_mul_f32_e32 v27, v27, v19
	v_mul_f32_e32 v31, v31, v23
	v_add_f32_e32 v136, 1.0, v136
	v_add_f32_e32 v137, 1.0, v137
	v_rcp_f32_e32 v136, v136
	v_rcp_f32_e32 v137, v137
	s_nop 0
	v_mul_f32_e32 v27, v27, v136
	v_mul_f32_e32 v31, v31, v137
	v_cvt_pk_bf16_f32 v27, v27, v31
	ds_write_b16 v188, v27 offset:2448
	ds_write_b16_d16_hi v188, v27 offset:2480
	v_mul_f32_e32 v20, v20, v246
	v_mul_f32_e32 v24, v24, v246
	v_mul_f32_e32 v28, v28, v246
	v_mul_f32_e32 v32, v32, v246
	v_mul_f32_e32 v136, 0xbfb8aa3b, v20
	v_mul_f32_e32 v137, 0xbfb8aa3b, v24
	v_exp_f32_e32 v136, v136
	v_exp_f32_e32 v137, v137
	v_mul_f32_e32 v28, v28, v20
	v_mul_f32_e32 v32, v32, v24
	v_add_f32_e32 v136, 1.0, v136
	v_add_f32_e32 v137, 1.0, v137
	v_rcp_f32_e32 v136, v136
	v_rcp_f32_e32 v137, v137
	s_nop 0
	v_mul_f32_e32 v28, v28, v136
	v_mul_f32_e32 v32, v32, v137
	v_cvt_pk_bf16_f32 v28, v28, v32
	ds_write_b16 v188, v28 offset:2592
	ds_write_b16_d16_hi v188, v28 offset:2624
	v_mul_f32_e32 v21, v21, v247
	v_mul_f32_e32 v25, v25, v247
	v_mul_f32_e32 v29, v29, v247
	v_mul_f32_e32 v33, v33, v247
	v_mul_f32_e32 v136, 0xbfb8aa3b, v21
	v_mul_f32_e32 v137, 0xbfb8aa3b, v25
	v_exp_f32_e32 v136, v136
	v_exp_f32_e32 v137, v137
	v_mul_f32_e32 v29, v29, v21
	v_mul_f32_e32 v33, v33, v25
	v_add_f32_e32 v136, 1.0, v136
	v_add_f32_e32 v137, 1.0, v137
	v_rcp_f32_e32 v136, v136
	v_rcp_f32_e32 v137, v137
	s_nop 0
	v_mul_f32_e32 v29, v29, v136
	v_mul_f32_e32 v33, v33, v137
	v_cvt_pk_bf16_f32 v29, v29, v33
	ds_write_b16 v188, v29 offset:2736
	ds_write_b16_d16_hi v188, v29 offset:2768
	v_mul_f32_e32 v34, v34, v248
	v_mul_f32_e32 v38, v38, v248
	v_mul_f32_e32 v42, v42, v248
	v_mul_f32_e32 v46, v46, v248
	v_mul_f32_e32 v136, 0xbfb8aa3b, v34
	v_mul_f32_e32 v137, 0xbfb8aa3b, v38
	v_exp_f32_e32 v136, v136
	v_exp_f32_e32 v137, v137
	v_mul_f32_e32 v42, v42, v34
	v_mul_f32_e32 v46, v46, v38
	v_add_f32_e32 v136, 1.0, v136
	v_add_f32_e32 v137, 1.0, v137
	v_rcp_f32_e32 v136, v136
	v_rcp_f32_e32 v137, v137
	s_nop 0
	v_mul_f32_e32 v42, v42, v136
	v_mul_f32_e32 v46, v46, v137
	v_cvt_pk_bf16_f32 v42, v42, v46
	ds_write_b16 v188, v42 offset:4608
	ds_write_b16_d16_hi v188, v42 offset:4640
	v_mul_f32_e32 v35, v35, v249
	v_mul_f32_e32 v39, v39, v249
	v_mul_f32_e32 v43, v43, v249
	v_mul_f32_e32 v47, v47, v249
	v_mul_f32_e32 v136, 0xbfb8aa3b, v35
	v_mul_f32_e32 v137, 0xbfb8aa3b, v39
	v_exp_f32_e32 v136, v136
	v_exp_f32_e32 v137, v137
	v_mul_f32_e32 v43, v43, v35
	v_mul_f32_e32 v47, v47, v39
	v_add_f32_e32 v136, 1.0, v136
	v_add_f32_e32 v137, 1.0, v137
	v_rcp_f32_e32 v136, v136
	v_rcp_f32_e32 v137, v137
	s_nop 0
	v_mul_f32_e32 v43, v43, v136
	v_mul_f32_e32 v47, v47, v137
	v_cvt_pk_bf16_f32 v43, v43, v47
	ds_write_b16 v188, v43 offset:4752
	ds_write_b16_d16_hi v188, v43 offset:4784
	v_mul_f32_e32 v36, v36, v250
	v_mul_f32_e32 v40, v40, v250
	v_mul_f32_e32 v44, v44, v250
	v_mul_f32_e32 v48, v48, v250
	v_mul_f32_e32 v136, 0xbfb8aa3b, v36
	v_mul_f32_e32 v137, 0xbfb8aa3b, v40
	v_exp_f32_e32 v136, v136
	v_exp_f32_e32 v137, v137
	v_mul_f32_e32 v44, v44, v36
	v_mul_f32_e32 v48, v48, v40
	v_add_f32_e32 v136, 1.0, v136
	v_add_f32_e32 v137, 1.0, v137
	v_rcp_f32_e32 v136, v136
	v_rcp_f32_e32 v137, v137
	s_nop 0
	v_mul_f32_e32 v44, v44, v136
	v_mul_f32_e32 v48, v48, v137
	v_cvt_pk_bf16_f32 v44, v44, v48
	ds_write_b16 v188, v44 offset:4896
	ds_write_b16_d16_hi v188, v44 offset:4928
	v_mul_f32_e32 v37, v37, v251
	v_mul_f32_e32 v41, v41, v251
	v_mul_f32_e32 v45, v45, v251
	v_mul_f32_e32 v49, v49, v251
	v_mul_f32_e32 v136, 0xbfb8aa3b, v37
	v_mul_f32_e32 v137, 0xbfb8aa3b, v41
	v_exp_f32_e32 v136, v136
	v_exp_f32_e32 v137, v137
	v_mul_f32_e32 v45, v45, v37
	v_mul_f32_e32 v49, v49, v41
	v_add_f32_e32 v136, 1.0, v136
	v_add_f32_e32 v137, 1.0, v137
	v_rcp_f32_e32 v136, v136
	v_rcp_f32_e32 v137, v137
	s_nop 0
	v_mul_f32_e32 v45, v45, v136
	v_mul_f32_e32 v49, v49, v137
	v_cvt_pk_bf16_f32 v45, v45, v49
	ds_write_b16 v188, v45 offset:5040
	ds_write_b16_d16_hi v188, v45 offset:5072
	v_mul_f32_e32 v50, v50, v252
	v_mul_f32_e32 v54, v54, v252
	v_mul_f32_e32 v58, v58, v252
	v_mul_f32_e32 v62, v62, v252
	v_mul_f32_e32 v136, 0xbfb8aa3b, v50
	v_mul_f32_e32 v137, 0xbfb8aa3b, v54
	v_exp_f32_e32 v136, v136
	v_exp_f32_e32 v137, v137
	v_mul_f32_e32 v58, v58, v50
	v_mul_f32_e32 v62, v62, v54
	v_add_f32_e32 v136, 1.0, v136
	v_add_f32_e32 v137, 1.0, v137
	v_rcp_f32_e32 v136, v136
	v_rcp_f32_e32 v137, v137
	s_nop 0
	v_mul_f32_e32 v58, v58, v136
	v_mul_f32_e32 v62, v62, v137
	v_cvt_pk_bf16_f32 v58, v58, v62
	ds_write_b16 v188, v58 offset:6912
	ds_write_b16_d16_hi v188, v58 offset:6944
	v_mul_f32_e32 v51, v51, v253
	v_mul_f32_e32 v55, v55, v253
	v_mul_f32_e32 v59, v59, v253
	v_mul_f32_e32 v63, v63, v253
	v_mul_f32_e32 v136, 0xbfb8aa3b, v51
	v_mul_f32_e32 v137, 0xbfb8aa3b, v55
	v_exp_f32_e32 v136, v136
	v_exp_f32_e32 v137, v137
	v_mul_f32_e32 v59, v59, v51
	v_mul_f32_e32 v63, v63, v55
	v_add_f32_e32 v136, 1.0, v136
	v_add_f32_e32 v137, 1.0, v137
	v_rcp_f32_e32 v136, v136
	v_rcp_f32_e32 v137, v137
	s_nop 0
	v_mul_f32_e32 v59, v59, v136
	v_mul_f32_e32 v63, v63, v137
	v_cvt_pk_bf16_f32 v59, v59, v63
	ds_write_b16 v188, v59 offset:7056
	ds_write_b16_d16_hi v188, v59 offset:7088
	v_mul_f32_e32 v52, v52, v254
	v_mul_f32_e32 v56, v56, v254
	v_mul_f32_e32 v60, v60, v254
	v_mul_f32_e32 v64, v64, v254
	v_mul_f32_e32 v136, 0xbfb8aa3b, v52
	v_mul_f32_e32 v137, 0xbfb8aa3b, v56
	v_exp_f32_e32 v136, v136
	v_exp_f32_e32 v137, v137
	v_mul_f32_e32 v60, v60, v52
	v_mul_f32_e32 v64, v64, v56
	v_add_f32_e32 v136, 1.0, v136
	v_add_f32_e32 v137, 1.0, v137
	v_rcp_f32_e32 v136, v136
	v_rcp_f32_e32 v137, v137
	s_nop 0
	v_mul_f32_e32 v60, v60, v136
	v_mul_f32_e32 v64, v64, v137
	v_cvt_pk_bf16_f32 v60, v60, v64
	ds_write_b16 v188, v60 offset:7200
	ds_write_b16_d16_hi v188, v60 offset:7232
	v_mul_f32_e32 v53, v53, v255
	v_mul_f32_e32 v57, v57, v255
	v_mul_f32_e32 v61, v61, v255
	v_mul_f32_e32 v65, v65, v255
	v_mul_f32_e32 v136, 0xbfb8aa3b, v53
	v_mul_f32_e32 v137, 0xbfb8aa3b, v57
	v_exp_f32_e32 v136, v136
	v_exp_f32_e32 v137, v137
	v_mul_f32_e32 v61, v61, v53
	v_mul_f32_e32 v65, v65, v57
	v_add_f32_e32 v136, 1.0, v136
	v_add_f32_e32 v137, 1.0, v137
	v_rcp_f32_e32 v136, v136
	v_rcp_f32_e32 v137, v137
	s_nop 0
	v_mul_f32_e32 v61, v61, v136
	v_mul_f32_e32 v65, v65, v137
	v_cvt_pk_bf16_f32 v61, v61, v65
	ds_write_b16 v188, v61 offset:7344
	ds_write_b16_d16_hi v188, v61 offset:7376
	s_waitcnt lgkmcnt(0)
	s_barrier
	ds_read_b128 v[144:147], v189
	ds_read_b128 v[148:151], v189 offset:4608
	ds_read_b128 v[172:175], v189 offset:9216
	ds_read_b128 v[176:179], v189 offset:13824
	s_mov_b32 s56, s58
	s_mov_b32 s57, s59
	s_waitcnt lgkmcnt(3)
	global_store_dwordx4 v243, v[144:147], s[56:57]
	s_add_u32 s56, s56, 0x59000
	s_addc_u32 s57, s57, 0
	s_waitcnt lgkmcnt(2)
	global_store_dwordx4 v243, v[148:151], s[56:57]
	s_add_u32 s56, s56, 0x59000
	s_addc_u32 s57, s57, 0
	s_waitcnt lgkmcnt(1)
	global_store_dwordx4 v243, v[172:175], s[56:57]
	s_add_u32 s56, s56, 0x59000
	s_addc_u32 s57, s57, 0
	s_waitcnt lgkmcnt(0)
	global_store_dwordx4 v243, v[176:179], s[56:57]
	s_add_u32 s58, s58, 0x400
	s_addc_u32 s59, s59, 0
	s_barrier
	v_mul_f32_e32 v66, v66, v152
	v_mul_f32_e32 v70, v70, v152
	v_mul_f32_e32 v74, v74, v152
	v_mul_f32_e32 v78, v78, v152
	v_mul_f32_e32 v136, 0xbfb8aa3b, v66
	v_mul_f32_e32 v137, 0xbfb8aa3b, v70
	v_exp_f32_e32 v136, v136
	v_exp_f32_e32 v137, v137
	v_mul_f32_e32 v74, v74, v66
	v_mul_f32_e32 v78, v78, v70
	v_add_f32_e32 v136, 1.0, v136
	v_add_f32_e32 v137, 1.0, v137
	v_rcp_f32_e32 v136, v136
	v_rcp_f32_e32 v137, v137
	s_nop 0
	v_mul_f32_e32 v74, v74, v136
	v_mul_f32_e32 v78, v78, v137
	v_cvt_pk_bf16_f32 v74, v74, v78
	ds_write_b16 v188, v74
	ds_write_b16_d16_hi v188, v74 offset:32
	v_mul_f32_e32 v67, v67, v153
	v_mul_f32_e32 v71, v71, v153
	v_mul_f32_e32 v75, v75, v153
	v_mul_f32_e32 v79, v79, v153
	v_mul_f32_e32 v136, 0xbfb8aa3b, v67
	v_mul_f32_e32 v137, 0xbfb8aa3b, v71
	v_exp_f32_e32 v136, v136
	v_exp_f32_e32 v137, v137
	v_mul_f32_e32 v75, v75, v67
	v_mul_f32_e32 v79, v79, v71
	v_add_f32_e32 v136, 1.0, v136
	v_add_f32_e32 v137, 1.0, v137
	v_rcp_f32_e32 v136, v136
	v_rcp_f32_e32 v137, v137
	s_nop 0
	v_mul_f32_e32 v75, v75, v136
	v_mul_f32_e32 v79, v79, v137
	v_cvt_pk_bf16_f32 v75, v75, v79
	ds_write_b16 v188, v75 offset:144
	ds_write_b16_d16_hi v188, v75 offset:176
	v_mul_f32_e32 v68, v68, v154
	v_mul_f32_e32 v72, v72, v154
	v_mul_f32_e32 v76, v76, v154
	v_mul_f32_e32 v80, v80, v154
	v_mul_f32_e32 v136, 0xbfb8aa3b, v68
	v_mul_f32_e32 v137, 0xbfb8aa3b, v72
	v_exp_f32_e32 v136, v136
	v_exp_f32_e32 v137, v137
	v_mul_f32_e32 v76, v76, v68
	v_mul_f32_e32 v80, v80, v72
	v_add_f32_e32 v136, 1.0, v136
	v_add_f32_e32 v137, 1.0, v137
	v_rcp_f32_e32 v136, v136
	v_rcp_f32_e32 v137, v137
	s_nop 0
	v_mul_f32_e32 v76, v76, v136
	v_mul_f32_e32 v80, v80, v137
	v_cvt_pk_bf16_f32 v76, v76, v80
	ds_write_b16 v188, v76 offset:288
	ds_write_b16_d16_hi v188, v76 offset:320
	v_mul_f32_e32 v69, v69, v155
	v_mul_f32_e32 v73, v73, v155
	v_mul_f32_e32 v77, v77, v155
	v_mul_f32_e32 v81, v81, v155
	v_mul_f32_e32 v136, 0xbfb8aa3b, v69
	v_mul_f32_e32 v137, 0xbfb8aa3b, v73
	v_exp_f32_e32 v136, v136
	v_exp_f32_e32 v137, v137
	v_mul_f32_e32 v77, v77, v69
	v_mul_f32_e32 v81, v81, v73
	v_add_f32_e32 v136, 1.0, v136
	v_add_f32_e32 v137, 1.0, v137
	v_rcp_f32_e32 v136, v136
	v_rcp_f32_e32 v137, v137
	s_nop 0
	v_mul_f32_e32 v77, v77, v136
	v_mul_f32_e32 v81, v81, v137
	v_cvt_pk_bf16_f32 v77, v77, v81
	ds_write_b16 v188, v77 offset:432
	ds_write_b16_d16_hi v188, v77 offset:464
	v_mul_f32_e32 v82, v82, v244
	v_mul_f32_e32 v86, v86, v244
	v_mul_f32_e32 v90, v90, v244
	v_mul_f32_e32 v94, v94, v244
	v_mul_f32_e32 v136, 0xbfb8aa3b, v82
	v_mul_f32_e32 v137, 0xbfb8aa3b, v86
	v_exp_f32_e32 v136, v136
	v_exp_f32_e32 v137, v137
	v_mul_f32_e32 v90, v90, v82
	v_mul_f32_e32 v94, v94, v86
	v_add_f32_e32 v136, 1.0, v136
	v_add_f32_e32 v137, 1.0, v137
	v_rcp_f32_e32 v136, v136
	v_rcp_f32_e32 v137, v137
	s_nop 0
	v_mul_f32_e32 v90, v90, v136
	v_mul_f32_e32 v94, v94, v137
	v_cvt_pk_bf16_f32 v90, v90, v94
	ds_write_b16 v188, v90 offset:2304
	ds_write_b16_d16_hi v188, v90 offset:2336
	v_mul_f32_e32 v83, v83, v245
	v_mul_f32_e32 v87, v87, v245
	v_mul_f32_e32 v91, v91, v245
	v_mul_f32_e32 v95, v95, v245
	v_mul_f32_e32 v136, 0xbfb8aa3b, v83
	v_mul_f32_e32 v137, 0xbfb8aa3b, v87
	v_exp_f32_e32 v136, v136
	v_exp_f32_e32 v137, v137
	v_mul_f32_e32 v91, v91, v83
	v_mul_f32_e32 v95, v95, v87
	v_add_f32_e32 v136, 1.0, v136
	v_add_f32_e32 v137, 1.0, v137
	v_rcp_f32_e32 v136, v136
	v_rcp_f32_e32 v137, v137
	s_nop 0
	v_mul_f32_e32 v91, v91, v136
	v_mul_f32_e32 v95, v95, v137
	v_cvt_pk_bf16_f32 v91, v91, v95
	ds_write_b16 v188, v91 offset:2448
	ds_write_b16_d16_hi v188, v91 offset:2480
	v_mul_f32_e32 v84, v84, v246
	v_mul_f32_e32 v88, v88, v246
	v_mul_f32_e32 v92, v92, v246
	v_mul_f32_e32 v96, v96, v246
	v_mul_f32_e32 v136, 0xbfb8aa3b, v84
	v_mul_f32_e32 v137, 0xbfb8aa3b, v88
	v_exp_f32_e32 v136, v136
	v_exp_f32_e32 v137, v137
	v_mul_f32_e32 v92, v92, v84
	v_mul_f32_e32 v96, v96, v88
	v_add_f32_e32 v136, 1.0, v136
	v_add_f32_e32 v137, 1.0, v137
	v_rcp_f32_e32 v136, v136
	v_rcp_f32_e32 v137, v137
	s_nop 0
	v_mul_f32_e32 v92, v92, v136
	v_mul_f32_e32 v96, v96, v137
	v_cvt_pk_bf16_f32 v92, v92, v96
	ds_write_b16 v188, v92 offset:2592
	ds_write_b16_d16_hi v188, v92 offset:2624
	v_mul_f32_e32 v85, v85, v247
	v_mul_f32_e32 v89, v89, v247
	v_mul_f32_e32 v93, v93, v247
	v_mul_f32_e32 v97, v97, v247
	v_mul_f32_e32 v136, 0xbfb8aa3b, v85
	v_mul_f32_e32 v137, 0xbfb8aa3b, v89
	v_exp_f32_e32 v136, v136
	v_exp_f32_e32 v137, v137
	v_mul_f32_e32 v93, v93, v85
	v_mul_f32_e32 v97, v97, v89
	v_add_f32_e32 v136, 1.0, v136
	v_add_f32_e32 v137, 1.0, v137
	v_rcp_f32_e32 v136, v136
	v_rcp_f32_e32 v137, v137
	s_nop 0
	v_mul_f32_e32 v93, v93, v136
	v_mul_f32_e32 v97, v97, v137
	v_cvt_pk_bf16_f32 v93, v93, v97
	ds_write_b16 v188, v93 offset:2736
	ds_write_b16_d16_hi v188, v93 offset:2768
	v_mul_f32_e32 v98, v98, v248
	v_mul_f32_e32 v102, v102, v248
	v_mul_f32_e32 v106, v106, v248
	v_mul_f32_e32 v110, v110, v248
	v_mul_f32_e32 v136, 0xbfb8aa3b, v98
	v_mul_f32_e32 v137, 0xbfb8aa3b, v102
	v_exp_f32_e32 v136, v136
	v_exp_f32_e32 v137, v137
	v_mul_f32_e32 v106, v106, v98
	v_mul_f32_e32 v110, v110, v102
	v_add_f32_e32 v136, 1.0, v136
	v_add_f32_e32 v137, 1.0, v137
	v_rcp_f32_e32 v136, v136
	v_rcp_f32_e32 v137, v137
	s_nop 0
	v_mul_f32_e32 v106, v106, v136
	v_mul_f32_e32 v110, v110, v137
	v_cvt_pk_bf16_f32 v106, v106, v110
	ds_write_b16 v188, v106 offset:4608
	ds_write_b16_d16_hi v188, v106 offset:4640
	v_mul_f32_e32 v99, v99, v249
	v_mul_f32_e32 v103, v103, v249
	v_mul_f32_e32 v107, v107, v249
	v_mul_f32_e32 v111, v111, v249
	v_mul_f32_e32 v136, 0xbfb8aa3b, v99
	v_mul_f32_e32 v137, 0xbfb8aa3b, v103
	v_exp_f32_e32 v136, v136
	v_exp_f32_e32 v137, v137
	v_mul_f32_e32 v107, v107, v99
	v_mul_f32_e32 v111, v111, v103
	v_add_f32_e32 v136, 1.0, v136
	v_add_f32_e32 v137, 1.0, v137
	v_rcp_f32_e32 v136, v136
	v_rcp_f32_e32 v137, v137
	s_nop 0
	v_mul_f32_e32 v107, v107, v136
	v_mul_f32_e32 v111, v111, v137
	v_cvt_pk_bf16_f32 v107, v107, v111
	ds_write_b16 v188, v107 offset:4752
	ds_write_b16_d16_hi v188, v107 offset:4784
	v_mul_f32_e32 v100, v100, v250
	v_mul_f32_e32 v104, v104, v250
	v_mul_f32_e32 v108, v108, v250
	v_mul_f32_e32 v112, v112, v250
	v_mul_f32_e32 v136, 0xbfb8aa3b, v100
	v_mul_f32_e32 v137, 0xbfb8aa3b, v104
	v_exp_f32_e32 v136, v136
	v_exp_f32_e32 v137, v137
	v_mul_f32_e32 v108, v108, v100
	v_mul_f32_e32 v112, v112, v104
	v_add_f32_e32 v136, 1.0, v136
	v_add_f32_e32 v137, 1.0, v137
	v_rcp_f32_e32 v136, v136
	v_rcp_f32_e32 v137, v137
	s_nop 0
	v_mul_f32_e32 v108, v108, v136
	v_mul_f32_e32 v112, v112, v137
	v_cvt_pk_bf16_f32 v108, v108, v112
	ds_write_b16 v188, v108 offset:4896
	ds_write_b16_d16_hi v188, v108 offset:4928
	v_mul_f32_e32 v101, v101, v251
	v_mul_f32_e32 v105, v105, v251
	v_mul_f32_e32 v109, v109, v251
	v_mul_f32_e32 v113, v113, v251
	v_mul_f32_e32 v136, 0xbfb8aa3b, v101
	v_mul_f32_e32 v137, 0xbfb8aa3b, v105
	v_exp_f32_e32 v136, v136
	v_exp_f32_e32 v137, v137
	v_mul_f32_e32 v109, v109, v101
	v_mul_f32_e32 v113, v113, v105
	v_add_f32_e32 v136, 1.0, v136
	v_add_f32_e32 v137, 1.0, v137
	v_rcp_f32_e32 v136, v136
	v_rcp_f32_e32 v137, v137
	s_nop 0
	v_mul_f32_e32 v109, v109, v136
	v_mul_f32_e32 v113, v113, v137
	v_cvt_pk_bf16_f32 v109, v109, v113
	ds_write_b16 v188, v109 offset:5040
	ds_write_b16_d16_hi v188, v109 offset:5072
	v_mul_f32_e32 v114, v114, v252
	v_mul_f32_e32 v118, v118, v252
	v_mul_f32_e32 v122, v122, v252
	v_mul_f32_e32 v126, v126, v252
	v_mul_f32_e32 v136, 0xbfb8aa3b, v114
	v_mul_f32_e32 v137, 0xbfb8aa3b, v118
	v_exp_f32_e32 v136, v136
	v_exp_f32_e32 v137, v137
	v_mul_f32_e32 v122, v122, v114
	v_mul_f32_e32 v126, v126, v118
	v_add_f32_e32 v136, 1.0, v136
	v_add_f32_e32 v137, 1.0, v137
	v_rcp_f32_e32 v136, v136
	v_rcp_f32_e32 v137, v137
	s_nop 0
	v_mul_f32_e32 v122, v122, v136
	v_mul_f32_e32 v126, v126, v137
	v_cvt_pk_bf16_f32 v122, v122, v126
	ds_write_b16 v188, v122 offset:6912
	ds_write_b16_d16_hi v188, v122 offset:6944
	v_mul_f32_e32 v115, v115, v253
	v_mul_f32_e32 v119, v119, v253
	v_mul_f32_e32 v123, v123, v253
	v_mul_f32_e32 v127, v127, v253
	v_mul_f32_e32 v136, 0xbfb8aa3b, v115
	v_mul_f32_e32 v137, 0xbfb8aa3b, v119
	v_exp_f32_e32 v136, v136
	v_exp_f32_e32 v137, v137
	v_mul_f32_e32 v123, v123, v115
	v_mul_f32_e32 v127, v127, v119
	v_add_f32_e32 v136, 1.0, v136
	v_add_f32_e32 v137, 1.0, v137
	v_rcp_f32_e32 v136, v136
	v_rcp_f32_e32 v137, v137
	s_nop 0
	v_mul_f32_e32 v123, v123, v136
	v_mul_f32_e32 v127, v127, v137
	v_cvt_pk_bf16_f32 v123, v123, v127
	ds_write_b16 v188, v123 offset:7056
	ds_write_b16_d16_hi v188, v123 offset:7088
	v_mul_f32_e32 v116, v116, v254
	v_mul_f32_e32 v120, v120, v254
	v_mul_f32_e32 v124, v124, v254
	v_mul_f32_e32 v128, v128, v254
	v_mul_f32_e32 v136, 0xbfb8aa3b, v116
	v_mul_f32_e32 v137, 0xbfb8aa3b, v120
	v_exp_f32_e32 v136, v136
	v_exp_f32_e32 v137, v137
	v_mul_f32_e32 v124, v124, v116
	v_mul_f32_e32 v128, v128, v120
	v_add_f32_e32 v136, 1.0, v136
	v_add_f32_e32 v137, 1.0, v137
	v_rcp_f32_e32 v136, v136
	v_rcp_f32_e32 v137, v137
	s_nop 0
	v_mul_f32_e32 v124, v124, v136
	v_mul_f32_e32 v128, v128, v137
	v_cvt_pk_bf16_f32 v124, v124, v128
	ds_write_b16 v188, v124 offset:7200
	ds_write_b16_d16_hi v188, v124 offset:7232
	v_mul_f32_e32 v117, v117, v255
	v_mul_f32_e32 v121, v121, v255
	v_mul_f32_e32 v125, v125, v255
	v_mul_f32_e32 v129, v129, v255
	v_mul_f32_e32 v136, 0xbfb8aa3b, v117
	v_mul_f32_e32 v137, 0xbfb8aa3b, v121
	v_exp_f32_e32 v136, v136
	v_exp_f32_e32 v137, v137
	v_mul_f32_e32 v125, v125, v117
	v_mul_f32_e32 v129, v129, v121
	v_add_f32_e32 v136, 1.0, v136
	v_add_f32_e32 v137, 1.0, v137
	v_rcp_f32_e32 v136, v136
	v_rcp_f32_e32 v137, v137
	s_nop 0
	v_mul_f32_e32 v125, v125, v136
	v_mul_f32_e32 v129, v129, v137
	v_cvt_pk_bf16_f32 v125, v125, v129
	ds_write_b16 v188, v125 offset:7344
	ds_write_b16_d16_hi v188, v125 offset:7376
	s_waitcnt lgkmcnt(0)
	s_barrier
	ds_read_b128 v[144:147], v189
	ds_read_b128 v[148:151], v189 offset:4608
	ds_read_b128 v[172:175], v189 offset:9216
	ds_read_b128 v[176:179], v189 offset:13824
	s_mov_b32 s56, s58
	s_mov_b32 s57, s59
	s_waitcnt lgkmcnt(3)
	global_store_dwordx4 v243, v[144:147], s[56:57]
	s_add_u32 s56, s56, 0x59000
	s_addc_u32 s57, s57, 0
	s_waitcnt lgkmcnt(2)
	global_store_dwordx4 v243, v[148:151], s[56:57]
	s_add_u32 s56, s56, 0x59000
	s_addc_u32 s57, s57, 0
	s_waitcnt lgkmcnt(1)
	global_store_dwordx4 v243, v[172:175], s[56:57]
	s_add_u32 s56, s56, 0x59000
	s_addc_u32 s57, s57, 0
	s_waitcnt lgkmcnt(0)
	global_store_dwordx4 v243, v[176:179], s[56:57]
	s_add_i32 s55, s55, 1
	s_cmp_lt_u32 s55, 5
	s_barrier
	s_cbranch_scc1 .Lgu2_tile
	s_add_i32 s21, s21, s72
	s_cmpk_lt_i32 s21, 0x200
	s_cbranch_scc1 .Lgu2_vloop

.Lres1_loop:
	v_add_u32_e32 v234, s22, v232
	v_add_u32_e32 v236, s28, v232
	v_add_u32_e32 v235, s22, v233
	v_add_u32_e32 v237, s28, v233
	ds_read_b128 v[136:139], v234
	ds_read_b128 v[140:143], v234 offset:2048
	ds_read_b128 v[144:147], v234 offset:4096
	ds_read_b128 v[148:151], v234 offset:6144
	ds_read_b128 v[188:191], v236
	ds_read_b128 v[196:199], v236 offset:2048
	ds_read_b128 v[200:203], v236 offset:4096
	ds_read_b128 v[204:207], v236 offset:6144
	ds_read_b128 v[172:175], v235
	ds_read_b128 v[176:179], v235 offset:2048
	ds_read_b128 v[180:183], v235 offset:4096
	ds_read_b128 v[184:187], v235 offset:6144
	ds_read_b128 v[212:215], v237
	ds_read_b128 v[216:219], v237 offset:2048
	ds_read_b128 v[220:223], v237 offset:4096
	ds_read_b128 v[224:227], v237 offset:6144
	s_add_i32 m0, s51, 0xc000
	s_nop 0
	global_load_lds_dwordx4 v228, s[44:45]
	s_add_i32 m0, s51, 0xc400
	s_nop 0
	global_load_lds_dwordx4 v230, s[44:45]
	s_add_i32 m0, s51, 0xe000
	s_nop 0
	global_load_lds_dwordx4 v229, s[44:45]
	s_add_i32 m0, s51, 0xe400
	s_nop 0
	global_load_lds_dwordx4 v231, s[44:45]
	s_add_i32 m0, s51, 0x10000
	s_nop 0
	global_load_lds_dwordx4 v228, s[46:47]
	s_add_i32 m0, s51, 0x10400
	s_nop 0
	global_load_lds_dwordx4 v230, s[46:47]
	s_waitcnt lgkmcnt(8)
	s_setprio 1
	v_mfma_f32_16x16x32_bf16 v[2:5], v[136:139], v[188:191], v[2:5]
	v_mfma_f32_16x16x32_bf16 v[6:9], v[136:139], v[196:199], v[6:9]
	v_mfma_f32_16x16x32_bf16 v[10:13], v[136:139], v[200:203], v[10:13]
	v_mfma_f32_16x16x32_bf16 v[14:17], v[136:139], v[204:207], v[14:17]
	v_mfma_f32_16x16x32_bf16 v[18:21], v[140:143], v[188:191], v[18:21]
	v_mfma_f32_16x16x32_bf16 v[22:25], v[140:143], v[196:199], v[22:25]
	v_mfma_f32_16x16x32_bf16 v[26:29], v[140:143], v[200:203], v[26:29]
	v_mfma_f32_16x16x32_bf16 v[30:33], v[140:143], v[204:207], v[30:33]
	v_mfma_f32_16x16x32_bf16 v[34:37], v[144:147], v[188:191], v[34:37]
	v_mfma_f32_16x16x32_bf16 v[38:41], v[144:147], v[196:199], v[38:41]
	v_mfma_f32_16x16x32_bf16 v[42:45], v[144:147], v[200:203], v[42:45]
	v_mfma_f32_16x16x32_bf16 v[46:49], v[144:147], v[204:207], v[46:49]
	v_mfma_f32_16x16x32_bf16 v[50:53], v[148:151], v[188:191], v[50:53]
	v_mfma_f32_16x16x32_bf16 v[54:57], v[148:151], v[196:199], v[54:57]
	v_mfma_f32_16x16x32_bf16 v[58:61], v[148:151], v[200:203], v[58:61]
	v_mfma_f32_16x16x32_bf16 v[62:65], v[148:151], v[204:207], v[62:65]
	s_waitcnt lgkmcnt(0)
	v_mfma_f32_16x16x32_bf16 v[2:5], v[172:175], v[212:215], v[2:5]
	v_mfma_f32_16x16x32_bf16 v[6:9], v[172:175], v[216:219], v[6:9]
	v_mfma_f32_16x16x32_bf16 v[10:13], v[172:175], v[220:223], v[10:13]
	v_mfma_f32_16x16x32_bf16 v[14:17], v[172:175], v[224:227], v[14:17]
	v_mfma_f32_16x16x32_bf16 v[18:21], v[176:179], v[212:215], v[18:21]
	v_mfma_f32_16x16x32_bf16 v[22:25], v[176:179], v[216:219], v[22:25]
	v_mfma_f32_16x16x32_bf16 v[26:29], v[176:179], v[220:223], v[26:29]
	v_mfma_f32_16x16x32_bf16 v[30:33], v[176:179], v[224:227], v[30:33]
	v_mfma_f32_16x16x32_bf16 v[34:37], v[180:183], v[212:215], v[34:37]
	v_mfma_f32_16x16x32_bf16 v[38:41], v[180:183], v[216:219], v[38:41]
	v_mfma_f32_16x16x32_bf16 v[42:45], v[180:183], v[220:223], v[42:45]
	v_mfma_f32_16x16x32_bf16 v[46:49], v[180:183], v[224:227], v[46:49]
	v_mfma_f32_16x16x32_bf16 v[50:53], v[184:187], v[212:215], v[50:53]
	v_mfma_f32_16x16x32_bf16 v[54:57], v[184:187], v[216:219], v[54:57]
	v_mfma_f32_16x16x32_bf16 v[58:61], v[184:187], v[220:223], v[58:61]
	v_mfma_f32_16x16x32_bf16 v[62:65], v[184:187], v[224:227], v[62:65]
	s_setprio 0
	s_waitcnt vmcnt(6)
	s_barrier
	v_add_u32_e32 v236, s40, v232
	v_add_u32_e32 v237, s40, v233
	ds_read_b128 v[188:191], v236
	ds_read_b128 v[196:199], v236 offset:2048
	ds_read_b128 v[200:203], v236 offset:4096
	ds_read_b128 v[204:207], v236 offset:6144
	ds_read_b128 v[212:215], v237
	ds_read_b128 v[216:219], v237 offset:2048
	ds_read_b128 v[220:223], v237 offset:4096
	ds_read_b128 v[224:227], v237 offset:6144
	s_mov_b32 m0, s51
	s_nop 0
	global_load_lds_dwordx4 v229, s[46:47]
	s_add_i32 m0, s51, 0x400
	s_nop 0
	global_load_lds_dwordx4 v231, s[46:47]
	s_add_i32 m0, s51, 0x2000
	s_nop 0
	global_load_lds_dwordx4 v228, s[48:49]
	s_add_i32 m0, s51, 0x2400
	s_nop 0
	global_load_lds_dwordx4 v230, s[48:49]
	s_add_i32 m0, s51, 0x4000
	s_nop 0
	global_load_lds_dwordx4 v229, s[48:49]
	s_add_i32 m0, s51, 0x4400
	s_nop 0
	global_load_lds_dwordx4 v231, s[48:49]
	s_waitcnt lgkmcnt(4)
	s_setprio 1
	v_mfma_f32_16x16x32_bf16 v[66:69], v[136:139], v[188:191], v[66:69]
	v_mfma_f32_16x16x32_bf16 v[70:73], v[136:139], v[196:199], v[70:73]
	v_mfma_f32_16x16x32_bf16 v[74:77], v[136:139], v[200:203], v[74:77]
	v_mfma_f32_16x16x32_bf16 v[78:81], v[136:139], v[204:207], v[78:81]
	v_mfma_f32_16x16x32_bf16 v[82:85], v[140:143], v[188:191], v[82:85]
	v_mfma_f32_16x16x32_bf16 v[86:89], v[140:143], v[196:199], v[86:89]
	v_mfma_f32_16x16x32_bf16 v[90:93], v[140:143], v[200:203], v[90:93]
	v_mfma_f32_16x16x32_bf16 v[94:97], v[140:143], v[204:207], v[94:97]
	v_mfma_f32_16x16x32_bf16 v[98:101], v[144:147], v[188:191], v[98:101]
	v_mfma_f32_16x16x32_bf16 v[102:105], v[144:147], v[196:199], v[102:105]
	v_mfma_f32_16x16x32_bf16 v[106:109], v[144:147], v[200:203], v[106:109]
	v_mfma_f32_16x16x32_bf16 v[110:113], v[144:147], v[204:207], v[110:113]
	v_mfma_f32_16x16x32_bf16 v[114:117], v[148:151], v[188:191], v[114:117]
	v_mfma_f32_16x16x32_bf16 v[118:121], v[148:151], v[196:199], v[118:121]
	v_mfma_f32_16x16x32_bf16 v[122:125], v[148:151], v[200:203], v[122:125]
	v_mfma_f32_16x16x32_bf16 v[126:129], v[148:151], v[204:207], v[126:129]
	s_waitcnt lgkmcnt(0)
	v_mfma_f32_16x16x32_bf16 v[66:69], v[172:175], v[212:215], v[66:69]
	v_mfma_f32_16x16x32_bf16 v[70:73], v[172:175], v[216:219], v[70:73]
	v_mfma_f32_16x16x32_bf16 v[74:77], v[172:175], v[220:223], v[74:77]
	v_mfma_f32_16x16x32_bf16 v[78:81], v[172:175], v[224:227], v[78:81]
	v_mfma_f32_16x16x32_bf16 v[82:85], v[176:179], v[212:215], v[82:85]
	v_mfma_f32_16x16x32_bf16 v[86:89], v[176:179], v[216:219], v[86:89]
	v_mfma_f32_16x16x32_bf16 v[90:93], v[176:179], v[220:223], v[90:93]
	v_mfma_f32_16x16x32_bf16 v[94:97], v[176:179], v[224:227], v[94:97]
	v_mfma_f32_16x16x32_bf16 v[98:101], v[180:183], v[212:215], v[98:101]
	v_mfma_f32_16x16x32_bf16 v[102:105], v[180:183], v[216:219], v[102:105]
	v_mfma_f32_16x16x32_bf16 v[106:109], v[180:183], v[220:223], v[106:109]
	v_mfma_f32_16x16x32_bf16 v[110:113], v[180:183], v[224:227], v[110:113]
	v_mfma_f32_16x16x32_bf16 v[114:117], v[184:187], v[212:215], v[114:117]
	v_mfma_f32_16x16x32_bf16 v[118:121], v[184:187], v[216:219], v[118:121]
	v_mfma_f32_16x16x32_bf16 v[122:125], v[184:187], v[220:223], v[122:125]
	v_mfma_f32_16x16x32_bf16 v[126:129], v[184:187], v[224:227], v[126:129]
	s_setprio 0
	v_add_u32_e32 v228, 0x80, v228
	v_add_u32_e32 v229, 0x80, v229
	v_add_u32_e32 v230, 0x80, v230
	v_add_u32_e32 v231, 0x80, v231
	s_waitcnt vmcnt(4)
	s_barrier
	v_add_u32_e32 v234, s23, v232
	v_add_u32_e32 v236, s29, v232
	v_add_u32_e32 v235, s23, v233
	v_add_u32_e32 v237, s29, v233
	ds_read_b128 v[136:139], v234
	ds_read_b128 v[140:143], v234 offset:2048
	ds_read_b128 v[144:147], v234 offset:4096
	ds_read_b128 v[148:151], v234 offset:6144
	ds_read_b128 v[188:191], v236
	ds_read_b128 v[196:199], v236 offset:2048
	ds_read_b128 v[200:203], v236 offset:4096
	ds_read_b128 v[204:207], v236 offset:6144
	ds_read_b128 v[172:175], v235
	ds_read_b128 v[176:179], v235 offset:2048
	ds_read_b128 v[180:183], v235 offset:4096
	ds_read_b128 v[184:187], v235 offset:6144
	ds_read_b128 v[212:215], v237
	ds_read_b128 v[216:219], v237 offset:2048
	ds_read_b128 v[220:223], v237 offset:4096
	ds_read_b128 v[224:227], v237 offset:6144
	s_add_i32 m0, s51, 0x6000
	s_nop 0
	global_load_lds_dwordx4 v228, s[44:45]
	s_add_i32 m0, s51, 0x6400
	s_nop 0
	global_load_lds_dwordx4 v230, s[44:45]
	s_add_i32 m0, s51, 0x8000
	s_nop 0
	global_load_lds_dwordx4 v229, s[44:45]
	s_add_i32 m0, s51, 0x8400
	s_nop 0
	global_load_lds_dwordx4 v231, s[44:45]
	s_add_i32 m0, s51, 0xa000
	s_nop 0
	global_load_lds_dwordx4 v228, s[46:47]
	s_add_i32 m0, s51, 0xa400
	s_nop 0
	global_load_lds_dwordx4 v230, s[46:47]
	s_waitcnt lgkmcnt(8)
	s_setprio 1
	v_mfma_f32_16x16x32_bf16 v[2:5], v[136:139], v[188:191], v[2:5]
	v_mfma_f32_16x16x32_bf16 v[6:9], v[136:139], v[196:199], v[6:9]
	v_mfma_f32_16x16x32_bf16 v[10:13], v[136:139], v[200:203], v[10:13]
	v_mfma_f32_16x16x32_bf16 v[14:17], v[136:139], v[204:207], v[14:17]
	v_mfma_f32_16x16x32_bf16 v[18:21], v[140:143], v[188:191], v[18:21]
	v_mfma_f32_16x16x32_bf16 v[22:25], v[140:143], v[196:199], v[22:25]
	v_mfma_f32_16x16x32_bf16 v[26:29], v[140:143], v[200:203], v[26:29]
	v_mfma_f32_16x16x32_bf16 v[30:33], v[140:143], v[204:207], v[30:33]
	v_mfma_f32_16x16x32_bf16 v[34:37], v[144:147], v[188:191], v[34:37]
	v_mfma_f32_16x16x32_bf16 v[38:41], v[144:147], v[196:199], v[38:41]
	v_mfma_f32_16x16x32_bf16 v[42:45], v[144:147], v[200:203], v[42:45]
	v_mfma_f32_16x16x32_bf16 v[46:49], v[144:147], v[204:207], v[46:49]
	v_mfma_f32_16x16x32_bf16 v[50:53], v[148:151], v[188:191], v[50:53]
	v_mfma_f32_16x16x32_bf16 v[54:57], v[148:151], v[196:199], v[54:57]
	v_mfma_f32_16x16x32_bf16 v[58:61], v[148:151], v[200:203], v[58:61]
	v_mfma_f32_16x16x32_bf16 v[62:65], v[148:151], v[204:207], v[62:65]
	s_waitcnt lgkmcnt(0)
	v_mfma_f32_16x16x32_bf16 v[2:5], v[172:175], v[212:215], v[2:5]
	v_mfma_f32_16x16x32_bf16 v[6:9], v[172:175], v[216:219], v[6:9]
	v_mfma_f32_16x16x32_bf16 v[10:13], v[172:175], v[220:223], v[10:13]
	v_mfma_f32_16x16x32_bf16 v[14:17], v[172:175], v[224:227], v[14:17]
	v_mfma_f32_16x16x32_bf16 v[18:21], v[176:179], v[212:215], v[18:21]
	v_mfma_f32_16x16x32_bf16 v[22:25], v[176:179], v[216:219], v[22:25]
	v_mfma_f32_16x16x32_bf16 v[26:29], v[176:179], v[220:223], v[26:29]
	v_mfma_f32_16x16x32_bf16 v[30:33], v[176:179], v[224:227], v[30:33]
	v_mfma_f32_16x16x32_bf16 v[34:37], v[180:183], v[212:215], v[34:37]
	v_mfma_f32_16x16x32_bf16 v[38:41], v[180:183], v[216:219], v[38:41]
	v_mfma_f32_16x16x32_bf16 v[42:45], v[180:183], v[220:223], v[42:45]
	v_mfma_f32_16x16x32_bf16 v[46:49], v[180:183], v[224:227], v[46:49]
	v_mfma_f32_16x16x32_bf16 v[50:53], v[184:187], v[212:215], v[50:53]
	v_mfma_f32_16x16x32_bf16 v[54:57], v[184:187], v[216:219], v[54:57]
	v_mfma_f32_16x16x32_bf16 v[58:61], v[184:187], v[220:223], v[58:61]
	v_mfma_f32_16x16x32_bf16 v[62:65], v[184:187], v[224:227], v[62:65]
	s_setprio 0
	s_waitcnt vmcnt(6)
	s_barrier
	v_add_u32_e32 v236, s41, v232
	v_add_u32_e32 v237, s41, v233
	ds_read_b128 v[188:191], v236
	ds_read_b128 v[196:199], v236 offset:2048
	ds_read_b128 v[200:203], v236 offset:4096
	ds_read_b128 v[204:207], v236 offset:6144
	ds_read_b128 v[212:215], v237
	ds_read_b128 v[216:219], v237 offset:2048
	ds_read_b128 v[220:223], v237 offset:4096
	ds_read_b128 v[224:227], v237 offset:6144
	s_add_i32 m0, s51, 0xc000
	s_nop 0
	global_load_lds_dwordx4 v229, s[46:47]
	s_add_i32 m0, s51, 0xc400
	s_nop 0
	global_load_lds_dwordx4 v231, s[46:47]
	s_add_i32 m0, s51, 0xe000
	s_nop 0
	global_load_lds_dwordx4 v228, s[48:49]
	s_add_i32 m0, s51, 0xe400
	s_nop 0
	global_load_lds_dwordx4 v230, s[48:49]
	s_add_i32 m0, s51, 0x10000
	s_nop 0
	global_load_lds_dwordx4 v229, s[48:49]
	s_add_i32 m0, s51, 0x10400
	s_nop 0
	global_load_lds_dwordx4 v231, s[48:49]
	s_waitcnt lgkmcnt(4)
	s_setprio 1
	v_mfma_f32_16x16x32_bf16 v[66:69], v[136:139], v[188:191], v[66:69]
	v_mfma_f32_16x16x32_bf16 v[70:73], v[136:139], v[196:199], v[70:73]
	v_mfma_f32_16x16x32_bf16 v[74:77], v[136:139], v[200:203], v[74:77]
	v_mfma_f32_16x16x32_bf16 v[78:81], v[136:139], v[204:207], v[78:81]
	v_mfma_f32_16x16x32_bf16 v[82:85], v[140:143], v[188:191], v[82:85]
	v_mfma_f32_16x16x32_bf16 v[86:89], v[140:143], v[196:199], v[86:89]
	v_mfma_f32_16x16x32_bf16 v[90:93], v[140:143], v[200:203], v[90:93]
	v_mfma_f32_16x16x32_bf16 v[94:97], v[140:143], v[204:207], v[94:97]
	v_mfma_f32_16x16x32_bf16 v[98:101], v[144:147], v[188:191], v[98:101]
	v_mfma_f32_16x16x32_bf16 v[102:105], v[144:147], v[196:199], v[102:105]
	v_mfma_f32_16x16x32_bf16 v[106:109], v[144:147], v[200:203], v[106:109]
	v_mfma_f32_16x16x32_bf16 v[110:113], v[144:147], v[204:207], v[110:113]
	v_mfma_f32_16x16x32_bf16 v[114:117], v[148:151], v[188:191], v[114:117]
	v_mfma_f32_16x16x32_bf16 v[118:121], v[148:151], v[196:199], v[118:121]
	v_mfma_f32_16x16x32_bf16 v[122:125], v[148:151], v[200:203], v[122:125]
	v_mfma_f32_16x16x32_bf16 v[126:129], v[148:151], v[204:207], v[126:129]
	s_waitcnt lgkmcnt(0)
	v_mfma_f32_16x16x32_bf16 v[66:69], v[172:175], v[212:215], v[66:69]
	v_mfma_f32_16x16x32_bf16 v[70:73], v[172:175], v[216:219], v[70:73]
	v_mfma_f32_16x16x32_bf16 v[74:77], v[172:175], v[220:223], v[74:77]
	v_mfma_f32_16x16x32_bf16 v[78:81], v[172:175], v[224:227], v[78:81]
	v_mfma_f32_16x16x32_bf16 v[82:85], v[176:179], v[212:215], v[82:85]
	v_mfma_f32_16x16x32_bf16 v[86:89], v[176:179], v[216:219], v[86:89]
	v_mfma_f32_16x16x32_bf16 v[90:93], v[176:179], v[220:223], v[90:93]
	v_mfma_f32_16x16x32_bf16 v[94:97], v[176:179], v[224:227], v[94:97]
	v_mfma_f32_16x16x32_bf16 v[98:101], v[180:183], v[212:215], v[98:101]
	v_mfma_f32_16x16x32_bf16 v[102:105], v[180:183], v[216:219], v[102:105]
	v_mfma_f32_16x16x32_bf16 v[106:109], v[180:183], v[220:223], v[106:109]
	v_mfma_f32_16x16x32_bf16 v[110:113], v[180:183], v[224:227], v[110:113]
	v_mfma_f32_16x16x32_bf16 v[114:117], v[184:187], v[212:215], v[114:117]
	v_mfma_f32_16x16x32_bf16 v[118:121], v[184:187], v[216:219], v[118:121]
	v_mfma_f32_16x16x32_bf16 v[122:125], v[184:187], v[220:223], v[122:125]
	v_mfma_f32_16x16x32_bf16 v[126:129], v[184:187], v[224:227], v[126:129]
	s_setprio 0
	v_add_u32_e32 v228, 0x80, v228
	v_add_u32_e32 v229, 0x80, v229
	v_add_u32_e32 v230, 0x80, v230
	v_add_u32_e32 v231, 0x80, v231
	s_waitcnt vmcnt(4)
	s_barrier
	v_add_u32_e32 v234, s24, v232
	v_add_u32_e32 v236, s30, v232
	v_add_u32_e32 v235, s24, v233
	v_add_u32_e32 v237, s30, v233
	ds_read_b128 v[136:139], v234
	ds_read_b128 v[140:143], v234 offset:2048
	ds_read_b128 v[144:147], v234 offset:4096
	ds_read_b128 v[148:151], v234 offset:6144
	ds_read_b128 v[188:191], v236
	ds_read_b128 v[196:199], v236 offset:2048
	ds_read_b128 v[200:203], v236 offset:4096
	ds_read_b128 v[204:207], v236 offset:6144
	ds_read_b128 v[172:175], v235
	ds_read_b128 v[176:179], v235 offset:2048
	ds_read_b128 v[180:183], v235 offset:4096
	ds_read_b128 v[184:187], v235 offset:6144
	ds_read_b128 v[212:215], v237
	ds_read_b128 v[216:219], v237 offset:2048
	ds_read_b128 v[220:223], v237 offset:4096
	ds_read_b128 v[224:227], v237 offset:6144
	s_mov_b32 m0, s51
	s_nop 0
	global_load_lds_dwordx4 v228, s[44:45]
	s_add_i32 m0, s51, 0x400
	s_nop 0
	global_load_lds_dwordx4 v230, s[44:45]
	s_add_i32 m0, s51, 0x2000
	s_nop 0
	global_load_lds_dwordx4 v229, s[44:45]
	s_add_i32 m0, s51, 0x2400
	s_nop 0
	global_load_lds_dwordx4 v231, s[44:45]
	s_add_i32 m0, s51, 0x4000
	s_nop 0
	global_load_lds_dwordx4 v228, s[46:47]
	s_add_i32 m0, s51, 0x4400
	s_nop 0
	global_load_lds_dwordx4 v230, s[46:47]
	s_waitcnt lgkmcnt(8)
	s_setprio 1
	v_mfma_f32_16x16x32_bf16 v[2:5], v[136:139], v[188:191], v[2:5]
	v_mfma_f32_16x16x32_bf16 v[6:9], v[136:139], v[196:199], v[6:9]
	v_mfma_f32_16x16x32_bf16 v[10:13], v[136:139], v[200:203], v[10:13]
	v_mfma_f32_16x16x32_bf16 v[14:17], v[136:139], v[204:207], v[14:17]
	v_mfma_f32_16x16x32_bf16 v[18:21], v[140:143], v[188:191], v[18:21]
	v_mfma_f32_16x16x32_bf16 v[22:25], v[140:143], v[196:199], v[22:25]
	v_mfma_f32_16x16x32_bf16 v[26:29], v[140:143], v[200:203], v[26:29]
	v_mfma_f32_16x16x32_bf16 v[30:33], v[140:143], v[204:207], v[30:33]
	v_mfma_f32_16x16x32_bf16 v[34:37], v[144:147], v[188:191], v[34:37]
	v_mfma_f32_16x16x32_bf16 v[38:41], v[144:147], v[196:199], v[38:41]
	v_mfma_f32_16x16x32_bf16 v[42:45], v[144:147], v[200:203], v[42:45]
	v_mfma_f32_16x16x32_bf16 v[46:49], v[144:147], v[204:207], v[46:49]
	v_mfma_f32_16x16x32_bf16 v[50:53], v[148:151], v[188:191], v[50:53]
	v_mfma_f32_16x16x32_bf16 v[54:57], v[148:151], v[196:199], v[54:57]
	v_mfma_f32_16x16x32_bf16 v[58:61], v[148:151], v[200:203], v[58:61]
	v_mfma_f32_16x16x32_bf16 v[62:65], v[148:151], v[204:207], v[62:65]
	s_waitcnt lgkmcnt(0)
	v_mfma_f32_16x16x32_bf16 v[2:5], v[172:175], v[212:215], v[2:5]
	v_mfma_f32_16x16x32_bf16 v[6:9], v[172:175], v[216:219], v[6:9]
	v_mfma_f32_16x16x32_bf16 v[10:13], v[172:175], v[220:223], v[10:13]
	v_mfma_f32_16x16x32_bf16 v[14:17], v[172:175], v[224:227], v[14:17]
	v_mfma_f32_16x16x32_bf16 v[18:21], v[176:179], v[212:215], v[18:21]
	v_mfma_f32_16x16x32_bf16 v[22:25], v[176:179], v[216:219], v[22:25]
	v_mfma_f32_16x16x32_bf16 v[26:29], v[176:179], v[220:223], v[26:29]
	v_mfma_f32_16x16x32_bf16 v[30:33], v[176:179], v[224:227], v[30:33]
	v_mfma_f32_16x16x32_bf16 v[34:37], v[180:183], v[212:215], v[34:37]
	v_mfma_f32_16x16x32_bf16 v[38:41], v[180:183], v[216:219], v[38:41]
	v_mfma_f32_16x16x32_bf16 v[42:45], v[180:183], v[220:223], v[42:45]
	v_mfma_f32_16x16x32_bf16 v[46:49], v[180:183], v[224:227], v[46:49]
	v_mfma_f32_16x16x32_bf16 v[50:53], v[184:187], v[212:215], v[50:53]
	v_mfma_f32_16x16x32_bf16 v[54:57], v[184:187], v[216:219], v[54:57]
	v_mfma_f32_16x16x32_bf16 v[58:61], v[184:187], v[220:223], v[58:61]
	v_mfma_f32_16x16x32_bf16 v[62:65], v[184:187], v[224:227], v[62:65]
	s_setprio 0
	s_waitcnt vmcnt(6)
	s_barrier
	v_add_u32_e32 v236, s42, v232
	v_add_u32_e32 v237, s42, v233
	ds_read_b128 v[188:191], v236
	ds_read_b128 v[196:199], v236 offset:2048
	ds_read_b128 v[200:203], v236 offset:4096
	ds_read_b128 v[204:207], v236 offset:6144
	ds_read_b128 v[212:215], v237
	ds_read_b128 v[216:219], v237 offset:2048
	ds_read_b128 v[220:223], v237 offset:4096
	ds_read_b128 v[224:227], v237 offset:6144
	s_add_i32 m0, s51, 0x6000
	s_nop 0
	global_load_lds_dwordx4 v229, s[46:47]
	s_add_i32 m0, s51, 0x6400
	s_nop 0
	global_load_lds_dwordx4 v231, s[46:47]
	s_add_i32 m0, s51, 0x8000
	s_nop 0
	global_load_lds_dwordx4 v228, s[48:49]
	s_add_i32 m0, s51, 0x8400
	s_nop 0
	global_load_lds_dwordx4 v230, s[48:49]
	s_add_i32 m0, s51, 0xa000
	s_nop 0
	global_load_lds_dwordx4 v229, s[48:49]
	s_add_i32 m0, s51, 0xa400
	s_nop 0
	global_load_lds_dwordx4 v231, s[48:49]
	s_waitcnt lgkmcnt(4)
	s_setprio 1
	v_mfma_f32_16x16x32_bf16 v[66:69], v[136:139], v[188:191], v[66:69]
	v_mfma_f32_16x16x32_bf16 v[70:73], v[136:139], v[196:199], v[70:73]
	v_mfma_f32_16x16x32_bf16 v[74:77], v[136:139], v[200:203], v[74:77]
	v_mfma_f32_16x16x32_bf16 v[78:81], v[136:139], v[204:207], v[78:81]
	v_mfma_f32_16x16x32_bf16 v[82:85], v[140:143], v[188:191], v[82:85]
	v_mfma_f32_16x16x32_bf16 v[86:89], v[140:143], v[196:199], v[86:89]
	v_mfma_f32_16x16x32_bf16 v[90:93], v[140:143], v[200:203], v[90:93]
	v_mfma_f32_16x16x32_bf16 v[94:97], v[140:143], v[204:207], v[94:97]
	v_mfma_f32_16x16x32_bf16 v[98:101], v[144:147], v[188:191], v[98:101]
	v_mfma_f32_16x16x32_bf16 v[102:105], v[144:147], v[196:199], v[102:105]
	v_mfma_f32_16x16x32_bf16 v[106:109], v[144:147], v[200:203], v[106:109]
	v_mfma_f32_16x16x32_bf16 v[110:113], v[144:147], v[204:207], v[110:113]
	v_mfma_f32_16x16x32_bf16 v[114:117], v[148:151], v[188:191], v[114:117]
	v_mfma_f32_16x16x32_bf16 v[118:121], v[148:151], v[196:199], v[118:121]
	v_mfma_f32_16x16x32_bf16 v[122:125], v[148:151], v[200:203], v[122:125]
	v_mfma_f32_16x16x32_bf16 v[126:129], v[148:151], v[204:207], v[126:129]
	s_waitcnt lgkmcnt(0)
	v_mfma_f32_16x16x32_bf16 v[66:69], v[172:175], v[212:215], v[66:69]
	v_mfma_f32_16x16x32_bf16 v[70:73], v[172:175], v[216:219], v[70:73]
	v_mfma_f32_16x16x32_bf16 v[74:77], v[172:175], v[220:223], v[74:77]
	v_mfma_f32_16x16x32_bf16 v[78:81], v[172:175], v[224:227], v[78:81]
	v_mfma_f32_16x16x32_bf16 v[82:85], v[176:179], v[212:215], v[82:85]
	v_mfma_f32_16x16x32_bf16 v[86:89], v[176:179], v[216:219], v[86:89]
	v_mfma_f32_16x16x32_bf16 v[90:93], v[176:179], v[220:223], v[90:93]
	v_mfma_f32_16x16x32_bf16 v[94:97], v[176:179], v[224:227], v[94:97]
	v_mfma_f32_16x16x32_bf16 v[98:101], v[180:183], v[212:215], v[98:101]
	v_mfma_f32_16x16x32_bf16 v[102:105], v[180:183], v[216:219], v[102:105]
	v_mfma_f32_16x16x32_bf16 v[106:109], v[180:183], v[220:223], v[106:109]
	v_mfma_f32_16x16x32_bf16 v[110:113], v[180:183], v[224:227], v[110:113]
	v_mfma_f32_16x16x32_bf16 v[114:117], v[184:187], v[212:215], v[114:117]
	v_mfma_f32_16x16x32_bf16 v[118:121], v[184:187], v[216:219], v[118:121]
	v_mfma_f32_16x16x32_bf16 v[122:125], v[184:187], v[220:223], v[122:125]
	v_mfma_f32_16x16x32_bf16 v[126:129], v[184:187], v[224:227], v[126:129]
	s_setprio 0
	v_add_u32_e32 v228, 0x80, v228
	v_add_u32_e32 v229, 0x80, v229
	v_add_u32_e32 v230, 0x80, v230
	v_add_u32_e32 v231, 0x80, v231
	s_waitcnt vmcnt(4)
	s_barrier
	s_add_i32 s52, s52, 1
	s_cmp_lt_u32 s52, 10
	s_cbranch_scc1 .Lres1_loop
	v_add_u32_e32 v234, s22, v232
	v_add_u32_e32 v236, s28, v232
	v_add_u32_e32 v235, s22, v233
	v_add_u32_e32 v237, s28, v233
	ds_read_b128 v[136:139], v234
	ds_read_b128 v[140:143], v234 offset:2048
	ds_read_b128 v[144:147], v234 offset:4096
	ds_read_b128 v[148:151], v234 offset:6144
	ds_read_b128 v[188:191], v236
	ds_read_b128 v[196:199], v236 offset:2048
	ds_read_b128 v[200:203], v236 offset:4096
	ds_read_b128 v[204:207], v236 offset:6144
	ds_read_b128 v[172:175], v235
	ds_read_b128 v[176:179], v235 offset:2048
	ds_read_b128 v[180:183], v235 offset:4096
	ds_read_b128 v[184:187], v235 offset:6144
	ds_read_b128 v[212:215], v237
	ds_read_b128 v[216:219], v237 offset:2048
	ds_read_b128 v[220:223], v237 offset:4096
	ds_read_b128 v[224:227], v237 offset:6144
	s_add_i32 m0, s51, 0xc000
	s_nop 0
	global_load_lds_dwordx4 v228, s[44:45]
	s_add_i32 m0, s51, 0xc400
	s_nop 0
	global_load_lds_dwordx4 v230, s[44:45]
	s_add_i32 m0, s51, 0xe000
	s_nop 0
	global_load_lds_dwordx4 v229, s[44:45]
	s_add_i32 m0, s51, 0xe400
	s_nop 0
	global_load_lds_dwordx4 v231, s[44:45]
	s_add_i32 m0, s51, 0x10000
	s_nop 0
	global_load_lds_dwordx4 v228, s[46:47]
	s_add_i32 m0, s51, 0x10400
	s_nop 0
	global_load_lds_dwordx4 v230, s[46:47]
	s_waitcnt lgkmcnt(8)
	s_setprio 1
	v_mfma_f32_16x16x32_bf16 v[2:5], v[136:139], v[188:191], v[2:5]
	v_mfma_f32_16x16x32_bf16 v[6:9], v[136:139], v[196:199], v[6:9]
	v_mfma_f32_16x16x32_bf16 v[10:13], v[136:139], v[200:203], v[10:13]
	v_mfma_f32_16x16x32_bf16 v[14:17], v[136:139], v[204:207], v[14:17]
	v_mfma_f32_16x16x32_bf16 v[18:21], v[140:143], v[188:191], v[18:21]
	v_mfma_f32_16x16x32_bf16 v[22:25], v[140:143], v[196:199], v[22:25]
	v_mfma_f32_16x16x32_bf16 v[26:29], v[140:143], v[200:203], v[26:29]
	v_mfma_f32_16x16x32_bf16 v[30:33], v[140:143], v[204:207], v[30:33]
	v_mfma_f32_16x16x32_bf16 v[34:37], v[144:147], v[188:191], v[34:37]
	v_mfma_f32_16x16x32_bf16 v[38:41], v[144:147], v[196:199], v[38:41]
	v_mfma_f32_16x16x32_bf16 v[42:45], v[144:147], v[200:203], v[42:45]
	v_mfma_f32_16x16x32_bf16 v[46:49], v[144:147], v[204:207], v[46:49]
	v_mfma_f32_16x16x32_bf16 v[50:53], v[148:151], v[188:191], v[50:53]
	v_mfma_f32_16x16x32_bf16 v[54:57], v[148:151], v[196:199], v[54:57]
	v_mfma_f32_16x16x32_bf16 v[58:61], v[148:151], v[200:203], v[58:61]
	v_mfma_f32_16x16x32_bf16 v[62:65], v[148:151], v[204:207], v[62:65]
	s_waitcnt lgkmcnt(0)
	v_mfma_f32_16x16x32_bf16 v[2:5], v[172:175], v[212:215], v[2:5]
	v_mfma_f32_16x16x32_bf16 v[6:9], v[172:175], v[216:219], v[6:9]
	v_mfma_f32_16x16x32_bf16 v[10:13], v[172:175], v[220:223], v[10:13]
	v_mfma_f32_16x16x32_bf16 v[14:17], v[172:175], v[224:227], v[14:17]
	v_mfma_f32_16x16x32_bf16 v[18:21], v[176:179], v[212:215], v[18:21]
	v_mfma_f32_16x16x32_bf16 v[22:25], v[176:179], v[216:219], v[22:25]
	v_mfma_f32_16x16x32_bf16 v[26:29], v[176:179], v[220:223], v[26:29]
	v_mfma_f32_16x16x32_bf16 v[30:33], v[176:179], v[224:227], v[30:33]
	v_mfma_f32_16x16x32_bf16 v[34:37], v[180:183], v[212:215], v[34:37]
	v_mfma_f32_16x16x32_bf16 v[38:41], v[180:183], v[216:219], v[38:41]
	v_mfma_f32_16x16x32_bf16 v[42:45], v[180:183], v[220:223], v[42:45]
	v_mfma_f32_16x16x32_bf16 v[46:49], v[180:183], v[224:227], v[46:49]
	v_mfma_f32_16x16x32_bf16 v[50:53], v[184:187], v[212:215], v[50:53]
	v_mfma_f32_16x16x32_bf16 v[54:57], v[184:187], v[216:219], v[54:57]
	v_mfma_f32_16x16x32_bf16 v[58:61], v[184:187], v[220:223], v[58:61]
	v_mfma_f32_16x16x32_bf16 v[62:65], v[184:187], v[224:227], v[62:65]
	s_setprio 0
	s_waitcnt vmcnt(6)
	s_barrier
	v_add_u32_e32 v236, s40, v232
	v_add_u32_e32 v237, s40, v233
	ds_read_b128 v[188:191], v236
	ds_read_b128 v[196:199], v236 offset:2048
	ds_read_b128 v[200:203], v236 offset:4096
	ds_read_b128 v[204:207], v236 offset:6144
	ds_read_b128 v[212:215], v237
	ds_read_b128 v[216:219], v237 offset:2048
	ds_read_b128 v[220:223], v237 offset:4096
	ds_read_b128 v[224:227], v237 offset:6144
	s_mov_b32 m0, s51
	s_nop 0
	global_load_lds_dwordx4 v229, s[46:47]
	s_add_i32 m0, s51, 0x400
	s_nop 0
	global_load_lds_dwordx4 v231, s[46:47]
	s_add_i32 m0, s51, 0x2000
	s_nop 0
	global_load_lds_dwordx4 v228, s[48:49]
	s_add_i32 m0, s51, 0x2400
	s_nop 0
	global_load_lds_dwordx4 v230, s[48:49]
	s_add_i32 m0, s51, 0x4000
	s_nop 0
	global_load_lds_dwordx4 v229, s[48:49]
	s_add_i32 m0, s51, 0x4400
	s_nop 0
	global_load_lds_dwordx4 v231, s[48:49]
	s_waitcnt lgkmcnt(4)
	s_setprio 1
	v_mfma_f32_16x16x32_bf16 v[66:69], v[136:139], v[188:191], v[66:69]
	v_mfma_f32_16x16x32_bf16 v[70:73], v[136:139], v[196:199], v[70:73]
	v_mfma_f32_16x16x32_bf16 v[74:77], v[136:139], v[200:203], v[74:77]
	v_mfma_f32_16x16x32_bf16 v[78:81], v[136:139], v[204:207], v[78:81]
	v_mfma_f32_16x16x32_bf16 v[82:85], v[140:143], v[188:191], v[82:85]
	v_mfma_f32_16x16x32_bf16 v[86:89], v[140:143], v[196:199], v[86:89]
	v_mfma_f32_16x16x32_bf16 v[90:93], v[140:143], v[200:203], v[90:93]
	v_mfma_f32_16x16x32_bf16 v[94:97], v[140:143], v[204:207], v[94:97]
	v_mfma_f32_16x16x32_bf16 v[98:101], v[144:147], v[188:191], v[98:101]
	v_mfma_f32_16x16x32_bf16 v[102:105], v[144:147], v[196:199], v[102:105]
	v_mfma_f32_16x16x32_bf16 v[106:109], v[144:147], v[200:203], v[106:109]
	v_mfma_f32_16x16x32_bf16 v[110:113], v[144:147], v[204:207], v[110:113]
	v_mfma_f32_16x16x32_bf16 v[114:117], v[148:151], v[188:191], v[114:117]
	v_mfma_f32_16x16x32_bf16 v[118:121], v[148:151], v[196:199], v[118:121]
	v_mfma_f32_16x16x32_bf16 v[122:125], v[148:151], v[200:203], v[122:125]
	v_mfma_f32_16x16x32_bf16 v[126:129], v[148:151], v[204:207], v[126:129]
	s_waitcnt lgkmcnt(0)
	v_mfma_f32_16x16x32_bf16 v[66:69], v[172:175], v[212:215], v[66:69]
	v_mfma_f32_16x16x32_bf16 v[70:73], v[172:175], v[216:219], v[70:73]
	v_mfma_f32_16x16x32_bf16 v[74:77], v[172:175], v[220:223], v[74:77]
	v_mfma_f32_16x16x32_bf16 v[78:81], v[172:175], v[224:227], v[78:81]
	v_mfma_f32_16x16x32_bf16 v[82:85], v[176:179], v[212:215], v[82:85]
	v_mfma_f32_16x16x32_bf16 v[86:89], v[176:179], v[216:219], v[86:89]
	v_mfma_f32_16x16x32_bf16 v[90:93], v[176:179], v[220:223], v[90:93]
	v_mfma_f32_16x16x32_bf16 v[94:97], v[176:179], v[224:227], v[94:97]
	v_mfma_f32_16x16x32_bf16 v[98:101], v[180:183], v[212:215], v[98:101]
	v_mfma_f32_16x16x32_bf16 v[102:105], v[180:183], v[216:219], v[102:105]
	v_mfma_f32_16x16x32_bf16 v[106:109], v[180:183], v[220:223], v[106:109]
	v_mfma_f32_16x16x32_bf16 v[110:113], v[180:183], v[224:227], v[110:113]
	v_mfma_f32_16x16x32_bf16 v[114:117], v[184:187], v[212:215], v[114:117]
	v_mfma_f32_16x16x32_bf16 v[118:121], v[184:187], v[216:219], v[118:121]
	v_mfma_f32_16x16x32_bf16 v[122:125], v[184:187], v[220:223], v[122:125]
	v_mfma_f32_16x16x32_bf16 v[126:129], v[184:187], v[224:227], v[126:129]
	s_setprio 0
	v_add_u32_e32 v228, 0x80, v228
	v_add_u32_e32 v229, 0x80, v229
	v_add_u32_e32 v230, 0x80, v230
	v_add_u32_e32 v231, 0x80, v231
	s_waitcnt vmcnt(4)
	s_barrier
	v_add_u32_e32 v234, s23, v232
	v_add_u32_e32 v236, s29, v232
	v_add_u32_e32 v235, s23, v233
	v_add_u32_e32 v237, s29, v233
	ds_read_b128 v[136:139], v234
	ds_read_b128 v[140:143], v234 offset:2048
	ds_read_b128 v[144:147], v234 offset:4096
	ds_read_b128 v[148:151], v234 offset:6144
	ds_read_b128 v[188:191], v236
	ds_read_b128 v[196:199], v236 offset:2048
	ds_read_b128 v[200:203], v236 offset:4096
	ds_read_b128 v[204:207], v236 offset:6144
	ds_read_b128 v[172:175], v235
	ds_read_b128 v[176:179], v235 offset:2048
	ds_read_b128 v[180:183], v235 offset:4096
	ds_read_b128 v[184:187], v235 offset:6144
	ds_read_b128 v[212:215], v237
	ds_read_b128 v[216:219], v237 offset:2048
	ds_read_b128 v[220:223], v237 offset:4096
	ds_read_b128 v[224:227], v237 offset:6144
	s_waitcnt lgkmcnt(8)
	s_setprio 1
	v_mfma_f32_16x16x32_bf16 v[2:5], v[136:139], v[188:191], v[2:5]
	v_mfma_f32_16x16x32_bf16 v[6:9], v[136:139], v[196:199], v[6:9]
	v_mfma_f32_16x16x32_bf16 v[10:13], v[136:139], v[200:203], v[10:13]
	v_mfma_f32_16x16x32_bf16 v[14:17], v[136:139], v[204:207], v[14:17]
	v_mfma_f32_16x16x32_bf16 v[18:21], v[140:143], v[188:191], v[18:21]
	v_mfma_f32_16x16x32_bf16 v[22:25], v[140:143], v[196:199], v[22:25]
	v_mfma_f32_16x16x32_bf16 v[26:29], v[140:143], v[200:203], v[26:29]
	v_mfma_f32_16x16x32_bf16 v[30:33], v[140:143], v[204:207], v[30:33]
	v_mfma_f32_16x16x32_bf16 v[34:37], v[144:147], v[188:191], v[34:37]
	v_mfma_f32_16x16x32_bf16 v[38:41], v[144:147], v[196:199], v[38:41]
	v_mfma_f32_16x16x32_bf16 v[42:45], v[144:147], v[200:203], v[42:45]
	v_mfma_f32_16x16x32_bf16 v[46:49], v[144:147], v[204:207], v[46:49]
	v_mfma_f32_16x16x32_bf16 v[50:53], v[148:151], v[188:191], v[50:53]
	v_mfma_f32_16x16x32_bf16 v[54:57], v[148:151], v[196:199], v[54:57]
	v_mfma_f32_16x16x32_bf16 v[58:61], v[148:151], v[200:203], v[58:61]
	v_mfma_f32_16x16x32_bf16 v[62:65], v[148:151], v[204:207], v[62:65]
	s_waitcnt lgkmcnt(0)
	v_mfma_f32_16x16x32_bf16 v[2:5], v[172:175], v[212:215], v[2:5]
	v_mfma_f32_16x16x32_bf16 v[6:9], v[172:175], v[216:219], v[6:9]
	v_mfma_f32_16x16x32_bf16 v[10:13], v[172:175], v[220:223], v[10:13]
	v_mfma_f32_16x16x32_bf16 v[14:17], v[172:175], v[224:227], v[14:17]
	v_mfma_f32_16x16x32_bf16 v[18:21], v[176:179], v[212:215], v[18:21]
	v_mfma_f32_16x16x32_bf16 v[22:25], v[176:179], v[216:219], v[22:25]
	v_mfma_f32_16x16x32_bf16 v[26:29], v[176:179], v[220:223], v[26:29]
	v_mfma_f32_16x16x32_bf16 v[30:33], v[176:179], v[224:227], v[30:33]
	v_mfma_f32_16x16x32_bf16 v[34:37], v[180:183], v[212:215], v[34:37]
	v_mfma_f32_16x16x32_bf16 v[38:41], v[180:183], v[216:219], v[38:41]
	v_mfma_f32_16x16x32_bf16 v[42:45], v[180:183], v[220:223], v[42:45]
	v_mfma_f32_16x16x32_bf16 v[46:49], v[180:183], v[224:227], v[46:49]
	v_mfma_f32_16x16x32_bf16 v[50:53], v[184:187], v[212:215], v[50:53]
	v_mfma_f32_16x16x32_bf16 v[54:57], v[184:187], v[216:219], v[54:57]
	v_mfma_f32_16x16x32_bf16 v[58:61], v[184:187], v[220:223], v[58:61]
	v_mfma_f32_16x16x32_bf16 v[62:65], v[184:187], v[224:227], v[62:65]
	s_setprio 0
	s_waitcnt vmcnt(0)
	s_barrier
	v_add_u32_e32 v236, s41, v232
	v_add_u32_e32 v237, s41, v233
	ds_read_b128 v[188:191], v236
	ds_read_b128 v[196:199], v236 offset:2048
	ds_read_b128 v[200:203], v236 offset:4096
	ds_read_b128 v[204:207], v236 offset:6144
	ds_read_b128 v[212:215], v237
	ds_read_b128 v[216:219], v237 offset:2048
	ds_read_b128 v[220:223], v237 offset:4096
	ds_read_b128 v[224:227], v237 offset:6144
	s_waitcnt lgkmcnt(4)
	s_setprio 1
	v_mfma_f32_16x16x32_bf16 v[66:69], v[136:139], v[188:191], v[66:69]
	v_mfma_f32_16x16x32_bf16 v[70:73], v[136:139], v[196:199], v[70:73]
	v_mfma_f32_16x16x32_bf16 v[74:77], v[136:139], v[200:203], v[74:77]
	v_mfma_f32_16x16x32_bf16 v[78:81], v[136:139], v[204:207], v[78:81]
	v_mfma_f32_16x16x32_bf16 v[82:85], v[140:143], v[188:191], v[82:85]
	v_mfma_f32_16x16x32_bf16 v[86:89], v[140:143], v[196:199], v[86:89]
	v_mfma_f32_16x16x32_bf16 v[90:93], v[140:143], v[200:203], v[90:93]
	v_mfma_f32_16x16x32_bf16 v[94:97], v[140:143], v[204:207], v[94:97]
	v_mfma_f32_16x16x32_bf16 v[98:101], v[144:147], v[188:191], v[98:101]
	v_mfma_f32_16x16x32_bf16 v[102:105], v[144:147], v[196:199], v[102:105]
	v_mfma_f32_16x16x32_bf16 v[106:109], v[144:147], v[200:203], v[106:109]
	v_mfma_f32_16x16x32_bf16 v[110:113], v[144:147], v[204:207], v[110:113]
	v_mfma_f32_16x16x32_bf16 v[114:117], v[148:151], v[188:191], v[114:117]
	v_mfma_f32_16x16x32_bf16 v[118:121], v[148:151], v[196:199], v[118:121]
	v_mfma_f32_16x16x32_bf16 v[122:125], v[148:151], v[200:203], v[122:125]
	v_mfma_f32_16x16x32_bf16 v[126:129], v[148:151], v[204:207], v[126:129]
	s_waitcnt lgkmcnt(0)
	v_mfma_f32_16x16x32_bf16 v[66:69], v[172:175], v[212:215], v[66:69]
	v_mfma_f32_16x16x32_bf16 v[70:73], v[172:175], v[216:219], v[70:73]
	v_mfma_f32_16x16x32_bf16 v[74:77], v[172:175], v[220:223], v[74:77]
	v_mfma_f32_16x16x32_bf16 v[78:81], v[172:175], v[224:227], v[78:81]
	v_mfma_f32_16x16x32_bf16 v[82:85], v[176:179], v[212:215], v[82:85]
	v_mfma_f32_16x16x32_bf16 v[86:89], v[176:179], v[216:219], v[86:89]
	v_mfma_f32_16x16x32_bf16 v[90:93], v[176:179], v[220:223], v[90:93]
	v_mfma_f32_16x16x32_bf16 v[94:97], v[176:179], v[224:227], v[94:97]
	v_mfma_f32_16x16x32_bf16 v[98:101], v[180:183], v[212:215], v[98:101]
	v_mfma_f32_16x16x32_bf16 v[102:105], v[180:183], v[216:219], v[102:105]
	v_mfma_f32_16x16x32_bf16 v[106:109], v[180:183], v[220:223], v[106:109]
	v_mfma_f32_16x16x32_bf16 v[110:113], v[180:183], v[224:227], v[110:113]
	v_mfma_f32_16x16x32_bf16 v[114:117], v[184:187], v[212:215], v[114:117]
	v_mfma_f32_16x16x32_bf16 v[118:121], v[184:187], v[216:219], v[118:121]
	v_mfma_f32_16x16x32_bf16 v[122:125], v[184:187], v[220:223], v[122:125]
	v_mfma_f32_16x16x32_bf16 v[126:129], v[184:187], v[224:227], v[126:129]
	s_setprio 0
	s_nop 7
	s_barrier
	s_load_dwordx2 s[44:45], s[12:13], 0x0
	s_load_dwordx2 s[58:59], s[12:13], 0x100
	s_load_dwordx2 s[46:47], s[12:13], 0x160
	s_load_dwordx2 s[48:49], s[12:13], 0x1c8
	v_lshrrev_b32_e32 v241, 5, v131
	v_and_b32_e32 v242, 31, v131
	v_lshlrev_b32_e32 v243, 4, v242
	s_movk_i32 s56, 0x210
	v_mad_u32_u24 v239, v241, s56, v243
	v_add_u32_e32 v239, 16, v239
	v_lshlrev_b32_e32 v240, 13, v241
	v_or_b32_e32 v240, v240, v243
	v_lshlrev_b32_e32 v244, 3, v242
	v_mad_u32_u24 v244, v241, s81, v244
	v_lshlrev_b32_e32 v245, 2, v241
	s_lshl_b32 s56, s53, 13
	s_lshl_b32 s57, s54, 2
	s_add_i32 s56, s56, s57
	s_mul_i32 s57, s53, s81
	s_lshl_b32 s0, s54, 1
	s_add_i32 s57, s57, s0
	s_lshl_b32 s0, s53, 2
	s_waitcnt lgkmcnt(0)
	s_add_u32 s44, s44, s56
	s_addc_u32 s45, s45, 0
	s_add_u32 s58, s58, s56
	s_addc_u32 s59, s59, 0
	s_add_u32 s46, s46, s57
	s_addc_u32 s47, s47, 0
	s_add_u32 s48, s48, s0
	s_addc_u32 s49, s49, 0
	s_mov_b32 s56, s44
	s_mov_b32 s57, s45
	global_load_dwordx4 v[136:139], v240, s[56:57]
	s_add_u32 s56, s56, 0x10000
	s_addc_u32 s57, s57, 0
	global_load_dwordx4 v[140:143], v240, s[56:57]
	s_add_u32 s56, s56, 0x10000
	s_addc_u32 s57, s57, 0
	global_load_dwordx4 v[144:147], v240, s[56:57]
	s_add_u32 s56, s56, 0x10000
	s_addc_u32 s57, s57, 0
	global_load_dwordx4 v[148:151], v240, s[56:57]
	s_add_u32 s56, s56, 0x10000
	s_addc_u32 s57, s57, 0
	global_load_dwordx4 v[172:175], v240, s[56:57]
	s_add_u32 s56, s56, 0x10000
	s_addc_u32 s57, s57, 0
	global_load_dwordx4 v[176:179], v240, s[56:57]
	s_add_u32 s56, s56, 0x10000
	s_addc_u32 s57, s57, 0
	global_load_dwordx4 v[180:183], v240, s[56:57]
	s_add_u32 s56, s56, 0x10000
	s_addc_u32 s57, s57, 0
	global_load_dwordx4 v[184:187], v240, s[56:57]
	s_add_u32 s56, s56, 0x10000
	s_addc_u32 s57, s57, 0
	global_load_dwordx4 v[188:191], v240, s[56:57]
	s_add_u32 s56, s56, 0x10000
	s_addc_u32 s57, s57, 0
	global_load_dwordx4 v[196:199], v240, s[56:57]
	s_add_u32 s56, s56, 0x10000
	s_addc_u32 s57, s57, 0
	global_load_dwordx4 v[200:203], v240, s[56:57]
	s_add_u32 s56, s56, 0x10000
	s_addc_u32 s57, s57, 0
	global_load_dwordx4 v[204:207], v240, s[56:57]
	s_add_u32 s56, s56, 0x10000
	s_addc_u32 s57, s57, 0
	global_load_dwordx4 v[212:215], v240, s[56:57]
	s_add_u32 s56, s56, 0x10000
	s_addc_u32 s57, s57, 0
	global_load_dwordx4 v[216:219], v240, s[56:57]
	s_add_u32 s56, s56, 0x10000
	s_addc_u32 s57, s57, 0
	global_load_dwordx4 v[220:223], v240, s[56:57]
	s_add_u32 s56, s56, 0x10000
	s_addc_u32 s57, s57, 0
	global_load_dwordx4 v[224:227], v240, s[56:57]
	ds_write_b32 v238, v2
	ds_write_b32 v238, v3 offset:528
	ds_write_b32 v238, v4 offset:1056
	ds_write_b32 v238, v5 offset:1584
	ds_write_b32 v238, v6 offset:64
	ds_write_b32 v238, v7 offset:592
	ds_write_b32 v238, v8 offset:1120
	ds_write_b32 v238, v9 offset:1648
	ds_write_b32 v238, v10 offset:128
	ds_write_b32 v238, v11 offset:656
	ds_write_b32 v238, v12 offset:1184
	ds_write_b32 v238, v13 offset:1712
	ds_write_b32 v238, v14 offset:192
	ds_write_b32 v238, v15 offset:720
	ds_write_b32 v238, v16 offset:1248
	ds_write_b32 v238, v17 offset:1776
	ds_write_b32 v238, v18 offset:8448
	ds_write_b32 v238, v19 offset:8976
	ds_write_b32 v238, v20 offset:9504
	ds_write_b32 v238, v21 offset:10032
	ds_write_b32 v238, v22 offset:8512
	ds_write_b32 v238, v23 offset:9040
	ds_write_b32 v238, v24 offset:9568
	ds_write_b32 v238, v25 offset:10096
	ds_write_b32 v238, v26 offset:8576
	ds_write_b32 v238, v27 offset:9104
	ds_write_b32 v238, v28 offset:9632
	ds_write_b32 v238, v29 offset:10160
	ds_write_b32 v238, v30 offset:8640
	ds_write_b32 v238, v31 offset:9168
	ds_write_b32 v238, v32 offset:9696
	ds_write_b32 v238, v33 offset:10224
	ds_write_b32 v238, v34 offset:16896
	ds_write_b32 v238, v35 offset:17424
	ds_write_b32 v238, v36 offset:17952
	ds_write_b32 v238, v37 offset:18480
	ds_write_b32 v238, v38 offset:16960
	ds_write_b32 v238, v39 offset:17488
	ds_write_b32 v238, v40 offset:18016
	ds_write_b32 v238, v41 offset:18544
	ds_write_b32 v238, v42 offset:17024
	ds_write_b32 v238, v43 offset:17552
	ds_write_b32 v238, v44 offset:18080
	ds_write_b32 v238, v45 offset:18608
	ds_write_b32 v238, v46 offset:17088
	ds_write_b32 v238, v47 offset:17616
	ds_write_b32 v238, v48 offset:18144
	ds_write_b32 v238, v49 offset:18672
	ds_write_b32 v238, v50 offset:25344
	ds_write_b32 v238, v51 offset:25872
	ds_write_b32 v238, v52 offset:26400
	ds_write_b32 v238, v53 offset:26928
	ds_write_b32 v238, v54 offset:25408
	ds_write_b32 v238, v55 offset:25936
	ds_write_b32 v238, v56 offset:26464
	ds_write_b32 v238, v57 offset:26992
	ds_write_b32 v238, v58 offset:25472
	ds_write_b32 v238, v59 offset:26000
	ds_write_b32 v238, v60 offset:26528
	ds_write_b32 v238, v61 offset:27056
	ds_write_b32 v238, v62 offset:25536
	ds_write_b32 v238, v63 offset:26064
	ds_write_b32 v238, v64 offset:26592
	ds_write_b32 v238, v65 offset:27120
	s_waitcnt lgkmcnt(0)
	s_barrier
	ds_read_b128 v[2:5], v239
	ds_read_b128 v[6:9], v239 offset:4224
	ds_read_b128 v[10:13], v239 offset:8448
	ds_read_b128 v[14:17], v239 offset:12672
	ds_read_b128 v[18:21], v239 offset:16896
	ds_read_b128 v[22:25], v239 offset:21120
	ds_read_b128 v[26:29], v239 offset:25344
	ds_read_b128 v[30:33], v239 offset:29568
	ds_read_b128 v[34:37], v239 offset:33792
	ds_read_b128 v[38:41], v239 offset:38016
	ds_read_b128 v[42:45], v239 offset:42240
	ds_read_b128 v[46:49], v239 offset:46464
	ds_read_b128 v[50:53], v239 offset:50688
	ds_read_b128 v[54:57], v239 offset:54912
	ds_read_b128 v[58:61], v239 offset:59136
	ds_read_b128 v[62:65], v239 offset:63360
	s_waitcnt vmcnt(15) lgkmcnt(15)
	v_pk_add_f32 v[2:3], v[2:3], v[136:137]
	v_pk_add_f32 v[4:5], v[4:5], v[138:139]
	v_cvt_pk_bf16_f32 v136, v2, v3
	v_cvt_pk_bf16_f32 v137, v4, v5
	v_mul_f32_e32 v138, v2, v2
	v_fmac_f32_e32 v138, v3, v3
	v_fmac_f32_e32 v138, v4, v4
	v_fmac_f32_e32 v138, v5, v5
	s_waitcnt vmcnt(14) lgkmcnt(14)
	v_pk_add_f32 v[6:7], v[6:7], v[140:141]
	v_pk_add_f32 v[8:9], v[8:9], v[142:143]
	v_cvt_pk_bf16_f32 v140, v6, v7
	v_cvt_pk_bf16_f32 v141, v8, v9
	v_mul_f32_e32 v142, v6, v6
	v_fmac_f32_e32 v142, v7, v7
	v_fmac_f32_e32 v142, v8, v8
	v_fmac_f32_e32 v142, v9, v9
	s_waitcnt vmcnt(13) lgkmcnt(13)
	v_pk_add_f32 v[10:11], v[10:11], v[144:145]
	v_pk_add_f32 v[12:13], v[12:13], v[146:147]
	v_cvt_pk_bf16_f32 v144, v10, v11
	v_cvt_pk_bf16_f32 v145, v12, v13
	v_mul_f32_e32 v146, v10, v10
	v_fmac_f32_e32 v146, v11, v11
	v_fmac_f32_e32 v146, v12, v12
	v_fmac_f32_e32 v146, v13, v13
	s_waitcnt vmcnt(12) lgkmcnt(12)
	v_pk_add_f32 v[14:15], v[14:15], v[148:149]
	v_pk_add_f32 v[16:17], v[16:17], v[150:151]
	v_cvt_pk_bf16_f32 v148, v14, v15
	v_cvt_pk_bf16_f32 v149, v16, v17
	v_mul_f32_e32 v150, v14, v14
	v_fmac_f32_e32 v150, v15, v15
	v_fmac_f32_e32 v150, v16, v16
	v_fmac_f32_e32 v150, v17, v17
	s_waitcnt vmcnt(11) lgkmcnt(11)
	v_pk_add_f32 v[18:19], v[18:19], v[172:173]
	v_pk_add_f32 v[20:21], v[20:21], v[174:175]
	v_cvt_pk_bf16_f32 v172, v18, v19
	v_cvt_pk_bf16_f32 v173, v20, v21
	v_mul_f32_e32 v174, v18, v18
	v_fmac_f32_e32 v174, v19, v19
	v_fmac_f32_e32 v174, v20, v20
	v_fmac_f32_e32 v174, v21, v21
	s_waitcnt vmcnt(10) lgkmcnt(10)
	v_pk_add_f32 v[22:23], v[22:23], v[176:177]
	v_pk_add_f32 v[24:25], v[24:25], v[178:179]
	v_cvt_pk_bf16_f32 v176, v22, v23
	v_cvt_pk_bf16_f32 v177, v24, v25
	v_mul_f32_e32 v178, v22, v22
	v_fmac_f32_e32 v178, v23, v23
	v_fmac_f32_e32 v178, v24, v24
	v_fmac_f32_e32 v178, v25, v25
	s_waitcnt vmcnt(9) lgkmcnt(9)
	v_pk_add_f32 v[26:27], v[26:27], v[180:181]
	v_pk_add_f32 v[28:29], v[28:29], v[182:183]
	v_cvt_pk_bf16_f32 v180, v26, v27
	v_cvt_pk_bf16_f32 v181, v28, v29
	v_mul_f32_e32 v182, v26, v26
	v_fmac_f32_e32 v182, v27, v27
	v_fmac_f32_e32 v182, v28, v28
	v_fmac_f32_e32 v182, v29, v29
	s_waitcnt vmcnt(8) lgkmcnt(8)
	v_pk_add_f32 v[30:31], v[30:31], v[184:185]
	v_pk_add_f32 v[32:33], v[32:33], v[186:187]
	v_cvt_pk_bf16_f32 v184, v30, v31
	v_cvt_pk_bf16_f32 v185, v32, v33
	v_mul_f32_e32 v186, v30, v30
	v_fmac_f32_e32 v186, v31, v31
	v_fmac_f32_e32 v186, v32, v32
	v_fmac_f32_e32 v186, v33, v33
	s_waitcnt vmcnt(7) lgkmcnt(7)
	v_pk_add_f32 v[34:35], v[34:35], v[188:189]
	v_pk_add_f32 v[36:37], v[36:37], v[190:191]
	v_cvt_pk_bf16_f32 v188, v34, v35
	v_cvt_pk_bf16_f32 v189, v36, v37
	v_mul_f32_e32 v190, v34, v34
	v_fmac_f32_e32 v190, v35, v35
	v_fmac_f32_e32 v190, v36, v36
	v_fmac_f32_e32 v190, v37, v37
	s_waitcnt vmcnt(6) lgkmcnt(6)
	v_pk_add_f32 v[38:39], v[38:39], v[196:197]
	v_pk_add_f32 v[40:41], v[40:41], v[198:199]
	v_cvt_pk_bf16_f32 v196, v38, v39
	v_cvt_pk_bf16_f32 v197, v40, v41
	v_mul_f32_e32 v198, v38, v38
	v_fmac_f32_e32 v198, v39, v39
	v_fmac_f32_e32 v198, v40, v40
	v_fmac_f32_e32 v198, v41, v41
	s_waitcnt vmcnt(5) lgkmcnt(5)
	v_pk_add_f32 v[42:43], v[42:43], v[200:201]
	v_pk_add_f32 v[44:45], v[44:45], v[202:203]
	v_cvt_pk_bf16_f32 v200, v42, v43
	v_cvt_pk_bf16_f32 v201, v44, v45
	v_mul_f32_e32 v202, v42, v42
	v_fmac_f32_e32 v202, v43, v43
	v_fmac_f32_e32 v202, v44, v44
	v_fmac_f32_e32 v202, v45, v45
	s_waitcnt vmcnt(4) lgkmcnt(4)
	v_pk_add_f32 v[46:47], v[46:47], v[204:205]
	v_pk_add_f32 v[48:49], v[48:49], v[206:207]
	v_cvt_pk_bf16_f32 v204, v46, v47
	v_cvt_pk_bf16_f32 v205, v48, v49
	v_mul_f32_e32 v206, v46, v46
	v_fmac_f32_e32 v206, v47, v47
	v_fmac_f32_e32 v206, v48, v48
	v_fmac_f32_e32 v206, v49, v49
	s_waitcnt vmcnt(3) lgkmcnt(3)
	v_pk_add_f32 v[50:51], v[50:51], v[212:213]
	v_pk_add_f32 v[52:53], v[52:53], v[214:215]
	v_cvt_pk_bf16_f32 v212, v50, v51
	v_cvt_pk_bf16_f32 v213, v52, v53
	v_mul_f32_e32 v214, v50, v50
	v_fmac_f32_e32 v214, v51, v51
	v_fmac_f32_e32 v214, v52, v52
	v_fmac_f32_e32 v214, v53, v53
	s_waitcnt vmcnt(2) lgkmcnt(2)
	v_pk_add_f32 v[54:55], v[54:55], v[216:217]
	v_pk_add_f32 v[56:57], v[56:57], v[218:219]
	v_cvt_pk_bf16_f32 v216, v54, v55
	v_cvt_pk_bf16_f32 v217, v56, v57
	v_mul_f32_e32 v218, v54, v54
	v_fmac_f32_e32 v218, v55, v55
	v_fmac_f32_e32 v218, v56, v56
	v_fmac_f32_e32 v218, v57, v57
	s_waitcnt vmcnt(1) lgkmcnt(1)
	v_pk_add_f32 v[58:59], v[58:59], v[220:221]
	v_pk_add_f32 v[60:61], v[60:61], v[222:223]
	v_cvt_pk_bf16_f32 v220, v58, v59
	v_cvt_pk_bf16_f32 v221, v60, v61
	v_mul_f32_e32 v222, v58, v58
	v_fmac_f32_e32 v222, v59, v59
	v_fmac_f32_e32 v222, v60, v60
	v_fmac_f32_e32 v222, v61, v61
	s_waitcnt vmcnt(0) lgkmcnt(0)
	v_pk_add_f32 v[62:63], v[62:63], v[224:225]
	v_pk_add_f32 v[64:65], v[64:65], v[226:227]
	v_cvt_pk_bf16_f32 v224, v62, v63
	v_cvt_pk_bf16_f32 v225, v64, v65
	v_mul_f32_e32 v226, v62, v62
	v_fmac_f32_e32 v226, v63, v63
	v_fmac_f32_e32 v226, v64, v64
	v_fmac_f32_e32 v226, v65, v65
	s_mov_b32 s56, s58
	s_mov_b32 s57, s59
	s_mov_b32 s40, s46
	s_mov_b32 s41, s47
	global_store_dwordx4 v240, v[2:5], s[56:57]
	global_store_dwordx2 v244, v[136:137], s[40:41]
	s_add_u32 s56, s56, 0x10000
	s_addc_u32 s57, s57, 0
	s_add_u32 s40, s40, 0x8400
	s_addc_u32 s41, s41, 0
	global_store_dwordx4 v240, v[6:9], s[56:57]
	global_store_dwordx2 v244, v[140:141], s[40:41]
	s_add_u32 s56, s56, 0x10000
	s_addc_u32 s57, s57, 0
	s_add_u32 s40, s40, 0x8400
	s_addc_u32 s41, s41, 0
	global_store_dwordx4 v240, v[10:13], s[56:57]
	global_store_dwordx2 v244, v[144:145], s[40:41]
	s_add_u32 s56, s56, 0x10000
	s_addc_u32 s57, s57, 0
	s_add_u32 s40, s40, 0x8400
	s_addc_u32 s41, s41, 0
	global_store_dwordx4 v240, v[14:17], s[56:57]
	global_store_dwordx2 v244, v[148:149], s[40:41]
	s_add_u32 s56, s56, 0x10000
	s_addc_u32 s57, s57, 0
	s_add_u32 s40, s40, 0x8400
	s_addc_u32 s41, s41, 0
	global_store_dwordx4 v240, v[18:21], s[56:57]
	global_store_dwordx2 v244, v[172:173], s[40:41]
	s_add_u32 s56, s56, 0x10000
	s_addc_u32 s57, s57, 0
	s_add_u32 s40, s40, 0x8400
	s_addc_u32 s41, s41, 0
	global_store_dwordx4 v240, v[22:25], s[56:57]
	global_store_dwordx2 v244, v[176:177], s[40:41]
	s_add_u32 s56, s56, 0x10000
	s_addc_u32 s57, s57, 0
	s_add_u32 s40, s40, 0x8400
	s_addc_u32 s41, s41, 0
	global_store_dwordx4 v240, v[26:29], s[56:57]
	global_store_dwordx2 v244, v[180:181], s[40:41]
	s_add_u32 s56, s56, 0x10000
	s_addc_u32 s57, s57, 0
	s_add_u32 s40, s40, 0x8400
	s_addc_u32 s41, s41, 0
	global_store_dwordx4 v240, v[30:33], s[56:57]
	global_store_dwordx2 v244, v[184:185], s[40:41]
	s_add_u32 s56, s56, 0x10000
	s_addc_u32 s57, s57, 0
	s_add_u32 s40, s40, 0x8400
	s_addc_u32 s41, s41, 0
	global_store_dwordx4 v240, v[34:37], s[56:57]
	global_store_dwordx2 v244, v[188:189], s[40:41]
	s_add_u32 s56, s56, 0x10000
	s_addc_u32 s57, s57, 0
	s_add_u32 s40, s40, 0x8400
	s_addc_u32 s41, s41, 0
	global_store_dwordx4 v240, v[38:41], s[56:57]
	global_store_dwordx2 v244, v[196:197], s[40:41]
	s_add_u32 s56, s56, 0x10000
	s_addc_u32 s57, s57, 0
	s_add_u32 s40, s40, 0x8400
	s_addc_u32 s41, s41, 0
	global_store_dwordx4 v240, v[42:45], s[56:57]
	global_store_dwordx2 v244, v[200:201], s[40:41]
	s_add_u32 s56, s56, 0x10000
	s_addc_u32 s57, s57, 0
	s_add_u32 s40, s40, 0x8400
	s_addc_u32 s41, s41, 0
	global_store_dwordx4 v240, v[46:49], s[56:57]
	global_store_dwordx2 v244, v[204:205], s[40:41]
	s_add_u32 s56, s56, 0x10000
	s_addc_u32 s57, s57, 0
	s_add_u32 s40, s40, 0x8400
	s_addc_u32 s41, s41, 0
	global_store_dwordx4 v240, v[50:53], s[56:57]
	global_store_dwordx2 v244, v[212:213], s[40:41]
	s_add_u32 s56, s56, 0x10000
	s_addc_u32 s57, s57, 0
	s_add_u32 s40, s40, 0x8400
	s_addc_u32 s41, s41, 0
	global_store_dwordx4 v240, v[54:57], s[56:57]
	global_store_dwordx2 v244, v[216:217], s[40:41]
	s_add_u32 s56, s56, 0x10000
	s_addc_u32 s57, s57, 0
	s_add_u32 s40, s40, 0x8400
	s_addc_u32 s41, s41, 0
	global_store_dwordx4 v240, v[58:61], s[56:57]
	global_store_dwordx2 v244, v[220:221], s[40:41]
	s_add_u32 s56, s56, 0x10000
	s_addc_u32 s57, s57, 0
	s_add_u32 s40, s40, 0x8400
	s_addc_u32 s41, s41, 0
	global_store_dwordx4 v240, v[62:65], s[56:57]
	global_store_dwordx2 v244, v[224:225], s[40:41]
	v_add_f32_dpp v138, v138, v138 quad_perm:[1,0,3,2] row_mask:0xf bank_mask:0xf
	v_add_f32_dpp v142, v142, v142 quad_perm:[1,0,3,2] row_mask:0xf bank_mask:0xf
	v_add_f32_dpp v146, v146, v146 quad_perm:[1,0,3,2] row_mask:0xf bank_mask:0xf
	v_add_f32_dpp v150, v150, v150 quad_perm:[1,0,3,2] row_mask:0xf bank_mask:0xf
	v_add_f32_dpp v174, v174, v174 quad_perm:[1,0,3,2] row_mask:0xf bank_mask:0xf
	v_add_f32_dpp v178, v178, v178 quad_perm:[1,0,3,2] row_mask:0xf bank_mask:0xf
	v_add_f32_dpp v182, v182, v182 quad_perm:[1,0,3,2] row_mask:0xf bank_mask:0xf
	v_add_f32_dpp v186, v186, v186 quad_perm:[1,0,3,2] row_mask:0xf bank_mask:0xf
	v_add_f32_dpp v190, v190, v190 quad_perm:[1,0,3,2] row_mask:0xf bank_mask:0xf
	v_add_f32_dpp v198, v198, v198 quad_perm:[1,0,3,2] row_mask:0xf bank_mask:0xf
	v_add_f32_dpp v202, v202, v202 quad_perm:[1,0,3,2] row_mask:0xf bank_mask:0xf
	v_add_f32_dpp v206, v206, v206 quad_perm:[1,0,3,2] row_mask:0xf bank_mask:0xf
	v_add_f32_dpp v214, v214, v214 quad_perm:[1,0,3,2] row_mask:0xf bank_mask:0xf
	v_add_f32_dpp v218, v218, v218 quad_perm:[1,0,3,2] row_mask:0xf bank_mask:0xf
	v_add_f32_dpp v222, v222, v222 quad_perm:[1,0,3,2] row_mask:0xf bank_mask:0xf
	v_add_f32_dpp v226, v226, v226 quad_perm:[1,0,3,2] row_mask:0xf bank_mask:0xf
	v_add_f32_dpp v138, v138, v138 quad_perm:[2,3,0,1] row_mask:0xf bank_mask:0xf
	v_add_f32_dpp v142, v142, v142 quad_perm:[2,3,0,1] row_mask:0xf bank_mask:0xf
	v_add_f32_dpp v146, v146, v146 quad_perm:[2,3,0,1] row_mask:0xf bank_mask:0xf
	v_add_f32_dpp v150, v150, v150 quad_perm:[2,3,0,1] row_mask:0xf bank_mask:0xf
	v_add_f32_dpp v174, v174, v174 quad_perm:[2,3,0,1] row_mask:0xf bank_mask:0xf
	v_add_f32_dpp v178, v178, v178 quad_perm:[2,3,0,1] row_mask:0xf bank_mask:0xf
	v_add_f32_dpp v182, v182, v182 quad_perm:[2,3,0,1] row_mask:0xf bank_mask:0xf
	v_add_f32_dpp v186, v186, v186 quad_perm:[2,3,0,1] row_mask:0xf bank_mask:0xf
	v_add_f32_dpp v190, v190, v190 quad_perm:[2,3,0,1] row_mask:0xf bank_mask:0xf
	v_add_f32_dpp v198, v198, v198 quad_perm:[2,3,0,1] row_mask:0xf bank_mask:0xf
	v_add_f32_dpp v202, v202, v202 quad_perm:[2,3,0,1] row_mask:0xf bank_mask:0xf
	v_add_f32_dpp v206, v206, v206 quad_perm:[2,3,0,1] row_mask:0xf bank_mask:0xf
	v_add_f32_dpp v214, v214, v214 quad_perm:[2,3,0,1] row_mask:0xf bank_mask:0xf
	v_add_f32_dpp v218, v218, v218 quad_perm:[2,3,0,1] row_mask:0xf bank_mask:0xf
	v_add_f32_dpp v222, v222, v222 quad_perm:[2,3,0,1] row_mask:0xf bank_mask:0xf
	v_add_f32_dpp v226, v226, v226 quad_perm:[2,3,0,1] row_mask:0xf bank_mask:0xf
	v_add_f32_dpp v138, v138, v138 row_half_mirror row_mask:0xf bank_mask:0xf
	v_add_f32_dpp v142, v142, v142 row_half_mirror row_mask:0xf bank_mask:0xf
	v_add_f32_dpp v146, v146, v146 row_half_mirror row_mask:0xf bank_mask:0xf
	v_add_f32_dpp v150, v150, v150 row_half_mirror row_mask:0xf bank_mask:0xf
	v_add_f32_dpp v174, v174, v174 row_half_mirror row_mask:0xf bank_mask:0xf
	v_add_f32_dpp v178, v178, v178 row_half_mirror row_mask:0xf bank_mask:0xf
	v_add_f32_dpp v182, v182, v182 row_half_mirror row_mask:0xf bank_mask:0xf
	v_add_f32_dpp v186, v186, v186 row_half_mirror row_mask:0xf bank_mask:0xf
	v_add_f32_dpp v190, v190, v190 row_half_mirror row_mask:0xf bank_mask:0xf
	v_add_f32_dpp v198, v198, v198 row_half_mirror row_mask:0xf bank_mask:0xf
	v_add_f32_dpp v202, v202, v202 row_half_mirror row_mask:0xf bank_mask:0xf
	v_add_f32_dpp v206, v206, v206 row_half_mirror row_mask:0xf bank_mask:0xf
	v_add_f32_dpp v214, v214, v214 row_half_mirror row_mask:0xf bank_mask:0xf
	v_add_f32_dpp v218, v218, v218 row_half_mirror row_mask:0xf bank_mask:0xf
	v_add_f32_dpp v222, v222, v222 row_half_mirror row_mask:0xf bank_mask:0xf
	v_add_f32_dpp v226, v226, v226 row_half_mirror row_mask:0xf bank_mask:0xf
	v_add_f32_dpp v138, v138, v138 row_mirror row_mask:0xf bank_mask:0xf
	v_add_f32_dpp v142, v142, v142 row_mirror row_mask:0xf bank_mask:0xf
	v_add_f32_dpp v146, v146, v146 row_mirror row_mask:0xf bank_mask:0xf
	v_add_f32_dpp v150, v150, v150 row_mirror row_mask:0xf bank_mask:0xf
	v_add_f32_dpp v174, v174, v174 row_mirror row_mask:0xf bank_mask:0xf
	v_add_f32_dpp v178, v178, v178 row_mirror row_mask:0xf bank_mask:0xf
	v_add_f32_dpp v182, v182, v182 row_mirror row_mask:0xf bank_mask:0xf
	v_add_f32_dpp v186, v186, v186 row_mirror row_mask:0xf bank_mask:0xf
	v_add_f32_dpp v190, v190, v190 row_mirror row_mask:0xf bank_mask:0xf
	v_add_f32_dpp v198, v198, v198 row_mirror row_mask:0xf bank_mask:0xf
	v_add_f32_dpp v202, v202, v202 row_mirror row_mask:0xf bank_mask:0xf
	v_add_f32_dpp v206, v206, v206 row_mirror row_mask:0xf bank_mask:0xf
	v_add_f32_dpp v214, v214, v214 row_mirror row_mask:0xf bank_mask:0xf
	v_add_f32_dpp v218, v218, v218 row_mirror row_mask:0xf bank_mask:0xf
	v_add_f32_dpp v222, v222, v222 row_mirror row_mask:0xf bank_mask:0xf
	v_add_f32_dpp v226, v226, v226 row_mirror row_mask:0xf bank_mask:0xf
	v_add_f32_dpp v138, v138, v138 row_bcast:15 row_mask:0xa bank_mask:0xf
	v_add_f32_dpp v142, v142, v142 row_bcast:15 row_mask:0xa bank_mask:0xf
	v_add_f32_dpp v146, v146, v146 row_bcast:15 row_mask:0xa bank_mask:0xf
	v_add_f32_dpp v150, v150, v150 row_bcast:15 row_mask:0xa bank_mask:0xf
	v_add_f32_dpp v174, v174, v174 row_bcast:15 row_mask:0xa bank_mask:0xf
	v_add_f32_dpp v178, v178, v178 row_bcast:15 row_mask:0xa bank_mask:0xf
	v_add_f32_dpp v182, v182, v182 row_bcast:15 row_mask:0xa bank_mask:0xf
	v_add_f32_dpp v186, v186, v186 row_bcast:15 row_mask:0xa bank_mask:0xf
	v_add_f32_dpp v190, v190, v190 row_bcast:15 row_mask:0xa bank_mask:0xf
	v_add_f32_dpp v198, v198, v198 row_bcast:15 row_mask:0xa bank_mask:0xf
	v_add_f32_dpp v202, v202, v202 row_bcast:15 row_mask:0xa bank_mask:0xf
	v_add_f32_dpp v206, v206, v206 row_bcast:15 row_mask:0xa bank_mask:0xf
	v_add_f32_dpp v214, v214, v214 row_bcast:15 row_mask:0xa bank_mask:0xf
	v_add_f32_dpp v218, v218, v218 row_bcast:15 row_mask:0xa bank_mask:0xf
	v_add_f32_dpp v222, v222, v222 row_bcast:15 row_mask:0xa bank_mask:0xf
	v_add_f32_dpp v226, v226, v226 row_bcast:15 row_mask:0xa bank_mask:0xf
	s_mov_b32 exec_lo, 0x10000
	s_mov_b32 exec_hi, 0x10000
	global_atomic_add_f32 v245, v138, s[48:49]
	global_atomic_add_f32 v245, v142, s[48:49] offset:32
	global_atomic_add_f32 v245, v146, s[48:49] offset:64
	global_atomic_add_f32 v245, v150, s[48:49] offset:96
	global_atomic_add_f32 v245, v174, s[48:49] offset:128
	global_atomic_add_f32 v245, v178, s[48:49] offset:160
	global_atomic_add_f32 v245, v182, s[48:49] offset:192
	global_atomic_add_f32 v245, v186, s[48:49] offset:224
	global_atomic_add_f32 v245, v190, s[48:49] offset:256
	global_atomic_add_f32 v245, v198, s[48:49] offset:288
	global_atomic_add_f32 v245, v202, s[48:49] offset:320
	global_atomic_add_f32 v245, v206, s[48:49] offset:352
	global_atomic_add_f32 v245, v214, s[48:49] offset:384
	global_atomic_add_f32 v245, v218, s[48:49] offset:416
	global_atomic_add_f32 v245, v222, s[48:49] offset:448
	global_atomic_add_f32 v245, v226, s[48:49] offset:480
	s_mov_b64 exec, -1
	s_add_u32 s44, s44, 0x1000
	s_addc_u32 s45, s45, 0
	s_add_u32 s58, s58, 0x1000
	s_addc_u32 s59, s59, 0
	s_add_u32 s46, s46, 0x800
	s_addc_u32 s47, s47, 0
	s_waitcnt lgkmcnt(0)
	s_barrier
	s_mov_b32 s56, s44
	s_mov_b32 s57, s45
	global_load_dwordx4 v[136:139], v240, s[56:57]
	s_add_u32 s56, s56, 0x10000
	s_addc_u32 s57, s57, 0
	global_load_dwordx4 v[140:143], v240, s[56:57]
	s_add_u32 s56, s56, 0x10000
	s_addc_u32 s57, s57, 0
	global_load_dwordx4 v[144:147], v240, s[56:57]
	s_add_u32 s56, s56, 0x10000
	s_addc_u32 s57, s57, 0
	global_load_dwordx4 v[148:151], v240, s[56:57]
	s_add_u32 s56, s56, 0x10000
	s_addc_u32 s57, s57, 0
	global_load_dwordx4 v[172:175], v240, s[56:57]
	s_add_u32 s56, s56, 0x10000
	s_addc_u32 s57, s57, 0
	global_load_dwordx4 v[176:179], v240, s[56:57]
	s_add_u32 s56, s56, 0x10000
	s_addc_u32 s57, s57, 0
	global_load_dwordx4 v[180:183], v240, s[56:57]
	s_add_u32 s56, s56, 0x10000
	s_addc_u32 s57, s57, 0
	global_load_dwordx4 v[184:187], v240, s[56:57]
	s_add_u32 s56, s56, 0x10000
	s_addc_u32 s57, s57, 0
	global_load_dwordx4 v[188:191], v240, s[56:57]
	s_add_u32 s56, s56, 0x10000
	s_addc_u32 s57, s57, 0
	global_load_dwordx4 v[196:199], v240, s[56:57]
	s_add_u32 s56, s56, 0x10000
	s_addc_u32 s57, s57, 0
	global_load_dwordx4 v[200:203], v240, s[56:57]
	s_add_u32 s56, s56, 0x10000
	s_addc_u32 s57, s57, 0
	global_load_dwordx4 v[204:207], v240, s[56:57]
	s_add_u32 s56, s56, 0x10000
	s_addc_u32 s57, s57, 0
	global_load_dwordx4 v[212:215], v240, s[56:57]
	s_add_u32 s56, s56, 0x10000
	s_addc_u32 s57, s57, 0
	global_load_dwordx4 v[216:219], v240, s[56:57]
	s_add_u32 s56, s56, 0x10000
	s_addc_u32 s57, s57, 0
	global_load_dwordx4 v[220:223], v240, s[56:57]
	s_add_u32 s56, s56, 0x10000
	s_addc_u32 s57, s57, 0
	global_load_dwordx4 v[224:227], v240, s[56:57]
	ds_write_b32 v238, v66
	ds_write_b32 v238, v67 offset:528
	ds_write_b32 v238, v68 offset:1056
	ds_write_b32 v238, v69 offset:1584
	ds_write_b32 v238, v70 offset:64
	ds_write_b32 v238, v71 offset:592
	ds_write_b32 v238, v72 offset:1120
	ds_write_b32 v238, v73 offset:1648
	ds_write_b32 v238, v74 offset:128
	ds_write_b32 v238, v75 offset:656
	ds_write_b32 v238, v76 offset:1184
	ds_write_b32 v238, v77 offset:1712
	ds_write_b32 v238, v78 offset:192
	ds_write_b32 v238, v79 offset:720
	ds_write_b32 v238, v80 offset:1248
	ds_write_b32 v238, v81 offset:1776
	ds_write_b32 v238, v82 offset:8448
	ds_write_b32 v238, v83 offset:8976
	ds_write_b32 v238, v84 offset:9504
	ds_write_b32 v238, v85 offset:10032
	ds_write_b32 v238, v86 offset:8512
	ds_write_b32 v238, v87 offset:9040
	ds_write_b32 v238, v88 offset:9568
	ds_write_b32 v238, v89 offset:10096
	ds_write_b32 v238, v90 offset:8576
	ds_write_b32 v238, v91 offset:9104
	ds_write_b32 v238, v92 offset:9632
	ds_write_b32 v238, v93 offset:10160
	ds_write_b32 v238, v94 offset:8640
	ds_write_b32 v238, v95 offset:9168
	ds_write_b32 v238, v96 offset:9696
	ds_write_b32 v238, v97 offset:10224
	ds_write_b32 v238, v98 offset:16896
	ds_write_b32 v238, v99 offset:17424
	ds_write_b32 v238, v100 offset:17952
	ds_write_b32 v238, v101 offset:18480
	ds_write_b32 v238, v102 offset:16960
	ds_write_b32 v238, v103 offset:17488
	ds_write_b32 v238, v104 offset:18016
	ds_write_b32 v238, v105 offset:18544
	ds_write_b32 v238, v106 offset:17024
	ds_write_b32 v238, v107 offset:17552
	ds_write_b32 v238, v108 offset:18080
	ds_write_b32 v238, v109 offset:18608
	ds_write_b32 v238, v110 offset:17088
	ds_write_b32 v238, v111 offset:17616
	ds_write_b32 v238, v112 offset:18144
	ds_write_b32 v238, v113 offset:18672
	ds_write_b32 v238, v114 offset:25344
	ds_write_b32 v238, v115 offset:25872
	ds_write_b32 v238, v116 offset:26400
	ds_write_b32 v238, v117 offset:26928
	ds_write_b32 v238, v118 offset:25408
	ds_write_b32 v238, v119 offset:25936
	ds_write_b32 v238, v120 offset:26464
	ds_write_b32 v238, v121 offset:26992
	ds_write_b32 v238, v122 offset:25472
	ds_write_b32 v238, v123 offset:26000
	ds_write_b32 v238, v124 offset:26528
	ds_write_b32 v238, v125 offset:27056
	ds_write_b32 v238, v126 offset:25536
	ds_write_b32 v238, v127 offset:26064
	ds_write_b32 v238, v128 offset:26592
	ds_write_b32 v238, v129 offset:27120
	s_waitcnt lgkmcnt(0)
	s_barrier
	ds_read_b128 v[66:69], v239
	ds_read_b128 v[70:73], v239 offset:4224
	ds_read_b128 v[74:77], v239 offset:8448
	ds_read_b128 v[78:81], v239 offset:12672
	ds_read_b128 v[82:85], v239 offset:16896
	ds_read_b128 v[86:89], v239 offset:21120
	ds_read_b128 v[90:93], v239 offset:25344
	ds_read_b128 v[94:97], v239 offset:29568
	ds_read_b128 v[98:101], v239 offset:33792
	ds_read_b128 v[102:105], v239 offset:38016
	ds_read_b128 v[106:109], v239 offset:42240
	ds_read_b128 v[110:113], v239 offset:46464
	ds_read_b128 v[114:117], v239 offset:50688
	ds_read_b128 v[118:121], v239 offset:54912
	ds_read_b128 v[122:125], v239 offset:59136
	ds_read_b128 v[126:129], v239 offset:63360
	s_waitcnt vmcnt(15) lgkmcnt(15)
	v_pk_add_f32 v[66:67], v[66:67], v[136:137]
	v_pk_add_f32 v[68:69], v[68:69], v[138:139]
	v_cvt_pk_bf16_f32 v136, v66, v67
	v_cvt_pk_bf16_f32 v137, v68, v69
	v_mul_f32_e32 v138, v66, v66
	v_fmac_f32_e32 v138, v67, v67
	v_fmac_f32_e32 v138, v68, v68
	v_fmac_f32_e32 v138, v69, v69
	s_waitcnt vmcnt(14) lgkmcnt(14)
	v_pk_add_f32 v[70:71], v[70:71], v[140:141]
	v_pk_add_f32 v[72:73], v[72:73], v[142:143]
	v_cvt_pk_bf16_f32 v140, v70, v71
	v_cvt_pk_bf16_f32 v141, v72, v73
	v_mul_f32_e32 v142, v70, v70
	v_fmac_f32_e32 v142, v71, v71
	v_fmac_f32_e32 v142, v72, v72
	v_fmac_f32_e32 v142, v73, v73
	s_waitcnt vmcnt(13) lgkmcnt(13)
	v_pk_add_f32 v[74:75], v[74:75], v[144:145]
	v_pk_add_f32 v[76:77], v[76:77], v[146:147]
	v_cvt_pk_bf16_f32 v144, v74, v75
	v_cvt_pk_bf16_f32 v145, v76, v77
	v_mul_f32_e32 v146, v74, v74
	v_fmac_f32_e32 v146, v75, v75
	v_fmac_f32_e32 v146, v76, v76
	v_fmac_f32_e32 v146, v77, v77
	s_waitcnt vmcnt(12) lgkmcnt(12)
	v_pk_add_f32 v[78:79], v[78:79], v[148:149]
	v_pk_add_f32 v[80:81], v[80:81], v[150:151]
	v_cvt_pk_bf16_f32 v148, v78, v79
	v_cvt_pk_bf16_f32 v149, v80, v81
	v_mul_f32_e32 v150, v78, v78
	v_fmac_f32_e32 v150, v79, v79
	v_fmac_f32_e32 v150, v80, v80
	v_fmac_f32_e32 v150, v81, v81
	s_waitcnt vmcnt(11) lgkmcnt(11)
	v_pk_add_f32 v[82:83], v[82:83], v[172:173]
	v_pk_add_f32 v[84:85], v[84:85], v[174:175]
	v_cvt_pk_bf16_f32 v172, v82, v83
	v_cvt_pk_bf16_f32 v173, v84, v85
	v_mul_f32_e32 v174, v82, v82
	v_fmac_f32_e32 v174, v83, v83
	v_fmac_f32_e32 v174, v84, v84
	v_fmac_f32_e32 v174, v85, v85
	s_waitcnt vmcnt(10) lgkmcnt(10)
	v_pk_add_f32 v[86:87], v[86:87], v[176:177]
	v_pk_add_f32 v[88:89], v[88:89], v[178:179]
	v_cvt_pk_bf16_f32 v176, v86, v87
	v_cvt_pk_bf16_f32 v177, v88, v89
	v_mul_f32_e32 v178, v86, v86
	v_fmac_f32_e32 v178, v87, v87
	v_fmac_f32_e32 v178, v88, v88
	v_fmac_f32_e32 v178, v89, v89
	s_waitcnt vmcnt(9) lgkmcnt(9)
	v_pk_add_f32 v[90:91], v[90:91], v[180:181]
	v_pk_add_f32 v[92:93], v[92:93], v[182:183]
	v_cvt_pk_bf16_f32 v180, v90, v91
	v_cvt_pk_bf16_f32 v181, v92, v93
	v_mul_f32_e32 v182, v90, v90
	v_fmac_f32_e32 v182, v91, v91
	v_fmac_f32_e32 v182, v92, v92
	v_fmac_f32_e32 v182, v93, v93
	s_waitcnt vmcnt(8) lgkmcnt(8)
	v_pk_add_f32 v[94:95], v[94:95], v[184:185]
	v_pk_add_f32 v[96:97], v[96:97], v[186:187]
	v_cvt_pk_bf16_f32 v184, v94, v95
	v_cvt_pk_bf16_f32 v185, v96, v97
	v_mul_f32_e32 v186, v94, v94
	v_fmac_f32_e32 v186, v95, v95
	v_fmac_f32_e32 v186, v96, v96
	v_fmac_f32_e32 v186, v97, v97
	s_waitcnt vmcnt(7) lgkmcnt(7)
	v_pk_add_f32 v[98:99], v[98:99], v[188:189]
	v_pk_add_f32 v[100:101], v[100:101], v[190:191]
	v_cvt_pk_bf16_f32 v188, v98, v99
	v_cvt_pk_bf16_f32 v189, v100, v101
	v_mul_f32_e32 v190, v98, v98
	v_fmac_f32_e32 v190, v99, v99
	v_fmac_f32_e32 v190, v100, v100
	v_fmac_f32_e32 v190, v101, v101
	s_waitcnt vmcnt(6) lgkmcnt(6)
	v_pk_add_f32 v[102:103], v[102:103], v[196:197]
	v_pk_add_f32 v[104:105], v[104:105], v[198:199]
	v_cvt_pk_bf16_f32 v196, v102, v103
	v_cvt_pk_bf16_f32 v197, v104, v105
	v_mul_f32_e32 v198, v102, v102
	v_fmac_f32_e32 v198, v103, v103
	v_fmac_f32_e32 v198, v104, v104
	v_fmac_f32_e32 v198, v105, v105
	s_waitcnt vmcnt(5) lgkmcnt(5)
	v_pk_add_f32 v[106:107], v[106:107], v[200:201]
	v_pk_add_f32 v[108:109], v[108:109], v[202:203]
	v_cvt_pk_bf16_f32 v200, v106, v107
	v_cvt_pk_bf16_f32 v201, v108, v109
	v_mul_f32_e32 v202, v106, v106
	v_fmac_f32_e32 v202, v107, v107
	v_fmac_f32_e32 v202, v108, v108
	v_fmac_f32_e32 v202, v109, v109
	s_waitcnt vmcnt(4) lgkmcnt(4)
	v_pk_add_f32 v[110:111], v[110:111], v[204:205]
	v_pk_add_f32 v[112:113], v[112:113], v[206:207]
	v_cvt_pk_bf16_f32 v204, v110, v111
	v_cvt_pk_bf16_f32 v205, v112, v113
	v_mul_f32_e32 v206, v110, v110
	v_fmac_f32_e32 v206, v111, v111
	v_fmac_f32_e32 v206, v112, v112
	v_fmac_f32_e32 v206, v113, v113
	s_waitcnt vmcnt(3) lgkmcnt(3)
	v_pk_add_f32 v[114:115], v[114:115], v[212:213]
	v_pk_add_f32 v[116:117], v[116:117], v[214:215]
	v_cvt_pk_bf16_f32 v212, v114, v115
	v_cvt_pk_bf16_f32 v213, v116, v117
	v_mul_f32_e32 v214, v114, v114
	v_fmac_f32_e32 v214, v115, v115
	v_fmac_f32_e32 v214, v116, v116
	v_fmac_f32_e32 v214, v117, v117
	s_waitcnt vmcnt(2) lgkmcnt(2)
	v_pk_add_f32 v[118:119], v[118:119], v[216:217]
	v_pk_add_f32 v[120:121], v[120:121], v[218:219]
	v_cvt_pk_bf16_f32 v216, v118, v119
	v_cvt_pk_bf16_f32 v217, v120, v121
	v_mul_f32_e32 v218, v118, v118
	v_fmac_f32_e32 v218, v119, v119
	v_fmac_f32_e32 v218, v120, v120
	v_fmac_f32_e32 v218, v121, v121
	s_waitcnt vmcnt(1) lgkmcnt(1)
	v_pk_add_f32 v[122:123], v[122:123], v[220:221]
	v_pk_add_f32 v[124:125], v[124:125], v[222:223]
	v_cvt_pk_bf16_f32 v220, v122, v123
	v_cvt_pk_bf16_f32 v221, v124, v125
	v_mul_f32_e32 v222, v122, v122
	v_fmac_f32_e32 v222, v123, v123
	v_fmac_f32_e32 v222, v124, v124
	v_fmac_f32_e32 v222, v125, v125
	s_waitcnt vmcnt(0) lgkmcnt(0)
	v_pk_add_f32 v[126:127], v[126:127], v[224:225]
	v_pk_add_f32 v[128:129], v[128:129], v[226:227]
	v_cvt_pk_bf16_f32 v224, v126, v127
	v_cvt_pk_bf16_f32 v225, v128, v129
	v_mul_f32_e32 v226, v126, v126
	v_fmac_f32_e32 v226, v127, v127
	v_fmac_f32_e32 v226, v128, v128
	v_fmac_f32_e32 v226, v129, v129
	s_mov_b32 s56, s58
	s_mov_b32 s57, s59
	s_mov_b32 s40, s46
	s_mov_b32 s41, s47
	global_store_dwordx4 v240, v[66:69], s[56:57]
	global_store_dwordx2 v244, v[136:137], s[40:41]
	s_add_u32 s56, s56, 0x10000
	s_addc_u32 s57, s57, 0
	s_add_u32 s40, s40, 0x8400
	s_addc_u32 s41, s41, 0
	global_store_dwordx4 v240, v[70:73], s[56:57]
	global_store_dwordx2 v244, v[140:141], s[40:41]
	s_add_u32 s56, s56, 0x10000
	s_addc_u32 s57, s57, 0
	s_add_u32 s40, s40, 0x8400
	s_addc_u32 s41, s41, 0
	global_store_dwordx4 v240, v[74:77], s[56:57]
	global_store_dwordx2 v244, v[144:145], s[40:41]
	s_add_u32 s56, s56, 0x10000
	s_addc_u32 s57, s57, 0
	s_add_u32 s40, s40, 0x8400
	s_addc_u32 s41, s41, 0
	global_store_dwordx4 v240, v[78:81], s[56:57]
	global_store_dwordx2 v244, v[148:149], s[40:41]
	s_add_u32 s56, s56, 0x10000
	s_addc_u32 s57, s57, 0
	s_add_u32 s40, s40, 0x8400
	s_addc_u32 s41, s41, 0
	global_store_dwordx4 v240, v[82:85], s[56:57]
	global_store_dwordx2 v244, v[172:173], s[40:41]
	s_add_u32 s56, s56, 0x10000
	s_addc_u32 s57, s57, 0
	s_add_u32 s40, s40, 0x8400
	s_addc_u32 s41, s41, 0
	global_store_dwordx4 v240, v[86:89], s[56:57]
	global_store_dwordx2 v244, v[176:177], s[40:41]
	s_add_u32 s56, s56, 0x10000
	s_addc_u32 s57, s57, 0
	s_add_u32 s40, s40, 0x8400
	s_addc_u32 s41, s41, 0
	global_store_dwordx4 v240, v[90:93], s[56:57]
	global_store_dwordx2 v244, v[180:181], s[40:41]
	s_add_u32 s56, s56, 0x10000
	s_addc_u32 s57, s57, 0
	s_add_u32 s40, s40, 0x8400
	s_addc_u32 s41, s41, 0
	global_store_dwordx4 v240, v[94:97], s[56:57]
	global_store_dwordx2 v244, v[184:185], s[40:41]
	s_add_u32 s56, s56, 0x10000
	s_addc_u32 s57, s57, 0
	s_add_u32 s40, s40, 0x8400
	s_addc_u32 s41, s41, 0
	global_store_dwordx4 v240, v[98:101], s[56:57]
	global_store_dwordx2 v244, v[188:189], s[40:41]
	s_add_u32 s56, s56, 0x10000
	s_addc_u32 s57, s57, 0
	s_add_u32 s40, s40, 0x8400
	s_addc_u32 s41, s41, 0
	global_store_dwordx4 v240, v[102:105], s[56:57]
	global_store_dwordx2 v244, v[196:197], s[40:41]
	s_add_u32 s56, s56, 0x10000
	s_addc_u32 s57, s57, 0
	s_add_u32 s40, s40, 0x8400
	s_addc_u32 s41, s41, 0
	global_store_dwordx4 v240, v[106:109], s[56:57]
	global_store_dwordx2 v244, v[200:201], s[40:41]
	s_add_u32 s56, s56, 0x10000
	s_addc_u32 s57, s57, 0
	s_add_u32 s40, s40, 0x8400
	s_addc_u32 s41, s41, 0
	global_store_dwordx4 v240, v[110:113], s[56:57]
	global_store_dwordx2 v244, v[204:205], s[40:41]
	s_add_u32 s56, s56, 0x10000
	s_addc_u32 s57, s57, 0
	s_add_u32 s40, s40, 0x8400
	s_addc_u32 s41, s41, 0
	global_store_dwordx4 v240, v[114:117], s[56:57]
	global_store_dwordx2 v244, v[212:213], s[40:41]
	s_add_u32 s56, s56, 0x10000
	s_addc_u32 s57, s57, 0
	s_add_u32 s40, s40, 0x8400
	s_addc_u32 s41, s41, 0
	global_store_dwordx4 v240, v[118:121], s[56:57]
	global_store_dwordx2 v244, v[216:217], s[40:41]
	s_add_u32 s56, s56, 0x10000
	s_addc_u32 s57, s57, 0
	s_add_u32 s40, s40, 0x8400
	s_addc_u32 s41, s41, 0
	global_store_dwordx4 v240, v[122:125], s[56:57]
	global_store_dwordx2 v244, v[220:221], s[40:41]
	s_add_u32 s56, s56, 0x10000
	s_addc_u32 s57, s57, 0
	s_add_u32 s40, s40, 0x8400
	s_addc_u32 s41, s41, 0
	global_store_dwordx4 v240, v[126:129], s[56:57]
	global_store_dwordx2 v244, v[224:225], s[40:41]
	v_add_f32_dpp v138, v138, v138 quad_perm:[1,0,3,2] row_mask:0xf bank_mask:0xf
	v_add_f32_dpp v142, v142, v142 quad_perm:[1,0,3,2] row_mask:0xf bank_mask:0xf
	v_add_f32_dpp v146, v146, v146 quad_perm:[1,0,3,2] row_mask:0xf bank_mask:0xf
	v_add_f32_dpp v150, v150, v150 quad_perm:[1,0,3,2] row_mask:0xf bank_mask:0xf
	v_add_f32_dpp v174, v174, v174 quad_perm:[1,0,3,2] row_mask:0xf bank_mask:0xf
	v_add_f32_dpp v178, v178, v178 quad_perm:[1,0,3,2] row_mask:0xf bank_mask:0xf
	v_add_f32_dpp v182, v182, v182 quad_perm:[1,0,3,2] row_mask:0xf bank_mask:0xf
	v_add_f32_dpp v186, v186, v186 quad_perm:[1,0,3,2] row_mask:0xf bank_mask:0xf
	v_add_f32_dpp v190, v190, v190 quad_perm:[1,0,3,2] row_mask:0xf bank_mask:0xf
	v_add_f32_dpp v198, v198, v198 quad_perm:[1,0,3,2] row_mask:0xf bank_mask:0xf
	v_add_f32_dpp v202, v202, v202 quad_perm:[1,0,3,2] row_mask:0xf bank_mask:0xf
	v_add_f32_dpp v206, v206, v206 quad_perm:[1,0,3,2] row_mask:0xf bank_mask:0xf
	v_add_f32_dpp v214, v214, v214 quad_perm:[1,0,3,2] row_mask:0xf bank_mask:0xf
	v_add_f32_dpp v218, v218, v218 quad_perm:[1,0,3,2] row_mask:0xf bank_mask:0xf
	v_add_f32_dpp v222, v222, v222 quad_perm:[1,0,3,2] row_mask:0xf bank_mask:0xf
	v_add_f32_dpp v226, v226, v226 quad_perm:[1,0,3,2] row_mask:0xf bank_mask:0xf
	v_add_f32_dpp v138, v138, v138 quad_perm:[2,3,0,1] row_mask:0xf bank_mask:0xf
	v_add_f32_dpp v142, v142, v142 quad_perm:[2,3,0,1] row_mask:0xf bank_mask:0xf
	v_add_f32_dpp v146, v146, v146 quad_perm:[2,3,0,1] row_mask:0xf bank_mask:0xf
	v_add_f32_dpp v150, v150, v150 quad_perm:[2,3,0,1] row_mask:0xf bank_mask:0xf
	v_add_f32_dpp v174, v174, v174 quad_perm:[2,3,0,1] row_mask:0xf bank_mask:0xf
	v_add_f32_dpp v178, v178, v178 quad_perm:[2,3,0,1] row_mask:0xf bank_mask:0xf
	v_add_f32_dpp v182, v182, v182 quad_perm:[2,3,0,1] row_mask:0xf bank_mask:0xf
	v_add_f32_dpp v186, v186, v186 quad_perm:[2,3,0,1] row_mask:0xf bank_mask:0xf
	v_add_f32_dpp v190, v190, v190 quad_perm:[2,3,0,1] row_mask:0xf bank_mask:0xf
	v_add_f32_dpp v198, v198, v198 quad_perm:[2,3,0,1] row_mask:0xf bank_mask:0xf
	v_add_f32_dpp v202, v202, v202 quad_perm:[2,3,0,1] row_mask:0xf bank_mask:0xf
	v_add_f32_dpp v206, v206, v206 quad_perm:[2,3,0,1] row_mask:0xf bank_mask:0xf
	v_add_f32_dpp v214, v214, v214 quad_perm:[2,3,0,1] row_mask:0xf bank_mask:0xf
	v_add_f32_dpp v218, v218, v218 quad_perm:[2,3,0,1] row_mask:0xf bank_mask:0xf
	v_add_f32_dpp v222, v222, v222 quad_perm:[2,3,0,1] row_mask:0xf bank_mask:0xf
	v_add_f32_dpp v226, v226, v226 quad_perm:[2,3,0,1] row_mask:0xf bank_mask:0xf
	v_add_f32_dpp v138, v138, v138 row_half_mirror row_mask:0xf bank_mask:0xf
	v_add_f32_dpp v142, v142, v142 row_half_mirror row_mask:0xf bank_mask:0xf
	v_add_f32_dpp v146, v146, v146 row_half_mirror row_mask:0xf bank_mask:0xf
	v_add_f32_dpp v150, v150, v150 row_half_mirror row_mask:0xf bank_mask:0xf
	v_add_f32_dpp v174, v174, v174 row_half_mirror row_mask:0xf bank_mask:0xf
	v_add_f32_dpp v178, v178, v178 row_half_mirror row_mask:0xf bank_mask:0xf
	v_add_f32_dpp v182, v182, v182 row_half_mirror row_mask:0xf bank_mask:0xf
	v_add_f32_dpp v186, v186, v186 row_half_mirror row_mask:0xf bank_mask:0xf
	v_add_f32_dpp v190, v190, v190 row_half_mirror row_mask:0xf bank_mask:0xf
	v_add_f32_dpp v198, v198, v198 row_half_mirror row_mask:0xf bank_mask:0xf
	v_add_f32_dpp v202, v202, v202 row_half_mirror row_mask:0xf bank_mask:0xf
	v_add_f32_dpp v206, v206, v206 row_half_mirror row_mask:0xf bank_mask:0xf
	v_add_f32_dpp v214, v214, v214 row_half_mirror row_mask:0xf bank_mask:0xf
	v_add_f32_dpp v218, v218, v218 row_half_mirror row_mask:0xf bank_mask:0xf
	v_add_f32_dpp v222, v222, v222 row_half_mirror row_mask:0xf bank_mask:0xf
	v_add_f32_dpp v226, v226, v226 row_half_mirror row_mask:0xf bank_mask:0xf
	v_add_f32_dpp v138, v138, v138 row_mirror row_mask:0xf bank_mask:0xf
	v_add_f32_dpp v142, v142, v142 row_mirror row_mask:0xf bank_mask:0xf
	v_add_f32_dpp v146, v146, v146 row_mirror row_mask:0xf bank_mask:0xf
	v_add_f32_dpp v150, v150, v150 row_mirror row_mask:0xf bank_mask:0xf
	v_add_f32_dpp v174, v174, v174 row_mirror row_mask:0xf bank_mask:0xf
	v_add_f32_dpp v178, v178, v178 row_mirror row_mask:0xf bank_mask:0xf
	v_add_f32_dpp v182, v182, v182 row_mirror row_mask:0xf bank_mask:0xf
	v_add_f32_dpp v186, v186, v186 row_mirror row_mask:0xf bank_mask:0xf
	v_add_f32_dpp v190, v190, v190 row_mirror row_mask:0xf bank_mask:0xf
	v_add_f32_dpp v198, v198, v198 row_mirror row_mask:0xf bank_mask:0xf
	v_add_f32_dpp v202, v202, v202 row_mirror row_mask:0xf bank_mask:0xf
	v_add_f32_dpp v206, v206, v206 row_mirror row_mask:0xf bank_mask:0xf
	v_add_f32_dpp v214, v214, v214 row_mirror row_mask:0xf bank_mask:0xf
	v_add_f32_dpp v218, v218, v218 row_mirror row_mask:0xf bank_mask:0xf
	v_add_f32_dpp v222, v222, v222 row_mirror row_mask:0xf bank_mask:0xf
	v_add_f32_dpp v226, v226, v226 row_mirror row_mask:0xf bank_mask:0xf
	v_add_f32_dpp v138, v138, v138 row_bcast:15 row_mask:0xa bank_mask:0xf
	v_add_f32_dpp v142, v142, v142 row_bcast:15 row_mask:0xa bank_mask:0xf
	v_add_f32_dpp v146, v146, v146 row_bcast:15 row_mask:0xa bank_mask:0xf
	v_add_f32_dpp v150, v150, v150 row_bcast:15 row_mask:0xa bank_mask:0xf
	v_add_f32_dpp v174, v174, v174 row_bcast:15 row_mask:0xa bank_mask:0xf
	v_add_f32_dpp v178, v178, v178 row_bcast:15 row_mask:0xa bank_mask:0xf
	v_add_f32_dpp v182, v182, v182 row_bcast:15 row_mask:0xa bank_mask:0xf
	v_add_f32_dpp v186, v186, v186 row_bcast:15 row_mask:0xa bank_mask:0xf
	v_add_f32_dpp v190, v190, v190 row_bcast:15 row_mask:0xa bank_mask:0xf
	v_add_f32_dpp v198, v198, v198 row_bcast:15 row_mask:0xa bank_mask:0xf
	v_add_f32_dpp v202, v202, v202 row_bcast:15 row_mask:0xa bank_mask:0xf
	v_add_f32_dpp v206, v206, v206 row_bcast:15 row_mask:0xa bank_mask:0xf
	v_add_f32_dpp v214, v214, v214 row_bcast:15 row_mask:0xa bank_mask:0xf
	v_add_f32_dpp v218, v218, v218 row_bcast:15 row_mask:0xa bank_mask:0xf
	v_add_f32_dpp v222, v222, v222 row_bcast:15 row_mask:0xa bank_mask:0xf
	v_add_f32_dpp v226, v226, v226 row_bcast:15 row_mask:0xa bank_mask:0xf
	s_mov_b32 exec_lo, 0x10000
	s_mov_b32 exec_hi, 0x10000
	global_atomic_add_f32 v245, v138, s[48:49]
	global_atomic_add_f32 v245, v142, s[48:49] offset:32
	global_atomic_add_f32 v245, v146, s[48:49] offset:64
	global_atomic_add_f32 v245, v150, s[48:49] offset:96
	global_atomic_add_f32 v245, v174, s[48:49] offset:128
	global_atomic_add_f32 v245, v178, s[48:49] offset:160
	global_atomic_add_f32 v245, v182, s[48:49] offset:192
	global_atomic_add_f32 v245, v186, s[48:49] offset:224
	global_atomic_add_f32 v245, v190, s[48:49] offset:256
	global_atomic_add_f32 v245, v198, s[48:49] offset:288
	global_atomic_add_f32 v245, v202, s[48:49] offset:320
	global_atomic_add_f32 v245, v206, s[48:49] offset:352
	global_atomic_add_f32 v245, v214, s[48:49] offset:384
	global_atomic_add_f32 v245, v218, s[48:49] offset:416
	global_atomic_add_f32 v245, v222, s[48:49] offset:448
	global_atomic_add_f32 v245, v226, s[48:49] offset:480
	s_mov_b64 exec, -1
	s_add_i32 s21, s21, s72
	s_cmpk_lt_i32 s21, 0x200
	s_waitcnt lgkmcnt(0)
	s_barrier
	s_cbranch_scc1 .Lres1_tile

.Lin2_loop:
	v_add_u32_e32 v234, s22, v232
	v_add_u32_e32 v236, s28, v232
	v_add_u32_e32 v235, s22, v233
	v_add_u32_e32 v237, s28, v233
	ds_read_b128 v[136:139], v234
	ds_read_b128 v[140:143], v234 offset:2048
	ds_read_b128 v[144:147], v234 offset:4096
	ds_read_b128 v[148:151], v234 offset:6144
	ds_read_b128 v[188:191], v236
	ds_read_b128 v[196:199], v236 offset:2048
	ds_read_b128 v[200:203], v236 offset:4096
	ds_read_b128 v[204:207], v236 offset:6144
	ds_read_b128 v[172:175], v235
	ds_read_b128 v[176:179], v235 offset:2048
	ds_read_b128 v[180:183], v235 offset:4096
	ds_read_b128 v[184:187], v235 offset:6144
	ds_read_b128 v[212:215], v237
	ds_read_b128 v[216:219], v237 offset:2048
	ds_read_b128 v[220:223], v237 offset:4096
	ds_read_b128 v[224:227], v237 offset:6144
	s_add_i32 m0, s51, 0xc000
	s_nop 0
	global_load_lds_dwordx4 v228, s[44:45]
	s_add_i32 m0, s51, 0xc400
	s_nop 0
	global_load_lds_dwordx4 v230, s[44:45]
	s_add_i32 m0, s51, 0xe000
	s_nop 0
	global_load_lds_dwordx4 v229, s[44:45]
	s_add_i32 m0, s51, 0xe400
	s_nop 0
	global_load_lds_dwordx4 v231, s[44:45]
	s_add_i32 m0, s51, 0x10000
	s_nop 0
	global_load_lds_dwordx4 v228, s[46:47]
	s_add_i32 m0, s51, 0x10400
	s_nop 0
	global_load_lds_dwordx4 v230, s[46:47]
	s_waitcnt lgkmcnt(8)
	s_setprio 1
	v_mfma_f32_16x16x32_bf16 v[2:5], v[136:139], v[188:191], v[2:5]
	v_mfma_f32_16x16x32_bf16 v[6:9], v[136:139], v[196:199], v[6:9]
	v_mfma_f32_16x16x32_bf16 v[10:13], v[136:139], v[200:203], v[10:13]
	v_mfma_f32_16x16x32_bf16 v[14:17], v[136:139], v[204:207], v[14:17]
	v_mfma_f32_16x16x32_bf16 v[18:21], v[140:143], v[188:191], v[18:21]
	v_mfma_f32_16x16x32_bf16 v[22:25], v[140:143], v[196:199], v[22:25]
	v_mfma_f32_16x16x32_bf16 v[26:29], v[140:143], v[200:203], v[26:29]
	v_mfma_f32_16x16x32_bf16 v[30:33], v[140:143], v[204:207], v[30:33]
	v_mfma_f32_16x16x32_bf16 v[34:37], v[144:147], v[188:191], v[34:37]
	v_mfma_f32_16x16x32_bf16 v[38:41], v[144:147], v[196:199], v[38:41]
	v_mfma_f32_16x16x32_bf16 v[42:45], v[144:147], v[200:203], v[42:45]
	v_mfma_f32_16x16x32_bf16 v[46:49], v[144:147], v[204:207], v[46:49]
	v_mfma_f32_16x16x32_bf16 v[50:53], v[148:151], v[188:191], v[50:53]
	v_mfma_f32_16x16x32_bf16 v[54:57], v[148:151], v[196:199], v[54:57]
	v_mfma_f32_16x16x32_bf16 v[58:61], v[148:151], v[200:203], v[58:61]
	v_mfma_f32_16x16x32_bf16 v[62:65], v[148:151], v[204:207], v[62:65]
	s_waitcnt lgkmcnt(0)
	v_mfma_f32_16x16x32_bf16 v[2:5], v[172:175], v[212:215], v[2:5]
	v_mfma_f32_16x16x32_bf16 v[6:9], v[172:175], v[216:219], v[6:9]
	v_mfma_f32_16x16x32_bf16 v[10:13], v[172:175], v[220:223], v[10:13]
	v_mfma_f32_16x16x32_bf16 v[14:17], v[172:175], v[224:227], v[14:17]
	v_mfma_f32_16x16x32_bf16 v[18:21], v[176:179], v[212:215], v[18:21]
	v_mfma_f32_16x16x32_bf16 v[22:25], v[176:179], v[216:219], v[22:25]
	v_mfma_f32_16x16x32_bf16 v[26:29], v[176:179], v[220:223], v[26:29]
	v_mfma_f32_16x16x32_bf16 v[30:33], v[176:179], v[224:227], v[30:33]
	v_mfma_f32_16x16x32_bf16 v[34:37], v[180:183], v[212:215], v[34:37]
	v_mfma_f32_16x16x32_bf16 v[38:41], v[180:183], v[216:219], v[38:41]
	v_mfma_f32_16x16x32_bf16 v[42:45], v[180:183], v[220:223], v[42:45]
	v_mfma_f32_16x16x32_bf16 v[46:49], v[180:183], v[224:227], v[46:49]
	v_mfma_f32_16x16x32_bf16 v[50:53], v[184:187], v[212:215], v[50:53]
	v_mfma_f32_16x16x32_bf16 v[54:57], v[184:187], v[216:219], v[54:57]
	v_mfma_f32_16x16x32_bf16 v[58:61], v[184:187], v[220:223], v[58:61]
	v_mfma_f32_16x16x32_bf16 v[62:65], v[184:187], v[224:227], v[62:65]
	s_setprio 0
	s_waitcnt vmcnt(6)
	s_barrier
	v_add_u32_e32 v236, s40, v232
	v_add_u32_e32 v237, s40, v233
	ds_read_b128 v[188:191], v236
	ds_read_b128 v[196:199], v236 offset:2048
	ds_read_b128 v[200:203], v236 offset:4096
	ds_read_b128 v[204:207], v236 offset:6144
	ds_read_b128 v[212:215], v237
	ds_read_b128 v[216:219], v237 offset:2048
	ds_read_b128 v[220:223], v237 offset:4096
	ds_read_b128 v[224:227], v237 offset:6144
	s_mov_b32 m0, s51
	s_nop 0
	global_load_lds_dwordx4 v229, s[46:47]
	s_add_i32 m0, s51, 0x400
	s_nop 0
	global_load_lds_dwordx4 v231, s[46:47]
	s_add_i32 m0, s51, 0x2000
	s_nop 0
	global_load_lds_dwordx4 v228, s[48:49]
	s_add_i32 m0, s51, 0x2400
	s_nop 0
	global_load_lds_dwordx4 v230, s[48:49]
	s_add_i32 m0, s51, 0x4000
	s_nop 0
	global_load_lds_dwordx4 v229, s[48:49]
	s_add_i32 m0, s51, 0x4400
	s_nop 0
	global_load_lds_dwordx4 v231, s[48:49]
	s_waitcnt lgkmcnt(4)
	s_setprio 1
	v_mfma_f32_16x16x32_bf16 v[66:69], v[136:139], v[188:191], v[66:69]
	v_mfma_f32_16x16x32_bf16 v[70:73], v[136:139], v[196:199], v[70:73]
	v_mfma_f32_16x16x32_bf16 v[74:77], v[136:139], v[200:203], v[74:77]
	v_mfma_f32_16x16x32_bf16 v[78:81], v[136:139], v[204:207], v[78:81]
	v_mfma_f32_16x16x32_bf16 v[82:85], v[140:143], v[188:191], v[82:85]
	v_mfma_f32_16x16x32_bf16 v[86:89], v[140:143], v[196:199], v[86:89]
	v_mfma_f32_16x16x32_bf16 v[90:93], v[140:143], v[200:203], v[90:93]
	v_mfma_f32_16x16x32_bf16 v[94:97], v[140:143], v[204:207], v[94:97]
	v_mfma_f32_16x16x32_bf16 v[98:101], v[144:147], v[188:191], v[98:101]
	v_mfma_f32_16x16x32_bf16 v[102:105], v[144:147], v[196:199], v[102:105]
	v_mfma_f32_16x16x32_bf16 v[106:109], v[144:147], v[200:203], v[106:109]
	v_mfma_f32_16x16x32_bf16 v[110:113], v[144:147], v[204:207], v[110:113]
	v_mfma_f32_16x16x32_bf16 v[114:117], v[148:151], v[188:191], v[114:117]
	v_mfma_f32_16x16x32_bf16 v[118:121], v[148:151], v[196:199], v[118:121]
	v_mfma_f32_16x16x32_bf16 v[122:125], v[148:151], v[200:203], v[122:125]
	v_mfma_f32_16x16x32_bf16 v[126:129], v[148:151], v[204:207], v[126:129]
	s_waitcnt lgkmcnt(0)
	v_mfma_f32_16x16x32_bf16 v[66:69], v[172:175], v[212:215], v[66:69]
	v_mfma_f32_16x16x32_bf16 v[70:73], v[172:175], v[216:219], v[70:73]
	v_mfma_f32_16x16x32_bf16 v[74:77], v[172:175], v[220:223], v[74:77]
	v_mfma_f32_16x16x32_bf16 v[78:81], v[172:175], v[224:227], v[78:81]
	v_mfma_f32_16x16x32_bf16 v[82:85], v[176:179], v[212:215], v[82:85]
	v_mfma_f32_16x16x32_bf16 v[86:89], v[176:179], v[216:219], v[86:89]
	v_mfma_f32_16x16x32_bf16 v[90:93], v[176:179], v[220:223], v[90:93]
	v_mfma_f32_16x16x32_bf16 v[94:97], v[176:179], v[224:227], v[94:97]
	v_mfma_f32_16x16x32_bf16 v[98:101], v[180:183], v[212:215], v[98:101]
	v_mfma_f32_16x16x32_bf16 v[102:105], v[180:183], v[216:219], v[102:105]
	v_mfma_f32_16x16x32_bf16 v[106:109], v[180:183], v[220:223], v[106:109]
	v_mfma_f32_16x16x32_bf16 v[110:113], v[180:183], v[224:227], v[110:113]
	v_mfma_f32_16x16x32_bf16 v[114:117], v[184:187], v[212:215], v[114:117]
	v_mfma_f32_16x16x32_bf16 v[118:121], v[184:187], v[216:219], v[118:121]
	v_mfma_f32_16x16x32_bf16 v[122:125], v[184:187], v[220:223], v[122:125]
	v_mfma_f32_16x16x32_bf16 v[126:129], v[184:187], v[224:227], v[126:129]
	s_setprio 0
	v_add_u32_e32 v228, 0x80, v228
	v_add_u32_e32 v229, 0x80, v229
	v_add_u32_e32 v230, 0x80, v230
	v_add_u32_e32 v231, 0x80, v231
	s_waitcnt vmcnt(4)
	s_barrier
	v_add_u32_e32 v234, s23, v232
	v_add_u32_e32 v236, s29, v232
	v_add_u32_e32 v235, s23, v233
	v_add_u32_e32 v237, s29, v233
	ds_read_b128 v[136:139], v234
	ds_read_b128 v[140:143], v234 offset:2048
	ds_read_b128 v[144:147], v234 offset:4096
	ds_read_b128 v[148:151], v234 offset:6144
	ds_read_b128 v[188:191], v236
	ds_read_b128 v[196:199], v236 offset:2048
	ds_read_b128 v[200:203], v236 offset:4096
	ds_read_b128 v[204:207], v236 offset:6144
	ds_read_b128 v[172:175], v235
	ds_read_b128 v[176:179], v235 offset:2048
	ds_read_b128 v[180:183], v235 offset:4096
	ds_read_b128 v[184:187], v235 offset:6144
	ds_read_b128 v[212:215], v237
	ds_read_b128 v[216:219], v237 offset:2048
	ds_read_b128 v[220:223], v237 offset:4096
	ds_read_b128 v[224:227], v237 offset:6144
	s_add_i32 m0, s51, 0x6000
	s_nop 0
	global_load_lds_dwordx4 v228, s[44:45]
	s_add_i32 m0, s51, 0x6400
	s_nop 0
	global_load_lds_dwordx4 v230, s[44:45]
	s_add_i32 m0, s51, 0x8000
	s_nop 0
	global_load_lds_dwordx4 v229, s[44:45]
	s_add_i32 m0, s51, 0x8400
	s_nop 0
	global_load_lds_dwordx4 v231, s[44:45]
	s_add_i32 m0, s51, 0xa000
	s_nop 0
	global_load_lds_dwordx4 v228, s[46:47]
	s_add_i32 m0, s51, 0xa400
	s_nop 0
	global_load_lds_dwordx4 v230, s[46:47]
	s_waitcnt lgkmcnt(8)
	s_setprio 1
	v_mfma_f32_16x16x32_bf16 v[2:5], v[136:139], v[188:191], v[2:5]
	v_mfma_f32_16x16x32_bf16 v[6:9], v[136:139], v[196:199], v[6:9]
	v_mfma_f32_16x16x32_bf16 v[10:13], v[136:139], v[200:203], v[10:13]
	v_mfma_f32_16x16x32_bf16 v[14:17], v[136:139], v[204:207], v[14:17]
	v_mfma_f32_16x16x32_bf16 v[18:21], v[140:143], v[188:191], v[18:21]
	v_mfma_f32_16x16x32_bf16 v[22:25], v[140:143], v[196:199], v[22:25]
	v_mfma_f32_16x16x32_bf16 v[26:29], v[140:143], v[200:203], v[26:29]
	v_mfma_f32_16x16x32_bf16 v[30:33], v[140:143], v[204:207], v[30:33]
	v_mfma_f32_16x16x32_bf16 v[34:37], v[144:147], v[188:191], v[34:37]
	v_mfma_f32_16x16x32_bf16 v[38:41], v[144:147], v[196:199], v[38:41]
	v_mfma_f32_16x16x32_bf16 v[42:45], v[144:147], v[200:203], v[42:45]
	v_mfma_f32_16x16x32_bf16 v[46:49], v[144:147], v[204:207], v[46:49]
	v_mfma_f32_16x16x32_bf16 v[50:53], v[148:151], v[188:191], v[50:53]
	v_mfma_f32_16x16x32_bf16 v[54:57], v[148:151], v[196:199], v[54:57]
	v_mfma_f32_16x16x32_bf16 v[58:61], v[148:151], v[200:203], v[58:61]
	v_mfma_f32_16x16x32_bf16 v[62:65], v[148:151], v[204:207], v[62:65]
	s_waitcnt lgkmcnt(0)
	v_mfma_f32_16x16x32_bf16 v[2:5], v[172:175], v[212:215], v[2:5]
	v_mfma_f32_16x16x32_bf16 v[6:9], v[172:175], v[216:219], v[6:9]
	v_mfma_f32_16x16x32_bf16 v[10:13], v[172:175], v[220:223], v[10:13]
	v_mfma_f32_16x16x32_bf16 v[14:17], v[172:175], v[224:227], v[14:17]
	v_mfma_f32_16x16x32_bf16 v[18:21], v[176:179], v[212:215], v[18:21]
	v_mfma_f32_16x16x32_bf16 v[22:25], v[176:179], v[216:219], v[22:25]
	v_mfma_f32_16x16x32_bf16 v[26:29], v[176:179], v[220:223], v[26:29]
	v_mfma_f32_16x16x32_bf16 v[30:33], v[176:179], v[224:227], v[30:33]
	v_mfma_f32_16x16x32_bf16 v[34:37], v[180:183], v[212:215], v[34:37]
	v_mfma_f32_16x16x32_bf16 v[38:41], v[180:183], v[216:219], v[38:41]
	v_mfma_f32_16x16x32_bf16 v[42:45], v[180:183], v[220:223], v[42:45]
	v_mfma_f32_16x16x32_bf16 v[46:49], v[180:183], v[224:227], v[46:49]
	v_mfma_f32_16x16x32_bf16 v[50:53], v[184:187], v[212:215], v[50:53]
	v_mfma_f32_16x16x32_bf16 v[54:57], v[184:187], v[216:219], v[54:57]
	v_mfma_f32_16x16x32_bf16 v[58:61], v[184:187], v[220:223], v[58:61]
	v_mfma_f32_16x16x32_bf16 v[62:65], v[184:187], v[224:227], v[62:65]
	s_setprio 0
	s_waitcnt vmcnt(6)
	s_barrier
	v_add_u32_e32 v236, s41, v232
	v_add_u32_e32 v237, s41, v233
	ds_read_b128 v[188:191], v236
	ds_read_b128 v[196:199], v236 offset:2048
	ds_read_b128 v[200:203], v236 offset:4096
	ds_read_b128 v[204:207], v236 offset:6144
	ds_read_b128 v[212:215], v237
	ds_read_b128 v[216:219], v237 offset:2048
	ds_read_b128 v[220:223], v237 offset:4096
	ds_read_b128 v[224:227], v237 offset:6144
	s_add_i32 m0, s51, 0xc000
	s_nop 0
	global_load_lds_dwordx4 v229, s[46:47]
	s_add_i32 m0, s51, 0xc400
	s_nop 0
	global_load_lds_dwordx4 v231, s[46:47]
	s_add_i32 m0, s51, 0xe000
	s_nop 0
	global_load_lds_dwordx4 v228, s[48:49]
	s_add_i32 m0, s51, 0xe400
	s_nop 0
	global_load_lds_dwordx4 v230, s[48:49]
	s_add_i32 m0, s51, 0x10000
	s_nop 0
	global_load_lds_dwordx4 v229, s[48:49]
	s_add_i32 m0, s51, 0x10400
	s_nop 0
	global_load_lds_dwordx4 v231, s[48:49]
	s_waitcnt lgkmcnt(4)
	s_setprio 1
	v_mfma_f32_16x16x32_bf16 v[66:69], v[136:139], v[188:191], v[66:69]
	v_mfma_f32_16x16x32_bf16 v[70:73], v[136:139], v[196:199], v[70:73]
	v_mfma_f32_16x16x32_bf16 v[74:77], v[136:139], v[200:203], v[74:77]
	v_mfma_f32_16x16x32_bf16 v[78:81], v[136:139], v[204:207], v[78:81]
	v_mfma_f32_16x16x32_bf16 v[82:85], v[140:143], v[188:191], v[82:85]
	v_mfma_f32_16x16x32_bf16 v[86:89], v[140:143], v[196:199], v[86:89]
	v_mfma_f32_16x16x32_bf16 v[90:93], v[140:143], v[200:203], v[90:93]
	v_mfma_f32_16x16x32_bf16 v[94:97], v[140:143], v[204:207], v[94:97]
	v_mfma_f32_16x16x32_bf16 v[98:101], v[144:147], v[188:191], v[98:101]
	v_mfma_f32_16x16x32_bf16 v[102:105], v[144:147], v[196:199], v[102:105]
	v_mfma_f32_16x16x32_bf16 v[106:109], v[144:147], v[200:203], v[106:109]
	v_mfma_f32_16x16x32_bf16 v[110:113], v[144:147], v[204:207], v[110:113]
	v_mfma_f32_16x16x32_bf16 v[114:117], v[148:151], v[188:191], v[114:117]
	v_mfma_f32_16x16x32_bf16 v[118:121], v[148:151], v[196:199], v[118:121]
	v_mfma_f32_16x16x32_bf16 v[122:125], v[148:151], v[200:203], v[122:125]
	v_mfma_f32_16x16x32_bf16 v[126:129], v[148:151], v[204:207], v[126:129]
	s_waitcnt lgkmcnt(0)
	v_mfma_f32_16x16x32_bf16 v[66:69], v[172:175], v[212:215], v[66:69]
	v_mfma_f32_16x16x32_bf16 v[70:73], v[172:175], v[216:219], v[70:73]
	v_mfma_f32_16x16x32_bf16 v[74:77], v[172:175], v[220:223], v[74:77]
	v_mfma_f32_16x16x32_bf16 v[78:81], v[172:175], v[224:227], v[78:81]
	v_mfma_f32_16x16x32_bf16 v[82:85], v[176:179], v[212:215], v[82:85]
	v_mfma_f32_16x16x32_bf16 v[86:89], v[176:179], v[216:219], v[86:89]
	v_mfma_f32_16x16x32_bf16 v[90:93], v[176:179], v[220:223], v[90:93]
	v_mfma_f32_16x16x32_bf16 v[94:97], v[176:179], v[224:227], v[94:97]
	v_mfma_f32_16x16x32_bf16 v[98:101], v[180:183], v[212:215], v[98:101]
	v_mfma_f32_16x16x32_bf16 v[102:105], v[180:183], v[216:219], v[102:105]
	v_mfma_f32_16x16x32_bf16 v[106:109], v[180:183], v[220:223], v[106:109]
	v_mfma_f32_16x16x32_bf16 v[110:113], v[180:183], v[224:227], v[110:113]
	v_mfma_f32_16x16x32_bf16 v[114:117], v[184:187], v[212:215], v[114:117]
	v_mfma_f32_16x16x32_bf16 v[118:121], v[184:187], v[216:219], v[118:121]
	v_mfma_f32_16x16x32_bf16 v[122:125], v[184:187], v[220:223], v[122:125]
	v_mfma_f32_16x16x32_bf16 v[126:129], v[184:187], v[224:227], v[126:129]
	s_setprio 0
	v_add_u32_e32 v228, 0x80, v228
	v_add_u32_e32 v229, 0x80, v229
	v_add_u32_e32 v230, 0x80, v230
	v_add_u32_e32 v231, 0x80, v231
	s_waitcnt vmcnt(4)
	s_barrier
	v_add_u32_e32 v234, s24, v232
	v_add_u32_e32 v236, s30, v232
	v_add_u32_e32 v235, s24, v233
	v_add_u32_e32 v237, s30, v233
	ds_read_b128 v[136:139], v234
	ds_read_b128 v[140:143], v234 offset:2048
	ds_read_b128 v[144:147], v234 offset:4096
	ds_read_b128 v[148:151], v234 offset:6144
	ds_read_b128 v[188:191], v236
	ds_read_b128 v[196:199], v236 offset:2048
	ds_read_b128 v[200:203], v236 offset:4096
	ds_read_b128 v[204:207], v236 offset:6144
	ds_read_b128 v[172:175], v235
	ds_read_b128 v[176:179], v235 offset:2048
	ds_read_b128 v[180:183], v235 offset:4096
	ds_read_b128 v[184:187], v235 offset:6144
	ds_read_b128 v[212:215], v237
	ds_read_b128 v[216:219], v237 offset:2048
	ds_read_b128 v[220:223], v237 offset:4096
	ds_read_b128 v[224:227], v237 offset:6144
	s_mov_b32 m0, s51
	s_nop 0
	global_load_lds_dwordx4 v228, s[44:45]
	s_add_i32 m0, s51, 0x400
	s_nop 0
	global_load_lds_dwordx4 v230, s[44:45]
	s_add_i32 m0, s51, 0x2000
	s_nop 0
	global_load_lds_dwordx4 v229, s[44:45]
	s_add_i32 m0, s51, 0x2400
	s_nop 0
	global_load_lds_dwordx4 v231, s[44:45]
	s_add_i32 m0, s51, 0x4000
	s_nop 0
	global_load_lds_dwordx4 v228, s[46:47]
	s_add_i32 m0, s51, 0x4400
	s_nop 0
	global_load_lds_dwordx4 v230, s[46:47]
	s_waitcnt lgkmcnt(8)
	s_setprio 1
	v_mfma_f32_16x16x32_bf16 v[2:5], v[136:139], v[188:191], v[2:5]
	v_mfma_f32_16x16x32_bf16 v[6:9], v[136:139], v[196:199], v[6:9]
	v_mfma_f32_16x16x32_bf16 v[10:13], v[136:139], v[200:203], v[10:13]
	v_mfma_f32_16x16x32_bf16 v[14:17], v[136:139], v[204:207], v[14:17]
	v_mfma_f32_16x16x32_bf16 v[18:21], v[140:143], v[188:191], v[18:21]
	v_mfma_f32_16x16x32_bf16 v[22:25], v[140:143], v[196:199], v[22:25]
	v_mfma_f32_16x16x32_bf16 v[26:29], v[140:143], v[200:203], v[26:29]
	v_mfma_f32_16x16x32_bf16 v[30:33], v[140:143], v[204:207], v[30:33]
	v_mfma_f32_16x16x32_bf16 v[34:37], v[144:147], v[188:191], v[34:37]
	v_mfma_f32_16x16x32_bf16 v[38:41], v[144:147], v[196:199], v[38:41]
	v_mfma_f32_16x16x32_bf16 v[42:45], v[144:147], v[200:203], v[42:45]
	v_mfma_f32_16x16x32_bf16 v[46:49], v[144:147], v[204:207], v[46:49]
	v_mfma_f32_16x16x32_bf16 v[50:53], v[148:151], v[188:191], v[50:53]
	v_mfma_f32_16x16x32_bf16 v[54:57], v[148:151], v[196:199], v[54:57]
	v_mfma_f32_16x16x32_bf16 v[58:61], v[148:151], v[200:203], v[58:61]
	v_mfma_f32_16x16x32_bf16 v[62:65], v[148:151], v[204:207], v[62:65]
	s_waitcnt lgkmcnt(0)
	v_mfma_f32_16x16x32_bf16 v[2:5], v[172:175], v[212:215], v[2:5]
	v_mfma_f32_16x16x32_bf16 v[6:9], v[172:175], v[216:219], v[6:9]
	v_mfma_f32_16x16x32_bf16 v[10:13], v[172:175], v[220:223], v[10:13]
	v_mfma_f32_16x16x32_bf16 v[14:17], v[172:175], v[224:227], v[14:17]
	v_mfma_f32_16x16x32_bf16 v[18:21], v[176:179], v[212:215], v[18:21]
	v_mfma_f32_16x16x32_bf16 v[22:25], v[176:179], v[216:219], v[22:25]
	v_mfma_f32_16x16x32_bf16 v[26:29], v[176:179], v[220:223], v[26:29]
	v_mfma_f32_16x16x32_bf16 v[30:33], v[176:179], v[224:227], v[30:33]
	v_mfma_f32_16x16x32_bf16 v[34:37], v[180:183], v[212:215], v[34:37]
	v_mfma_f32_16x16x32_bf16 v[38:41], v[180:183], v[216:219], v[38:41]
	v_mfma_f32_16x16x32_bf16 v[42:45], v[180:183], v[220:223], v[42:45]
	v_mfma_f32_16x16x32_bf16 v[46:49], v[180:183], v[224:227], v[46:49]
	v_mfma_f32_16x16x32_bf16 v[50:53], v[184:187], v[212:215], v[50:53]
	v_mfma_f32_16x16x32_bf16 v[54:57], v[184:187], v[216:219], v[54:57]
	v_mfma_f32_16x16x32_bf16 v[58:61], v[184:187], v[220:223], v[58:61]
	v_mfma_f32_16x16x32_bf16 v[62:65], v[184:187], v[224:227], v[62:65]
	s_setprio 0
	s_waitcnt vmcnt(6)
	s_barrier
	v_add_u32_e32 v236, s42, v232
	v_add_u32_e32 v237, s42, v233
	ds_read_b128 v[188:191], v236
	ds_read_b128 v[196:199], v236 offset:2048
	ds_read_b128 v[200:203], v236 offset:4096
	ds_read_b128 v[204:207], v236 offset:6144
	ds_read_b128 v[212:215], v237
	ds_read_b128 v[216:219], v237 offset:2048
	ds_read_b128 v[220:223], v237 offset:4096
	ds_read_b128 v[224:227], v237 offset:6144
	s_add_i32 m0, s51, 0x6000
	s_nop 0
	global_load_lds_dwordx4 v229, s[46:47]
	s_add_i32 m0, s51, 0x6400
	s_nop 0
	global_load_lds_dwordx4 v231, s[46:47]
	s_add_i32 m0, s51, 0x8000
	s_nop 0
	global_load_lds_dwordx4 v228, s[48:49]
	s_add_i32 m0, s51, 0x8400
	s_nop 0
	global_load_lds_dwordx4 v230, s[48:49]
	s_add_i32 m0, s51, 0xa000
	s_nop 0
	global_load_lds_dwordx4 v229, s[48:49]
	s_add_i32 m0, s51, 0xa400
	s_nop 0
	global_load_lds_dwordx4 v231, s[48:49]
	s_waitcnt lgkmcnt(4)
	s_setprio 1
	v_mfma_f32_16x16x32_bf16 v[66:69], v[136:139], v[188:191], v[66:69]
	v_mfma_f32_16x16x32_bf16 v[70:73], v[136:139], v[196:199], v[70:73]
	v_mfma_f32_16x16x32_bf16 v[74:77], v[136:139], v[200:203], v[74:77]
	v_mfma_f32_16x16x32_bf16 v[78:81], v[136:139], v[204:207], v[78:81]
	v_mfma_f32_16x16x32_bf16 v[82:85], v[140:143], v[188:191], v[82:85]
	v_mfma_f32_16x16x32_bf16 v[86:89], v[140:143], v[196:199], v[86:89]
	v_mfma_f32_16x16x32_bf16 v[90:93], v[140:143], v[200:203], v[90:93]
	v_mfma_f32_16x16x32_bf16 v[94:97], v[140:143], v[204:207], v[94:97]
	v_mfma_f32_16x16x32_bf16 v[98:101], v[144:147], v[188:191], v[98:101]
	v_mfma_f32_16x16x32_bf16 v[102:105], v[144:147], v[196:199], v[102:105]
	v_mfma_f32_16x16x32_bf16 v[106:109], v[144:147], v[200:203], v[106:109]
	v_mfma_f32_16x16x32_bf16 v[110:113], v[144:147], v[204:207], v[110:113]
	v_mfma_f32_16x16x32_bf16 v[114:117], v[148:151], v[188:191], v[114:117]
	v_mfma_f32_16x16x32_bf16 v[118:121], v[148:151], v[196:199], v[118:121]
	v_mfma_f32_16x16x32_bf16 v[122:125], v[148:151], v[200:203], v[122:125]
	v_mfma_f32_16x16x32_bf16 v[126:129], v[148:151], v[204:207], v[126:129]
	s_waitcnt lgkmcnt(0)
	v_mfma_f32_16x16x32_bf16 v[66:69], v[172:175], v[212:215], v[66:69]
	v_mfma_f32_16x16x32_bf16 v[70:73], v[172:175], v[216:219], v[70:73]
	v_mfma_f32_16x16x32_bf16 v[74:77], v[172:175], v[220:223], v[74:77]
	v_mfma_f32_16x16x32_bf16 v[78:81], v[172:175], v[224:227], v[78:81]
	v_mfma_f32_16x16x32_bf16 v[82:85], v[176:179], v[212:215], v[82:85]
	v_mfma_f32_16x16x32_bf16 v[86:89], v[176:179], v[216:219], v[86:89]
	v_mfma_f32_16x16x32_bf16 v[90:93], v[176:179], v[220:223], v[90:93]
	v_mfma_f32_16x16x32_bf16 v[94:97], v[176:179], v[224:227], v[94:97]
	v_mfma_f32_16x16x32_bf16 v[98:101], v[180:183], v[212:215], v[98:101]
	v_mfma_f32_16x16x32_bf16 v[102:105], v[180:183], v[216:219], v[102:105]
	v_mfma_f32_16x16x32_bf16 v[106:109], v[180:183], v[220:223], v[106:109]
	v_mfma_f32_16x16x32_bf16 v[110:113], v[180:183], v[224:227], v[110:113]
	v_mfma_f32_16x16x32_bf16 v[114:117], v[184:187], v[212:215], v[114:117]
	v_mfma_f32_16x16x32_bf16 v[118:121], v[184:187], v[216:219], v[118:121]
	v_mfma_f32_16x16x32_bf16 v[122:125], v[184:187], v[220:223], v[122:125]
	v_mfma_f32_16x16x32_bf16 v[126:129], v[184:187], v[224:227], v[126:129]
	s_setprio 0
	v_add_u32_e32 v228, 0x80, v228
	v_add_u32_e32 v229, 0x80, v229
	v_add_u32_e32 v230, 0x80, v230
	v_add_u32_e32 v231, 0x80, v231
	s_waitcnt vmcnt(4)
	s_barrier
	s_add_i32 s52, s52, 1
	s_cmp_lt_u32 s52, 10
	s_cbranch_scc1 .Lin2_loop
	v_add_u32_e32 v234, s22, v232
	v_add_u32_e32 v236, s28, v232
	v_add_u32_e32 v235, s22, v233
	v_add_u32_e32 v237, s28, v233
	ds_read_b128 v[136:139], v234
	ds_read_b128 v[140:143], v234 offset:2048
	ds_read_b128 v[144:147], v234 offset:4096
	ds_read_b128 v[148:151], v234 offset:6144
	ds_read_b128 v[188:191], v236
	ds_read_b128 v[196:199], v236 offset:2048
	ds_read_b128 v[200:203], v236 offset:4096
	ds_read_b128 v[204:207], v236 offset:6144
	ds_read_b128 v[172:175], v235
	ds_read_b128 v[176:179], v235 offset:2048
	ds_read_b128 v[180:183], v235 offset:4096
	ds_read_b128 v[184:187], v235 offset:6144
	ds_read_b128 v[212:215], v237
	ds_read_b128 v[216:219], v237 offset:2048
	ds_read_b128 v[220:223], v237 offset:4096
	ds_read_b128 v[224:227], v237 offset:6144
	s_add_i32 m0, s51, 0xc000
	s_nop 0
	global_load_lds_dwordx4 v228, s[44:45]
	s_add_i32 m0, s51, 0xc400
	s_nop 0
	global_load_lds_dwordx4 v230, s[44:45]
	s_add_i32 m0, s51, 0xe000
	s_nop 0
	global_load_lds_dwordx4 v229, s[44:45]
	s_add_i32 m0, s51, 0xe400
	s_nop 0
	global_load_lds_dwordx4 v231, s[44:45]
	s_add_i32 m0, s51, 0x10000
	s_nop 0
	global_load_lds_dwordx4 v228, s[46:47]
	s_add_i32 m0, s51, 0x10400
	s_nop 0
	global_load_lds_dwordx4 v230, s[46:47]
	s_waitcnt lgkmcnt(8)
	s_setprio 1
	v_mfma_f32_16x16x32_bf16 v[2:5], v[136:139], v[188:191], v[2:5]
	v_mfma_f32_16x16x32_bf16 v[6:9], v[136:139], v[196:199], v[6:9]
	v_mfma_f32_16x16x32_bf16 v[10:13], v[136:139], v[200:203], v[10:13]
	v_mfma_f32_16x16x32_bf16 v[14:17], v[136:139], v[204:207], v[14:17]
	v_mfma_f32_16x16x32_bf16 v[18:21], v[140:143], v[188:191], v[18:21]
	v_mfma_f32_16x16x32_bf16 v[22:25], v[140:143], v[196:199], v[22:25]
	v_mfma_f32_16x16x32_bf16 v[26:29], v[140:143], v[200:203], v[26:29]
	v_mfma_f32_16x16x32_bf16 v[30:33], v[140:143], v[204:207], v[30:33]
	v_mfma_f32_16x16x32_bf16 v[34:37], v[144:147], v[188:191], v[34:37]
	v_mfma_f32_16x16x32_bf16 v[38:41], v[144:147], v[196:199], v[38:41]
	v_mfma_f32_16x16x32_bf16 v[42:45], v[144:147], v[200:203], v[42:45]
	v_mfma_f32_16x16x32_bf16 v[46:49], v[144:147], v[204:207], v[46:49]
	v_mfma_f32_16x16x32_bf16 v[50:53], v[148:151], v[188:191], v[50:53]
	v_mfma_f32_16x16x32_bf16 v[54:57], v[148:151], v[196:199], v[54:57]
	v_mfma_f32_16x16x32_bf16 v[58:61], v[148:151], v[200:203], v[58:61]
	v_mfma_f32_16x16x32_bf16 v[62:65], v[148:151], v[204:207], v[62:65]
	s_waitcnt lgkmcnt(0)
	v_mfma_f32_16x16x32_bf16 v[2:5], v[172:175], v[212:215], v[2:5]
	v_mfma_f32_16x16x32_bf16 v[6:9], v[172:175], v[216:219], v[6:9]
	v_mfma_f32_16x16x32_bf16 v[10:13], v[172:175], v[220:223], v[10:13]
	v_mfma_f32_16x16x32_bf16 v[14:17], v[172:175], v[224:227], v[14:17]
	v_mfma_f32_16x16x32_bf16 v[18:21], v[176:179], v[212:215], v[18:21]
	v_mfma_f32_16x16x32_bf16 v[22:25], v[176:179], v[216:219], v[22:25]
	v_mfma_f32_16x16x32_bf16 v[26:29], v[176:179], v[220:223], v[26:29]
	v_mfma_f32_16x16x32_bf16 v[30:33], v[176:179], v[224:227], v[30:33]
	v_mfma_f32_16x16x32_bf16 v[34:37], v[180:183], v[212:215], v[34:37]
	v_mfma_f32_16x16x32_bf16 v[38:41], v[180:183], v[216:219], v[38:41]
	v_mfma_f32_16x16x32_bf16 v[42:45], v[180:183], v[220:223], v[42:45]
	v_mfma_f32_16x16x32_bf16 v[46:49], v[180:183], v[224:227], v[46:49]
	v_mfma_f32_16x16x32_bf16 v[50:53], v[184:187], v[212:215], v[50:53]
	v_mfma_f32_16x16x32_bf16 v[54:57], v[184:187], v[216:219], v[54:57]
	v_mfma_f32_16x16x32_bf16 v[58:61], v[184:187], v[220:223], v[58:61]
	v_mfma_f32_16x16x32_bf16 v[62:65], v[184:187], v[224:227], v[62:65]
	s_setprio 0
	s_waitcnt vmcnt(6)
	s_barrier
	v_add_u32_e32 v236, s40, v232
	v_add_u32_e32 v237, s40, v233
	ds_read_b128 v[188:191], v236
	ds_read_b128 v[196:199], v236 offset:2048
	ds_read_b128 v[200:203], v236 offset:4096
	ds_read_b128 v[204:207], v236 offset:6144
	ds_read_b128 v[212:215], v237
	ds_read_b128 v[216:219], v237 offset:2048
	ds_read_b128 v[220:223], v237 offset:4096
	ds_read_b128 v[224:227], v237 offset:6144
	s_mov_b32 m0, s51
	s_nop 0
	global_load_lds_dwordx4 v229, s[46:47]
	s_add_i32 m0, s51, 0x400
	s_nop 0
	global_load_lds_dwordx4 v231, s[46:47]
	s_add_i32 m0, s51, 0x2000
	s_nop 0
	global_load_lds_dwordx4 v228, s[48:49]
	s_add_i32 m0, s51, 0x2400
	s_nop 0
	global_load_lds_dwordx4 v230, s[48:49]
	s_add_i32 m0, s51, 0x4000
	s_nop 0
	global_load_lds_dwordx4 v229, s[48:49]
	s_add_i32 m0, s51, 0x4400
	s_nop 0
	global_load_lds_dwordx4 v231, s[48:49]
	s_waitcnt lgkmcnt(4)
	s_setprio 1
	v_mfma_f32_16x16x32_bf16 v[66:69], v[136:139], v[188:191], v[66:69]
	v_mfma_f32_16x16x32_bf16 v[70:73], v[136:139], v[196:199], v[70:73]
	v_mfma_f32_16x16x32_bf16 v[74:77], v[136:139], v[200:203], v[74:77]
	v_mfma_f32_16x16x32_bf16 v[78:81], v[136:139], v[204:207], v[78:81]
	v_mfma_f32_16x16x32_bf16 v[82:85], v[140:143], v[188:191], v[82:85]
	v_mfma_f32_16x16x32_bf16 v[86:89], v[140:143], v[196:199], v[86:89]
	v_mfma_f32_16x16x32_bf16 v[90:93], v[140:143], v[200:203], v[90:93]
	v_mfma_f32_16x16x32_bf16 v[94:97], v[140:143], v[204:207], v[94:97]
	v_mfma_f32_16x16x32_bf16 v[98:101], v[144:147], v[188:191], v[98:101]
	v_mfma_f32_16x16x32_bf16 v[102:105], v[144:147], v[196:199], v[102:105]
	v_mfma_f32_16x16x32_bf16 v[106:109], v[144:147], v[200:203], v[106:109]
	v_mfma_f32_16x16x32_bf16 v[110:113], v[144:147], v[204:207], v[110:113]
	v_mfma_f32_16x16x32_bf16 v[114:117], v[148:151], v[188:191], v[114:117]
	v_mfma_f32_16x16x32_bf16 v[118:121], v[148:151], v[196:199], v[118:121]
	v_mfma_f32_16x16x32_bf16 v[122:125], v[148:151], v[200:203], v[122:125]
	v_mfma_f32_16x16x32_bf16 v[126:129], v[148:151], v[204:207], v[126:129]
	s_waitcnt lgkmcnt(0)
	v_mfma_f32_16x16x32_bf16 v[66:69], v[172:175], v[212:215], v[66:69]
	v_mfma_f32_16x16x32_bf16 v[70:73], v[172:175], v[216:219], v[70:73]
	v_mfma_f32_16x16x32_bf16 v[74:77], v[172:175], v[220:223], v[74:77]
	v_mfma_f32_16x16x32_bf16 v[78:81], v[172:175], v[224:227], v[78:81]
	v_mfma_f32_16x16x32_bf16 v[82:85], v[176:179], v[212:215], v[82:85]
	v_mfma_f32_16x16x32_bf16 v[86:89], v[176:179], v[216:219], v[86:89]
	v_mfma_f32_16x16x32_bf16 v[90:93], v[176:179], v[220:223], v[90:93]
	v_mfma_f32_16x16x32_bf16 v[94:97], v[176:179], v[224:227], v[94:97]
	v_mfma_f32_16x16x32_bf16 v[98:101], v[180:183], v[212:215], v[98:101]
	v_mfma_f32_16x16x32_bf16 v[102:105], v[180:183], v[216:219], v[102:105]
	v_mfma_f32_16x16x32_bf16 v[106:109], v[180:183], v[220:223], v[106:109]
	v_mfma_f32_16x16x32_bf16 v[110:113], v[180:183], v[224:227], v[110:113]
	v_mfma_f32_16x16x32_bf16 v[114:117], v[184:187], v[212:215], v[114:117]
	v_mfma_f32_16x16x32_bf16 v[118:121], v[184:187], v[216:219], v[118:121]
	v_mfma_f32_16x16x32_bf16 v[122:125], v[184:187], v[220:223], v[122:125]
	v_mfma_f32_16x16x32_bf16 v[126:129], v[184:187], v[224:227], v[126:129]
	s_setprio 0
	v_add_u32_e32 v228, 0x80, v228
	v_add_u32_e32 v229, 0x80, v229
	v_add_u32_e32 v230, 0x80, v230
	v_add_u32_e32 v231, 0x80, v231
	s_waitcnt vmcnt(4)
	s_barrier
	v_add_u32_e32 v234, s23, v232
	v_add_u32_e32 v236, s29, v232
	v_add_u32_e32 v235, s23, v233
	v_add_u32_e32 v237, s29, v233
	ds_read_b128 v[136:139], v234
	ds_read_b128 v[140:143], v234 offset:2048
	ds_read_b128 v[144:147], v234 offset:4096
	ds_read_b128 v[148:151], v234 offset:6144
	ds_read_b128 v[188:191], v236
	ds_read_b128 v[196:199], v236 offset:2048
	ds_read_b128 v[200:203], v236 offset:4096
	ds_read_b128 v[204:207], v236 offset:6144
	ds_read_b128 v[172:175], v235
	ds_read_b128 v[176:179], v235 offset:2048
	ds_read_b128 v[180:183], v235 offset:4096
	ds_read_b128 v[184:187], v235 offset:6144
	ds_read_b128 v[212:215], v237
	ds_read_b128 v[216:219], v237 offset:2048
	ds_read_b128 v[220:223], v237 offset:4096
	ds_read_b128 v[224:227], v237 offset:6144
	s_waitcnt lgkmcnt(8)
	s_setprio 1
	v_mfma_f32_16x16x32_bf16 v[2:5], v[136:139], v[188:191], v[2:5]
	v_mfma_f32_16x16x32_bf16 v[6:9], v[136:139], v[196:199], v[6:9]
	v_mfma_f32_16x16x32_bf16 v[10:13], v[136:139], v[200:203], v[10:13]
	v_mfma_f32_16x16x32_bf16 v[14:17], v[136:139], v[204:207], v[14:17]
	v_mfma_f32_16x16x32_bf16 v[18:21], v[140:143], v[188:191], v[18:21]
	v_mfma_f32_16x16x32_bf16 v[22:25], v[140:143], v[196:199], v[22:25]
	v_mfma_f32_16x16x32_bf16 v[26:29], v[140:143], v[200:203], v[26:29]
	v_mfma_f32_16x16x32_bf16 v[30:33], v[140:143], v[204:207], v[30:33]
	v_mfma_f32_16x16x32_bf16 v[34:37], v[144:147], v[188:191], v[34:37]
	v_mfma_f32_16x16x32_bf16 v[38:41], v[144:147], v[196:199], v[38:41]
	v_mfma_f32_16x16x32_bf16 v[42:45], v[144:147], v[200:203], v[42:45]
	v_mfma_f32_16x16x32_bf16 v[46:49], v[144:147], v[204:207], v[46:49]
	v_mfma_f32_16x16x32_bf16 v[50:53], v[148:151], v[188:191], v[50:53]
	v_mfma_f32_16x16x32_bf16 v[54:57], v[148:151], v[196:199], v[54:57]
	v_mfma_f32_16x16x32_bf16 v[58:61], v[148:151], v[200:203], v[58:61]
	v_mfma_f32_16x16x32_bf16 v[62:65], v[148:151], v[204:207], v[62:65]
	s_waitcnt lgkmcnt(0)
	v_mfma_f32_16x16x32_bf16 v[2:5], v[172:175], v[212:215], v[2:5]
	v_mfma_f32_16x16x32_bf16 v[6:9], v[172:175], v[216:219], v[6:9]
	v_mfma_f32_16x16x32_bf16 v[10:13], v[172:175], v[220:223], v[10:13]
	v_mfma_f32_16x16x32_bf16 v[14:17], v[172:175], v[224:227], v[14:17]
	v_mfma_f32_16x16x32_bf16 v[18:21], v[176:179], v[212:215], v[18:21]
	v_mfma_f32_16x16x32_bf16 v[22:25], v[176:179], v[216:219], v[22:25]
	v_mfma_f32_16x16x32_bf16 v[26:29], v[176:179], v[220:223], v[26:29]
	v_mfma_f32_16x16x32_bf16 v[30:33], v[176:179], v[224:227], v[30:33]
	v_mfma_f32_16x16x32_bf16 v[34:37], v[180:183], v[212:215], v[34:37]
	v_mfma_f32_16x16x32_bf16 v[38:41], v[180:183], v[216:219], v[38:41]
	v_mfma_f32_16x16x32_bf16 v[42:45], v[180:183], v[220:223], v[42:45]
	v_mfma_f32_16x16x32_bf16 v[46:49], v[180:183], v[224:227], v[46:49]
	v_mfma_f32_16x16x32_bf16 v[50:53], v[184:187], v[212:215], v[50:53]
	v_mfma_f32_16x16x32_bf16 v[54:57], v[184:187], v[216:219], v[54:57]
	v_mfma_f32_16x16x32_bf16 v[58:61], v[184:187], v[220:223], v[58:61]
	v_mfma_f32_16x16x32_bf16 v[62:65], v[184:187], v[224:227], v[62:65]
	s_setprio 0
	s_waitcnt vmcnt(0)
	s_barrier
	v_add_u32_e32 v236, s41, v232
	v_add_u32_e32 v237, s41, v233
	ds_read_b128 v[188:191], v236
	ds_read_b128 v[196:199], v236 offset:2048
	ds_read_b128 v[200:203], v236 offset:4096
	ds_read_b128 v[204:207], v236 offset:6144
	ds_read_b128 v[212:215], v237
	ds_read_b128 v[216:219], v237 offset:2048
	ds_read_b128 v[220:223], v237 offset:4096
	ds_read_b128 v[224:227], v237 offset:6144
	s_waitcnt lgkmcnt(4)
	s_setprio 1
	v_mfma_f32_16x16x32_bf16 v[66:69], v[136:139], v[188:191], v[66:69]
	v_mfma_f32_16x16x32_bf16 v[70:73], v[136:139], v[196:199], v[70:73]
	v_mfma_f32_16x16x32_bf16 v[74:77], v[136:139], v[200:203], v[74:77]
	v_mfma_f32_16x16x32_bf16 v[78:81], v[136:139], v[204:207], v[78:81]
	v_mfma_f32_16x16x32_bf16 v[82:85], v[140:143], v[188:191], v[82:85]
	v_mfma_f32_16x16x32_bf16 v[86:89], v[140:143], v[196:199], v[86:89]
	v_mfma_f32_16x16x32_bf16 v[90:93], v[140:143], v[200:203], v[90:93]
	v_mfma_f32_16x16x32_bf16 v[94:97], v[140:143], v[204:207], v[94:97]
	v_mfma_f32_16x16x32_bf16 v[98:101], v[144:147], v[188:191], v[98:101]
	v_mfma_f32_16x16x32_bf16 v[102:105], v[144:147], v[196:199], v[102:105]
	v_mfma_f32_16x16x32_bf16 v[106:109], v[144:147], v[200:203], v[106:109]
	v_mfma_f32_16x16x32_bf16 v[110:113], v[144:147], v[204:207], v[110:113]
	v_mfma_f32_16x16x32_bf16 v[114:117], v[148:151], v[188:191], v[114:117]
	v_mfma_f32_16x16x32_bf16 v[118:121], v[148:151], v[196:199], v[118:121]
	v_mfma_f32_16x16x32_bf16 v[122:125], v[148:151], v[200:203], v[122:125]
	v_mfma_f32_16x16x32_bf16 v[126:129], v[148:151], v[204:207], v[126:129]
	s_waitcnt lgkmcnt(0)
	v_mfma_f32_16x16x32_bf16 v[66:69], v[172:175], v[212:215], v[66:69]
	v_mfma_f32_16x16x32_bf16 v[70:73], v[172:175], v[216:219], v[70:73]
	v_mfma_f32_16x16x32_bf16 v[74:77], v[172:175], v[220:223], v[74:77]
	v_mfma_f32_16x16x32_bf16 v[78:81], v[172:175], v[224:227], v[78:81]
	v_mfma_f32_16x16x32_bf16 v[82:85], v[176:179], v[212:215], v[82:85]
	v_mfma_f32_16x16x32_bf16 v[86:89], v[176:179], v[216:219], v[86:89]
	v_mfma_f32_16x16x32_bf16 v[90:93], v[176:179], v[220:223], v[90:93]
	v_mfma_f32_16x16x32_bf16 v[94:97], v[176:179], v[224:227], v[94:97]
	v_mfma_f32_16x16x32_bf16 v[98:101], v[180:183], v[212:215], v[98:101]
	v_mfma_f32_16x16x32_bf16 v[102:105], v[180:183], v[216:219], v[102:105]
	v_mfma_f32_16x16x32_bf16 v[106:109], v[180:183], v[220:223], v[106:109]
	v_mfma_f32_16x16x32_bf16 v[110:113], v[180:183], v[224:227], v[110:113]
	v_mfma_f32_16x16x32_bf16 v[114:117], v[184:187], v[212:215], v[114:117]
	v_mfma_f32_16x16x32_bf16 v[118:121], v[184:187], v[216:219], v[118:121]
	v_mfma_f32_16x16x32_bf16 v[122:125], v[184:187], v[220:223], v[122:125]
	v_mfma_f32_16x16x32_bf16 v[126:129], v[184:187], v[224:227], v[126:129]
	s_setprio 0
	s_nop 7
	s_barrier
	v_and_b32_e32 v241, 63, v131
	v_and_b32_e32 v242, 15, v241
	v_lshrrev_b32_e32 v243, 4, v241
	s_lshr_b32 s56, s50, 1
	s_and_b32 s57, s50, 1
	s_mul_i32 s0, s56, 64*272
	s_lshl_b32 s52, s57, 7
	s_add_i32 s0, s0, s52
	s_add_i32 s0, s0, 16
	v_mul_u32_u24_e32 v244, 1088, v243
	v_lshl_add_u32 v244, v242, 1, v244
	v_add_u32_e32 v229, s0, v244
	s_mul_i32 s0, s57, 64*272
	s_lshl_b32 s52, s56, 7
	s_add_i32 s0, s0, s52
	s_add_i32 s0, s0, 16
	v_mul_u32_u24_e32 v244, 272, v242
	v_lshl_add_u32 v244, v243, 3, v244
	v_add_u32_e32 v230, s0, v244
	s_lshl_b32 s0, s57, 9
	s_lshl_b32 s52, s56, 8
	s_add_i32 s0, s0, s52
	s_add_i32 s0, s0, 16+34816
	v_lshl_add_u32 v228, v243, 4, s0
	s_lshl_b32 s0, s57, 8
	v_lshl_add_u32 v234, v242, 2, s0
	v_lshrrev_b32_e32 v241, 4, v131
	v_and_b32_e32 v242, 15, v131
	v_lshlrev_b32_e32 v242, 4, v242
	v_mul_u32_u24_e32 v243, 272, v241
	v_add3_u32 v231, v243, v242, 16
	s_movk_i32 s0, 0x2500
	v_mad_u32_u24 v232, v241, s0, v242
	v_lshl_add_u32 v233, v241, 12, v242
	s_lshr_b32 s52, s54, 7
	s_mov_b32 s57, 0
	s_movk_i32 s56, 0x170
	s_cmp_lt_u32 s52, 8
	s_cbranch_scc0 .Lin2_t1_v1
	s_mov_b32 s57, 1
	s_movk_i32 s56, 0x28
	s_branch .Lin2_t1_vd
